# GEMM K-loops: loop back-edge block and load-segment SALU preambles (counter/pointer adds, M0 writes, DMA address adds) hoisted above the preceding MFMA-segment barrier
# baseline (speedup 1.0000x reference)
;     DI bool next(int i, Unit& u) const { const long L = (long)i * G + c; if (L >= T.nwg) return false; T.map((int)L, u.pm, u.pn); u.seg = 0; return true; }
;     DI bool next(int i, Unit& u) const { const int ti = i / 3; const long L = (long)ti * G + c; if (L >= T.nwg) return false; T.map((int)L, u.pm, u.pn); u.seg = i - 3 * ti; return true; }
;     DI const char* aptr(const Unit& u) const { return A + (size_t)u.pm * ta + (size_t)kofs(u.seg) * 2; }
;     DI const char* bptr(const Unit& u) const { return B + (size_t)u.pn * tb + (size_t)kofs(u.seg) * 2; }
; #define PG8_STAGE(bufoff, gbase, voff) do { _Pragma("unroll") for (int _i = 0; _i < 2; ++_i) \
;         __builtin_amdgcn_global_load_lds((const unsigned*)((const char*)(gbase) + (voff)[_i]), (LAS unsigned*)(lds + (bufoff) + ldsw + _i * 8192), 16, 0, 0); } while (0)
; #define PG8_LDA(dst, b, h) do { _Pragma("unroll") for (int m = 0; m < 4; ++m) _Pragma("unroll") for (int k = 0; k < 2; ++k) dst[m][k] = *(const LAS bf16x8*)(lds + PG8_SA(b, h) + aoff + m * 2048 + k * 1024); } while (0)
; #define PG8_WAIT_V(n) asm volatile("s_waitcnt vmcnt(" #n ")" ::: "memory")
; #define PG8_WAIT_L(n) asm volatile("s_waitcnt lgkmcnt(" #n ")" ::: "memory")
; template <class Epi, class Sched>
; DI void gemm_phase(LAS unsigned char* lds, const int wv, const int lda, const int ldb, const Sched& S, const Epi& E) {
;     ...
;         const bool has_next = S.next(ui + 1, nxt);
;         const char* nA = has_next ? S.aptr(nxt) : cA; const char* nB = has_next ? S.bptr(nxt) : cB;
;         for (int t = 0; t < nt; t += 2) {
;             const bool last = (t == nt - 2);
;             const char* a1 = cA + (size_t)(t + 1) * kstep;
;             const char* a2 = last ? nA : cA + (size_t)(t + 2) * kstep; const char* b2 = last ? nB : cB + (size_t)(t + 2) * kstep;
;             const char* a3 = a2 + kstep; const char* b3 = b2 + kstep;
;             PG8_LDB(B0, 0, 0); PG8_LDB(B1, 0, 1); PG8_SCHED; PG8_LDA(At, 0, 0); PG8_STAGE(PG8_SA(1, 1), a1 + hstepA, voffA);
;             PG8_WAIT_V(8); PG8_WAIT_L(0); PG8_BAR; PG8_MMA(0, 0, At, B0); PG8_MMA(0, 1, At, B1); PG8_BAR; PG8_SCHED;
;             PG8_LDA(At, 0, 1); PG8_STAGE(PG8_SB(0, 0), b2, voffB); PG8_STAGE(PG8_SB(0, 1), b2 + hstepB, voffB); PG8_STAGE(PG8_SA(0, 0), a2, voffA);
;             PG8_WAIT_V(8); PG8_WAIT_L(0); PG8_BAR; PG8_MMA(1, 0, At, B0); PG8_MMA(1, 1, At, B1); PG8_BAR; PG8_SCHED;
.LBB0_377:
	s_ashr_i32 s23, s22, 31
	s_lshl_b64 s[0:1], s[22:23], 20
	s_add_u32 s24, s8, s0
	s_addc_u32 s25, s9, s1
	s_and_b64 s[0:1], s[40:41], exec
	s_cselect_b32 s0, s25, s35
	s_cselect_b32 s1, s24, s34
	s_ashr_i32 s19, s18, 31
	s_lshl_b64 s[16:17], s[18:19], 20
	s_add_u32 s26, s45, s16
	s_addc_u32 s27, s46, s17
	s_and_b64 s[16:17], s[40:41], exec
	s_cselect_b32 s5, s27, s37
	s_cselect_b32 s16, s26, s36
	s_add_u32 s34, s34, 0x80080
	s_addc_u32 s35, s35, 0
	s_add_u32 s17, s36, 0x100
	s_addc_u32 s19, s37, 0
	s_mov_b32 s23, -2
	s_waitcnt vmcnt(0)
	s_add_u32 s33, s34, 0xfff80080
	s_addc_u32 s36, s35, -1
	s_add_i32 s61, 0, 0x10000
	s_cmp_eq_u32 s23, 28
	s_cselect_b32 s39, s0, s36
	s_cselect_b32 s38, s1, s33
	s_cselect_b32 s37, s5, s19
	s_cselect_b32 s36, s16, s17
	s_add_i32 s33, 0, 0x14000
	v_add_u32_e32 v154, s61, v170
	v_add_u32_e32 v173, s33, v170
	ds_read_b128 v[104:107], v154
	ds_read_b128 v[108:111], v154 offset:1024
	ds_read_b128 v[150:153], v154 offset:2048
	ds_read_b128 v[154:157], v154 offset:3072
	ds_read_b128 v[158:161], v173
	ds_read_b128 v[162:165], v173 offset:1024
	ds_read_b128 v[166:169], v173 offset:2048
	ds_read_b128 v[174:177], v173 offset:3072
	v_lshl_add_u64 v[182:183], s[34:35], 0, v[146:147]
	s_add_i32 m0, s31, 0xc000
	ds_read_b128 v[178:181], v172
	ds_read_b128 v[200:203], v172 offset:1024
	ds_read_b128 v[204:207], v172 offset:2048
	ds_read_b128 v[208:211], v172 offset:3072
	ds_read_b128 v[212:215], v172 offset:4096
	ds_read_b128 v[216:219], v172 offset:5120
	ds_read_b128 v[220:223], v172 offset:6144
	ds_read_b128 v[234:237], v172 offset:7168
	global_load_lds_dwordx4 v[182:183], off
	s_add_i32 m0, s31, 0xe000
	v_lshl_add_u64 v[182:183], s[34:35], 0, v[148:149]
	global_load_lds_dwordx4 v[182:183], off
	s_waitcnt vmcnt(8) lgkmcnt(0)
	s_barrier
	v_mfma_f32_16x16x32_bf16 v[132:135], v[104:107], v[178:181], 0
	v_mfma_f32_16x16x32_bf16 v[128:131], v[150:153], v[178:181], 0
	v_mfma_f32_16x16x32_bf16 v[124:127], v[104:107], v[204:207], 0
	v_mfma_f32_16x16x32_bf16 v[120:123], v[150:153], v[204:207], 0
	v_mfma_f32_16x16x32_bf16 v[116:119], v[104:107], v[212:215], 0
	v_mfma_f32_16x16x32_bf16 v[112:115], v[150:153], v[212:215], 0
	v_mfma_f32_16x16x32_bf16 v[100:103], v[104:107], v[220:223], 0
	v_mfma_f32_16x16x32_bf16 v[96:99], v[150:153], v[220:223], 0
	v_mfma_f32_16x16x32_bf16 v[132:135], v[108:111], v[200:203], v[132:135]
	v_mfma_f32_16x16x32_bf16 v[128:131], v[154:157], v[200:203], v[128:131]
	v_mfma_f32_16x16x32_bf16 v[124:127], v[108:111], v[208:211], v[124:127]
	v_mfma_f32_16x16x32_bf16 v[120:123], v[154:157], v[208:211], v[120:123]
	v_mfma_f32_16x16x32_bf16 v[116:119], v[108:111], v[216:219], v[116:119]
	v_mfma_f32_16x16x32_bf16 v[112:115], v[154:157], v[216:219], v[112:115]
	v_mfma_f32_16x16x32_bf16 v[100:103], v[108:111], v[234:237], v[100:103]
	v_mfma_f32_16x16x32_bf16 v[96:99], v[154:157], v[234:237], v[96:99]
	v_mfma_f32_16x16x32_bf16 v[60:63], v[158:161], v[178:181], 0
	v_mfma_f32_16x16x32_bf16 v[56:59], v[166:169], v[178:181], 0
	v_mfma_f32_16x16x32_bf16 v[52:55], v[158:161], v[204:207], 0
	v_mfma_f32_16x16x32_bf16 v[48:51], v[166:169], v[204:207], 0
	v_mfma_f32_16x16x32_bf16 v[44:47], v[158:161], v[212:215], 0
	v_mfma_f32_16x16x32_bf16 v[40:43], v[166:169], v[212:215], 0
	v_mfma_f32_16x16x32_bf16 v[36:39], v[158:161], v[220:223], 0
	v_mfma_f32_16x16x32_bf16 v[32:35], v[166:169], v[220:223], 0
	v_mfma_f32_16x16x32_bf16 v[60:63], v[162:165], v[200:203], v[60:63]
	v_mfma_f32_16x16x32_bf16 v[56:59], v[174:177], v[200:203], v[56:59]
	v_mfma_f32_16x16x32_bf16 v[52:55], v[162:165], v[208:211], v[52:55]
	v_mfma_f32_16x16x32_bf16 v[48:51], v[174:177], v[208:211], v[48:51]
	v_mfma_f32_16x16x32_bf16 v[44:47], v[162:165], v[216:219], v[44:47]
	v_mfma_f32_16x16x32_bf16 v[40:43], v[174:177], v[216:219], v[40:43]
	v_mfma_f32_16x16x32_bf16 v[36:39], v[162:165], v[234:237], v[36:39]
	v_mfma_f32_16x16x32_bf16 v[32:35], v[174:177], v[234:237], v[32:35]
	s_add_i32 s61, s61, s47
	v_lshl_add_u64 v[182:183], s[36:37], 0, v[138:139]
	s_mov_b32 m0, s61
	s_barrier
	ds_read_b128 v[178:181], v172 offset:16384
	ds_read_b128 v[200:203], v172 offset:17408
	ds_read_b128 v[204:207], v172 offset:18432
	ds_read_b128 v[208:211], v172 offset:19456
	ds_read_b128 v[212:215], v172 offset:20480
	ds_read_b128 v[216:219], v172 offset:21504
	ds_read_b128 v[220:223], v172 offset:22528
	ds_read_b128 v[234:237], v172 offset:23552
	global_load_lds_dwordx4 v[182:183], off
	s_add_i32 m0, s61, 0x2000
	s_add_u32 s62, s36, 0x80000
	v_lshl_add_u64 v[188:189], s[36:37], 0, v[142:143]
	s_addc_u32 s63, s37, 0
	s_add_i32 s33, s33, s47
	global_load_lds_dwordx4 v[188:189], off
	v_lshl_add_u64 v[190:191], s[62:63], 0, v[138:139]
	s_mov_b32 m0, s33
	v_lshl_add_u64 v[196:197], s[38:39], 0, v[140:141]
	global_load_lds_dwordx4 v[190:191], off
	s_add_i32 m0, s33, 0x2000
	v_lshl_add_u64 v[190:191], s[62:63], 0, v[142:143]
	global_load_lds_dwordx4 v[190:191], off
	s_mov_b32 m0, s31
	v_lshl_add_u64 v[190:191], s[38:39], 0, v[136:137]
	global_load_lds_dwordx4 v[190:191], off
	s_mov_b32 m0, s48
	s_nop 0
	global_load_lds_dwordx4 v[196:197], off
	s_waitcnt vmcnt(8) lgkmcnt(0)
	s_barrier
; #define PG8_STAGE(bufoff, gbase, voff) do { _Pragma("unroll") for (int _i = 0; _i < 2; ++_i) \
;         __builtin_amdgcn_global_load_lds((const unsigned*)((const char*)(gbase) + (voff)[_i]), (LAS unsigned*)(lds + (bufoff) + ldsw + _i * 8192), 16, 0, 0); } while (0)
; #define PG8_LDA(dst, b, h) do { _Pragma("unroll") for (int m = 0; m < 4; ++m) _Pragma("unroll") for (int k = 0; k < 2; ++k) dst[m][k] = *(const LAS bf16x8*)(lds + PG8_SA(b, h) + aoff + m * 2048 + k * 1024); } while (0)
; #define PG8_LDB(dst, b, h) do { _Pragma("unroll") for (int n = 0; n < 2; ++n) _Pragma("unroll") for (int k = 0; k < 2; ++k) dst[n][k] = *(const LAS bf16x8*)(lds + PG8_SB(b, h) + boff + n * 2048 + k * 1024); } while (0)
; #define PG8_MMA(ai, bj, At, Bt) do { __builtin_amdgcn_s_setprio(1); _Pragma("unroll") for (int m = 0; m < 4; ++m) _Pragma("unroll") for (int n = 0; n < 2; ++n) _Pragma("unroll") for (int k = 0; k < 2; ++k) \
;         acc[ai][bj][m][n] = __builtin_amdgcn_mfma_f32_16x16x32_bf16(Bt[n][k], At[m][k], acc[ai][bj][m][n], 0, 0, 0); __builtin_amdgcn_s_setprio(0); } while (0)
; #define PG8_WAIT_V(n) asm volatile("s_waitcnt vmcnt(" #n ")" ::: "memory")
; #define PG8_WAIT_L(n) asm volatile("s_waitcnt lgkmcnt(" #n ")" ::: "memory")
; #define PG8_BAR __builtin_amdgcn_s_barrier()
; #define PG8_SCHED __builtin_amdgcn_sched_barrier(0)
; template <class Epi, class Sched>
; DI void gemm_phase(LAS unsigned char* lds, const int wv, const int lda, const int ldb, const Sched& S, const Epi& E) {
;     ...
;             PG8_LDA(At, 0, 1); PG8_STAGE(PG8_SB(0, 0), b2, voffB); PG8_STAGE(PG8_SB(0, 1), b2 + hstepB, voffB); PG8_STAGE(PG8_SA(0, 0), a2, voffA);
;             PG8_WAIT_V(8); PG8_WAIT_L(0); PG8_BAR; PG8_MMA(1, 0, At, B0); PG8_MMA(1, 1, At, B1); PG8_BAR; PG8_SCHED;
;             PG8_LDB(B0, 1, 0); PG8_LDB(B1, 1, 1); PG8_SCHED; PG8_LDA(At, 1, 0); PG8_STAGE(PG8_SA(0, 1), a2 + hstepA, voffA);
;             PG8_WAIT_V(8); PG8_WAIT_L(0); PG8_BAR; PG8_MMA(0, 0, At, B0); PG8_MMA(0, 1, At, B1); PG8_BAR; PG8_SCHED;
	v_mfma_f32_16x16x32_bf16 v[92:95], v[104:107], v[178:181], 0
	v_mfma_f32_16x16x32_bf16 v[88:91], v[150:153], v[178:181], 0
	v_mfma_f32_16x16x32_bf16 v[84:87], v[104:107], v[204:207], 0
	v_mfma_f32_16x16x32_bf16 v[80:83], v[150:153], v[204:207], 0
	v_mfma_f32_16x16x32_bf16 v[76:79], v[104:107], v[212:215], 0
	v_mfma_f32_16x16x32_bf16 v[72:75], v[150:153], v[212:215], 0
	v_mfma_f32_16x16x32_bf16 v[68:71], v[104:107], v[220:223], 0
	v_mfma_f32_16x16x32_bf16 v[64:67], v[150:153], v[220:223], 0
	v_mfma_f32_16x16x32_bf16 v[92:95], v[108:111], v[200:203], v[92:95]
	v_mfma_f32_16x16x32_bf16 v[88:91], v[154:157], v[200:203], v[88:91]
	v_mfma_f32_16x16x32_bf16 v[84:87], v[108:111], v[208:211], v[84:87]
	v_mfma_f32_16x16x32_bf16 v[80:83], v[154:157], v[208:211], v[80:83]
	v_mfma_f32_16x16x32_bf16 v[76:79], v[108:111], v[216:219], v[76:79]
	v_mfma_f32_16x16x32_bf16 v[72:75], v[154:157], v[216:219], v[72:75]
	v_mfma_f32_16x16x32_bf16 v[68:71], v[108:111], v[234:237], v[68:71]
	v_mfma_f32_16x16x32_bf16 v[64:67], v[154:157], v[234:237], v[64:67]
	v_mfma_f32_16x16x32_bf16 v[28:31], v[158:161], v[178:181], 0
	v_mfma_f32_16x16x32_bf16 v[24:27], v[166:169], v[178:181], 0
	v_mfma_f32_16x16x32_bf16 v[20:23], v[158:161], v[204:207], 0
	v_mfma_f32_16x16x32_bf16 v[16:19], v[166:169], v[204:207], 0
	v_mfma_f32_16x16x32_bf16 v[12:15], v[158:161], v[212:215], 0
	v_mfma_f32_16x16x32_bf16 v[8:11], v[166:169], v[212:215], 0
	v_mfma_f32_16x16x32_bf16 v[4:7], v[158:161], v[220:223], 0
	v_mfma_f32_16x16x32_bf16 v[0:3], v[166:169], v[220:223], 0
	v_mfma_f32_16x16x32_bf16 v[28:31], v[162:165], v[200:203], v[28:31]
	v_mfma_f32_16x16x32_bf16 v[24:27], v[174:177], v[200:203], v[24:27]
	v_mfma_f32_16x16x32_bf16 v[20:23], v[162:165], v[208:211], v[20:23]
	v_mfma_f32_16x16x32_bf16 v[16:19], v[174:177], v[208:211], v[16:19]
	v_mfma_f32_16x16x32_bf16 v[12:15], v[162:165], v[216:219], v[12:15]
	v_mfma_f32_16x16x32_bf16 v[8:11], v[174:177], v[216:219], v[8:11]
	v_mfma_f32_16x16x32_bf16 v[4:7], v[162:165], v[234:237], v[4:7]
	v_mfma_f32_16x16x32_bf16 v[0:3], v[174:177], v[234:237], v[0:3]
	s_add_i32 s33, 0, 0x18000
	s_add_i32 s61, 0, 0x1c000
	s_barrier
	v_add_u32_e32 v154, s33, v170
	v_add_u32_e32 v173, s61, v170
	ds_read_b128 v[104:107], v154
	ds_read_b128 v[108:111], v154 offset:1024
	ds_read_b128 v[150:153], v154 offset:2048
	ds_read_b128 v[154:157], v154 offset:3072
	ds_read_b128 v[158:161], v173
	ds_read_b128 v[162:165], v173 offset:1024
	ds_read_b128 v[166:169], v173 offset:2048
	ds_read_b128 v[174:177], v173 offset:3072
	s_add_u32 s38, s38, 0x80000
	s_addc_u32 s39, s39, 0
	s_mov_b32 m0, s49
	v_lshl_add_u64 v[198:199], s[38:39], 0, v[136:137]
	ds_read_b128 v[178:181], v172 offset:32768
	ds_read_b128 v[200:203], v172 offset:33792
	ds_read_b128 v[204:207], v172 offset:34816
	ds_read_b128 v[208:211], v172 offset:35840
	ds_read_b128 v[212:215], v172 offset:36864
	ds_read_b128 v[216:219], v172 offset:37888
	ds_read_b128 v[220:223], v172 offset:38912
	ds_read_b128 v[234:237], v172 offset:39936
	global_load_lds_dwordx4 v[198:199], off
	s_mov_b32 m0, s50
	v_lshl_add_u64 v[198:199], s[38:39], 0, v[140:141]
	global_load_lds_dwordx4 v[198:199], off
	s_waitcnt vmcnt(8) lgkmcnt(0)
	s_barrier
	v_mfma_f32_16x16x32_bf16 v[132:135], v[104:107], v[178:181], v[132:135]
	v_mfma_f32_16x16x32_bf16 v[128:131], v[150:153], v[178:181], v[128:131]
	v_mfma_f32_16x16x32_bf16 v[124:127], v[104:107], v[204:207], v[124:127]
	v_mfma_f32_16x16x32_bf16 v[120:123], v[150:153], v[204:207], v[120:123]
	v_mfma_f32_16x16x32_bf16 v[116:119], v[104:107], v[212:215], v[116:119]
	v_mfma_f32_16x16x32_bf16 v[112:115], v[150:153], v[212:215], v[112:115]
	v_mfma_f32_16x16x32_bf16 v[100:103], v[104:107], v[220:223], v[100:103]
	v_mfma_f32_16x16x32_bf16 v[96:99], v[150:153], v[220:223], v[96:99]
	v_mfma_f32_16x16x32_bf16 v[132:135], v[108:111], v[200:203], v[132:135]
	v_mfma_f32_16x16x32_bf16 v[128:131], v[154:157], v[200:203], v[128:131]
	v_mfma_f32_16x16x32_bf16 v[124:127], v[108:111], v[208:211], v[124:127]
	v_mfma_f32_16x16x32_bf16 v[120:123], v[154:157], v[208:211], v[120:123]
	v_mfma_f32_16x16x32_bf16 v[116:119], v[108:111], v[216:219], v[116:119]
	v_mfma_f32_16x16x32_bf16 v[112:115], v[154:157], v[216:219], v[112:115]
	v_mfma_f32_16x16x32_bf16 v[100:103], v[108:111], v[234:237], v[100:103]
	v_mfma_f32_16x16x32_bf16 v[96:99], v[154:157], v[234:237], v[96:99]
	v_mfma_f32_16x16x32_bf16 v[60:63], v[158:161], v[178:181], v[60:63]
	v_mfma_f32_16x16x32_bf16 v[56:59], v[166:169], v[178:181], v[56:59]
	v_mfma_f32_16x16x32_bf16 v[52:55], v[158:161], v[204:207], v[52:55]
	v_mfma_f32_16x16x32_bf16 v[48:51], v[166:169], v[204:207], v[48:51]
	v_mfma_f32_16x16x32_bf16 v[44:47], v[158:161], v[212:215], v[44:47]
	v_mfma_f32_16x16x32_bf16 v[40:43], v[166:169], v[212:215], v[40:43]
	v_mfma_f32_16x16x32_bf16 v[36:39], v[158:161], v[220:223], v[36:39]
	v_mfma_f32_16x16x32_bf16 v[32:35], v[166:169], v[220:223], v[32:35]
	v_mfma_f32_16x16x32_bf16 v[60:63], v[162:165], v[200:203], v[60:63]
	v_mfma_f32_16x16x32_bf16 v[56:59], v[174:177], v[200:203], v[56:59]
	v_mfma_f32_16x16x32_bf16 v[52:55], v[162:165], v[208:211], v[52:55]
	v_mfma_f32_16x16x32_bf16 v[48:51], v[174:177], v[208:211], v[48:51]
	v_mfma_f32_16x16x32_bf16 v[44:47], v[162:165], v[216:219], v[44:47]
	v_mfma_f32_16x16x32_bf16 v[40:43], v[174:177], v[216:219], v[40:43]
	v_mfma_f32_16x16x32_bf16 v[36:39], v[162:165], v[234:237], v[36:39]
	v_mfma_f32_16x16x32_bf16 v[32:35], v[174:177], v[234:237], v[32:35]
	s_add_i32 s33, s33, s47
	v_lshl_add_u64 v[182:183], v[182:183], 0, s[28:29]
	s_mov_b32 m0, s33
	s_barrier
; #define PG8_STAGE(bufoff, gbase, voff) do { _Pragma("unroll") for (int _i = 0; _i < 2; ++_i) \
;         __builtin_amdgcn_global_load_lds((const unsigned*)((const char*)(gbase) + (voff)[_i]), (LAS unsigned*)(lds + (bufoff) + ldsw + _i * 8192), 16, 0, 0); } while (0)
; #define PG8_LDA(dst, b, h) do { _Pragma("unroll") for (int m = 0; m < 4; ++m) _Pragma("unroll") for (int k = 0; k < 2; ++k) dst[m][k] = *(const LAS bf16x8*)(lds + PG8_SA(b, h) + aoff + m * 2048 + k * 1024); } while (0)
; #define PG8_LDB(dst, b, h) do { _Pragma("unroll") for (int n = 0; n < 2; ++n) _Pragma("unroll") for (int k = 0; k < 2; ++k) dst[n][k] = *(const LAS bf16x8*)(lds + PG8_SB(b, h) + boff + n * 2048 + k * 1024); } while (0)
; #define PG8_WAIT_V(n) asm volatile("s_waitcnt vmcnt(" #n ")" ::: "memory")
; #define PG8_BAR __builtin_amdgcn_s_barrier()
; template <class Epi, class Sched>
; DI void gemm_phase(LAS unsigned char* lds, const int wv, const int lda, const int ldb, const Sched& S, const Epi& E) {
;     ...
;         for (int t = 0; t < nt; t += 2) {
;             const bool last = (t == nt - 2);
;             const char* a1 = cA + (size_t)(t + 1) * kstep;
;             const char* a2 = last ? nA : cA + (size_t)(t + 2) * kstep; const char* b2 = last ? nB : cB + (size_t)(t + 2) * kstep;
;             const char* a3 = a2 + kstep; const char* b3 = b2 + kstep;
;             PG8_LDB(B0, 0, 0); PG8_LDB(B1, 0, 1); PG8_SCHED; PG8_LDA(At, 0, 0); PG8_STAGE(PG8_SA(1, 1), a1 + hstepA, voffA);
;             PG8_WAIT_V(8); PG8_WAIT_L(0); PG8_BAR; PG8_MMA(0, 0, At, B0); PG8_MMA(0, 1, At, B1); PG8_BAR; PG8_SCHED;
;             PG8_LDA(At, 0, 1); PG8_STAGE(PG8_SB(0, 0), b2, voffB); PG8_STAGE(PG8_SB(0, 1), b2 + hstepB, voffB); PG8_STAGE(PG8_SA(0, 0), a2, voffA);
;             PG8_WAIT_V(8); PG8_WAIT_L(0); PG8_BAR; PG8_MMA(1, 0, At, B0); PG8_MMA(1, 1, At, B1); PG8_BAR; PG8_SCHED;
;             PG8_LDB(B0, 1, 0); PG8_LDB(B1, 1, 1); PG8_SCHED; PG8_LDA(At, 1, 0); PG8_STAGE(PG8_SA(0, 1), a2 + hstepA, voffA);
;             PG8_WAIT_V(8); PG8_WAIT_L(0); PG8_BAR; PG8_MMA(0, 0, At, B0); PG8_MMA(0, 1, At, B1); PG8_BAR; PG8_SCHED;
;             PG8_LDA(At, 1, 1); PG8_STAGE(PG8_SB(1, 0), b3, voffB); PG8_STAGE(PG8_SB(1, 1), b3 + hstepB, voffB); PG8_STAGE(PG8_SA(1, 0), a3, voffA);
;             PG8_WAIT_V(8); PG8_WAIT_L(0); PG8_BAR; PG8_MMA(1, 0, At, B0); PG8_MMA(1, 1, At, B1); PG8_BAR; PG8_SCHED;
	ds_read_b128 v[178:181], v172 offset:49152
	ds_read_b128 v[200:203], v172 offset:50176
	ds_read_b128 v[204:207], v172 offset:51200
	ds_read_b128 v[208:211], v172 offset:52224
	ds_read_b128 v[212:215], v172 offset:53248
	ds_read_b128 v[216:219], v172 offset:54272
	ds_read_b128 v[220:223], v172 offset:55296
	ds_read_b128 v[234:237], v172 offset:56320
	global_load_lds_dwordx4 v[182:183], off
	s_add_i32 m0, s33, 0x2000
	s_add_u32 s36, s36, 0x80080
	v_lshl_add_u64 v[182:183], v[188:189], 0, s[28:29]
	s_addc_u32 s37, s37, 0
	s_add_i32 s33, s61, s47
	global_load_lds_dwordx4 v[182:183], off
	s_mov_b32 m0, s33
	v_lshl_add_u64 v[182:183], s[36:37], 0, v[138:139]
	global_load_lds_dwordx4 v[182:183], off
	s_add_i32 m0, s33, 0x2000
	v_lshl_add_u64 v[182:183], s[36:37], 0, v[142:143]
	global_load_lds_dwordx4 v[182:183], off
	s_mov_b32 m0, s52
	v_lshl_add_u64 v[182:183], v[190:191], 0, s[28:29]
	global_load_lds_dwordx4 v[182:183], off
	s_mov_b32 m0, s53
	v_lshl_add_u64 v[182:183], v[196:197], 0, s[28:29]
	global_load_lds_dwordx4 v[182:183], off
	s_waitcnt vmcnt(8) lgkmcnt(0)
	s_barrier
	v_mfma_f32_16x16x32_bf16 v[92:95], v[104:107], v[178:181], v[92:95]
	v_mfma_f32_16x16x32_bf16 v[88:91], v[150:153], v[178:181], v[88:91]
	v_mfma_f32_16x16x32_bf16 v[84:87], v[104:107], v[204:207], v[84:87]
	v_mfma_f32_16x16x32_bf16 v[80:83], v[150:153], v[204:207], v[80:83]
	v_mfma_f32_16x16x32_bf16 v[76:79], v[104:107], v[212:215], v[76:79]
	v_mfma_f32_16x16x32_bf16 v[72:75], v[150:153], v[212:215], v[72:75]
	v_mfma_f32_16x16x32_bf16 v[68:71], v[104:107], v[220:223], v[68:71]
	v_mfma_f32_16x16x32_bf16 v[64:67], v[150:153], v[220:223], v[64:67]
	v_mfma_f32_16x16x32_bf16 v[92:95], v[108:111], v[200:203], v[92:95]
	v_mfma_f32_16x16x32_bf16 v[88:91], v[154:157], v[200:203], v[88:91]
	v_mfma_f32_16x16x32_bf16 v[84:87], v[108:111], v[208:211], v[84:87]
	v_mfma_f32_16x16x32_bf16 v[80:83], v[154:157], v[208:211], v[80:83]
	v_mfma_f32_16x16x32_bf16 v[76:79], v[108:111], v[216:219], v[76:79]
	v_mfma_f32_16x16x32_bf16 v[72:75], v[154:157], v[216:219], v[72:75]
	v_mfma_f32_16x16x32_bf16 v[68:71], v[108:111], v[234:237], v[68:71]
	v_mfma_f32_16x16x32_bf16 v[64:67], v[154:157], v[234:237], v[64:67]
	v_mfma_f32_16x16x32_bf16 v[28:31], v[158:161], v[178:181], v[28:31]
	v_mfma_f32_16x16x32_bf16 v[24:27], v[166:169], v[178:181], v[24:27]
	v_mfma_f32_16x16x32_bf16 v[20:23], v[158:161], v[204:207], v[20:23]
	v_mfma_f32_16x16x32_bf16 v[16:19], v[166:169], v[204:207], v[16:19]
	v_mfma_f32_16x16x32_bf16 v[12:15], v[158:161], v[212:215], v[12:15]
	v_mfma_f32_16x16x32_bf16 v[8:11], v[166:169], v[212:215], v[8:11]
	v_mfma_f32_16x16x32_bf16 v[4:7], v[158:161], v[220:223], v[4:7]
	v_mfma_f32_16x16x32_bf16 v[0:3], v[166:169], v[220:223], v[0:3]
	v_mfma_f32_16x16x32_bf16 v[28:31], v[162:165], v[200:203], v[28:31]
	v_mfma_f32_16x16x32_bf16 v[24:27], v[174:177], v[200:203], v[24:27]
	v_mfma_f32_16x16x32_bf16 v[20:23], v[162:165], v[208:211], v[20:23]
	v_mfma_f32_16x16x32_bf16 v[16:19], v[174:177], v[208:211], v[16:19]
	v_mfma_f32_16x16x32_bf16 v[12:15], v[162:165], v[216:219], v[12:15]
	v_mfma_f32_16x16x32_bf16 v[8:11], v[174:177], v[216:219], v[8:11]
	v_mfma_f32_16x16x32_bf16 v[4:7], v[162:165], v[234:237], v[4:7]
	v_mfma_f32_16x16x32_bf16 v[0:3], v[174:177], v[234:237], v[0:3]
	s_add_i32 s23, s23, 2
	s_add_u32 s34, s34, 0x100
	s_addc_u32 s35, s35, 0
	s_add_u32 s17, s17, 0x100
	s_addc_u32 s19, s19, 0
	s_barrier
.LBB0_378:
	s_add_u32 s33, s34, 0xfff80080
	s_addc_u32 s36, s35, -1
	s_add_i32 s61, 0, 0x10000
	s_cmp_eq_u32 s23, 28
	s_cselect_b32 s39, s0, s36
	s_cselect_b32 s38, s1, s33
	s_cselect_b32 s37, s5, s19
	s_cselect_b32 s36, s16, s17
	s_add_i32 s33, 0, 0x14000
	v_add_u32_e32 v154, s61, v170
	v_add_u32_e32 v173, s33, v170
	ds_read_b128 v[104:107], v154
	ds_read_b128 v[108:111], v154 offset:1024
	ds_read_b128 v[150:153], v154 offset:2048
	ds_read_b128 v[154:157], v154 offset:3072
	ds_read_b128 v[158:161], v173
	ds_read_b128 v[162:165], v173 offset:1024
	ds_read_b128 v[166:169], v173 offset:2048
	ds_read_b128 v[174:177], v173 offset:3072
	v_lshl_add_u64 v[182:183], s[34:35], 0, v[146:147]
	s_add_i32 m0, s31, 0xc000
	ds_read_b128 v[178:181], v172
	ds_read_b128 v[200:203], v172 offset:1024
	ds_read_b128 v[204:207], v172 offset:2048
	ds_read_b128 v[208:211], v172 offset:3072
	ds_read_b128 v[212:215], v172 offset:4096
	ds_read_b128 v[216:219], v172 offset:5120
	ds_read_b128 v[220:223], v172 offset:6144
	ds_read_b128 v[234:237], v172 offset:7168
	global_load_lds_dwordx4 v[182:183], off
	s_add_i32 m0, s31, 0xe000
	v_lshl_add_u64 v[182:183], s[34:35], 0, v[148:149]
	global_load_lds_dwordx4 v[182:183], off
	s_waitcnt vmcnt(8) lgkmcnt(0)
	s_barrier
; #define PG8_STAGE(bufoff, gbase, voff) do { _Pragma("unroll") for (int _i = 0; _i < 2; ++_i) \
;         __builtin_amdgcn_global_load_lds((const unsigned*)((const char*)(gbase) + (voff)[_i]), (LAS unsigned*)(lds + (bufoff) + ldsw + _i * 8192), 16, 0, 0); } while (0)
; #define PG8_LDA(dst, b, h) do { _Pragma("unroll") for (int m = 0; m < 4; ++m) _Pragma("unroll") for (int k = 0; k < 2; ++k) dst[m][k] = *(const LAS bf16x8*)(lds + PG8_SA(b, h) + aoff + m * 2048 + k * 1024); } while (0)
; #define PG8_MMA(ai, bj, At, Bt) do { __builtin_amdgcn_s_setprio(1); _Pragma("unroll") for (int m = 0; m < 4; ++m) _Pragma("unroll") for (int n = 0; n < 2; ++n) _Pragma("unroll") for (int k = 0; k < 2; ++k) \
;         acc[ai][bj][m][n] = __builtin_amdgcn_mfma_f32_16x16x32_bf16(Bt[n][k], At[m][k], acc[ai][bj][m][n], 0, 0, 0); __builtin_amdgcn_s_setprio(0); } while (0)
; #define PG8_WAIT_V(n) asm volatile("s_waitcnt vmcnt(" #n ")" ::: "memory")
; #define PG8_WAIT_L(n) asm volatile("s_waitcnt lgkmcnt(" #n ")" ::: "memory")
; #define PG8_BAR __builtin_amdgcn_s_barrier()
; #define PG8_SCHED __builtin_amdgcn_sched_barrier(0)
; template <class Epi, class Sched>
; DI void gemm_phase(LAS unsigned char* lds, const int wv, const int lda, const int ldb, const Sched& S, const Epi& E) {
;     ...
;             PG8_WAIT_V(8); PG8_WAIT_L(0); PG8_BAR; PG8_MMA(0, 0, At, B0); PG8_MMA(0, 1, At, B1); PG8_BAR; PG8_SCHED;
;             PG8_LDA(At, 0, 1); PG8_STAGE(PG8_SB(0, 0), b2, voffB); PG8_STAGE(PG8_SB(0, 1), b2 + hstepB, voffB); PG8_STAGE(PG8_SA(0, 0), a2, voffA);
;             PG8_WAIT_V(8); PG8_WAIT_L(0); PG8_BAR; PG8_MMA(1, 0, At, B0); PG8_MMA(1, 1, At, B1); PG8_BAR; PG8_SCHED;
	v_mfma_f32_16x16x32_bf16 v[132:135], v[104:107], v[178:181], v[132:135]
	v_mfma_f32_16x16x32_bf16 v[128:131], v[150:153], v[178:181], v[128:131]
	v_mfma_f32_16x16x32_bf16 v[124:127], v[104:107], v[204:207], v[124:127]
	v_mfma_f32_16x16x32_bf16 v[120:123], v[150:153], v[204:207], v[120:123]
	v_mfma_f32_16x16x32_bf16 v[116:119], v[104:107], v[212:215], v[116:119]
	v_mfma_f32_16x16x32_bf16 v[112:115], v[150:153], v[212:215], v[112:115]
	v_mfma_f32_16x16x32_bf16 v[100:103], v[104:107], v[220:223], v[100:103]
	v_mfma_f32_16x16x32_bf16 v[96:99], v[150:153], v[220:223], v[96:99]
	v_mfma_f32_16x16x32_bf16 v[132:135], v[108:111], v[200:203], v[132:135]
	v_mfma_f32_16x16x32_bf16 v[128:131], v[154:157], v[200:203], v[128:131]
	v_mfma_f32_16x16x32_bf16 v[124:127], v[108:111], v[208:211], v[124:127]
	v_mfma_f32_16x16x32_bf16 v[120:123], v[154:157], v[208:211], v[120:123]
	v_mfma_f32_16x16x32_bf16 v[116:119], v[108:111], v[216:219], v[116:119]
	v_mfma_f32_16x16x32_bf16 v[112:115], v[154:157], v[216:219], v[112:115]
	v_mfma_f32_16x16x32_bf16 v[100:103], v[108:111], v[234:237], v[100:103]
	v_mfma_f32_16x16x32_bf16 v[96:99], v[154:157], v[234:237], v[96:99]
	v_mfma_f32_16x16x32_bf16 v[60:63], v[158:161], v[178:181], v[60:63]
	v_mfma_f32_16x16x32_bf16 v[56:59], v[166:169], v[178:181], v[56:59]
	v_mfma_f32_16x16x32_bf16 v[52:55], v[158:161], v[204:207], v[52:55]
	v_mfma_f32_16x16x32_bf16 v[48:51], v[166:169], v[204:207], v[48:51]
	v_mfma_f32_16x16x32_bf16 v[44:47], v[158:161], v[212:215], v[44:47]
	v_mfma_f32_16x16x32_bf16 v[40:43], v[166:169], v[212:215], v[40:43]
	v_mfma_f32_16x16x32_bf16 v[36:39], v[158:161], v[220:223], v[36:39]
	v_mfma_f32_16x16x32_bf16 v[32:35], v[166:169], v[220:223], v[32:35]
	v_mfma_f32_16x16x32_bf16 v[60:63], v[162:165], v[200:203], v[60:63]
	v_mfma_f32_16x16x32_bf16 v[56:59], v[174:177], v[200:203], v[56:59]
	v_mfma_f32_16x16x32_bf16 v[52:55], v[162:165], v[208:211], v[52:55]
	v_mfma_f32_16x16x32_bf16 v[48:51], v[174:177], v[208:211], v[48:51]
	v_mfma_f32_16x16x32_bf16 v[44:47], v[162:165], v[216:219], v[44:47]
	v_mfma_f32_16x16x32_bf16 v[40:43], v[174:177], v[216:219], v[40:43]
	v_mfma_f32_16x16x32_bf16 v[36:39], v[162:165], v[234:237], v[36:39]
	v_mfma_f32_16x16x32_bf16 v[32:35], v[174:177], v[234:237], v[32:35]
	s_add_i32 s61, s61, s47
	v_lshl_add_u64 v[182:183], s[36:37], 0, v[138:139]
	s_mov_b32 m0, s61
	s_barrier
	ds_read_b128 v[178:181], v172 offset:16384
	ds_read_b128 v[200:203], v172 offset:17408
	ds_read_b128 v[204:207], v172 offset:18432
	ds_read_b128 v[208:211], v172 offset:19456
	ds_read_b128 v[212:215], v172 offset:20480
	ds_read_b128 v[216:219], v172 offset:21504
	ds_read_b128 v[220:223], v172 offset:22528
	ds_read_b128 v[234:237], v172 offset:23552
	global_load_lds_dwordx4 v[182:183], off
	s_add_i32 m0, s61, 0x2000
	s_add_u32 s62, s36, 0x80000
	v_lshl_add_u64 v[188:189], s[36:37], 0, v[142:143]
	s_addc_u32 s63, s37, 0
	s_add_i32 s33, s33, s47
	global_load_lds_dwordx4 v[188:189], off
	v_lshl_add_u64 v[190:191], s[62:63], 0, v[138:139]
	s_mov_b32 m0, s33
	v_lshl_add_u64 v[196:197], s[38:39], 0, v[140:141]
	global_load_lds_dwordx4 v[190:191], off
	s_add_i32 m0, s33, 0x2000
	v_lshl_add_u64 v[190:191], s[62:63], 0, v[142:143]
	global_load_lds_dwordx4 v[190:191], off
	s_mov_b32 m0, s31
	v_lshl_add_u64 v[190:191], s[38:39], 0, v[136:137]
	global_load_lds_dwordx4 v[190:191], off
	s_mov_b32 m0, s48
	s_nop 0
	global_load_lds_dwordx4 v[196:197], off
	s_waitcnt vmcnt(8) lgkmcnt(0)
	s_barrier
	v_mfma_f32_16x16x32_bf16 v[92:95], v[104:107], v[178:181], v[92:95]
	v_mfma_f32_16x16x32_bf16 v[88:91], v[150:153], v[178:181], v[88:91]
	v_mfma_f32_16x16x32_bf16 v[84:87], v[104:107], v[204:207], v[84:87]
	v_mfma_f32_16x16x32_bf16 v[80:83], v[150:153], v[204:207], v[80:83]
	v_mfma_f32_16x16x32_bf16 v[76:79], v[104:107], v[212:215], v[76:79]
	v_mfma_f32_16x16x32_bf16 v[72:75], v[150:153], v[212:215], v[72:75]
	v_mfma_f32_16x16x32_bf16 v[68:71], v[104:107], v[220:223], v[68:71]
	v_mfma_f32_16x16x32_bf16 v[64:67], v[150:153], v[220:223], v[64:67]
	v_mfma_f32_16x16x32_bf16 v[92:95], v[108:111], v[200:203], v[92:95]
	v_mfma_f32_16x16x32_bf16 v[88:91], v[154:157], v[200:203], v[88:91]
	v_mfma_f32_16x16x32_bf16 v[84:87], v[108:111], v[208:211], v[84:87]
	v_mfma_f32_16x16x32_bf16 v[80:83], v[154:157], v[208:211], v[80:83]
	v_mfma_f32_16x16x32_bf16 v[76:79], v[108:111], v[216:219], v[76:79]
	v_mfma_f32_16x16x32_bf16 v[72:75], v[154:157], v[216:219], v[72:75]
	v_mfma_f32_16x16x32_bf16 v[68:71], v[108:111], v[234:237], v[68:71]
	v_mfma_f32_16x16x32_bf16 v[64:67], v[154:157], v[234:237], v[64:67]
	v_mfma_f32_16x16x32_bf16 v[28:31], v[158:161], v[178:181], v[28:31]
	v_mfma_f32_16x16x32_bf16 v[24:27], v[166:169], v[178:181], v[24:27]
	v_mfma_f32_16x16x32_bf16 v[20:23], v[158:161], v[204:207], v[20:23]
	v_mfma_f32_16x16x32_bf16 v[16:19], v[166:169], v[204:207], v[16:19]
	v_mfma_f32_16x16x32_bf16 v[12:15], v[158:161], v[212:215], v[12:15]
	v_mfma_f32_16x16x32_bf16 v[8:11], v[166:169], v[212:215], v[8:11]
	v_mfma_f32_16x16x32_bf16 v[4:7], v[158:161], v[220:223], v[4:7]
	v_mfma_f32_16x16x32_bf16 v[0:3], v[166:169], v[220:223], v[0:3]
	v_mfma_f32_16x16x32_bf16 v[28:31], v[162:165], v[200:203], v[28:31]
	v_mfma_f32_16x16x32_bf16 v[24:27], v[174:177], v[200:203], v[24:27]
	v_mfma_f32_16x16x32_bf16 v[20:23], v[162:165], v[208:211], v[20:23]
	v_mfma_f32_16x16x32_bf16 v[16:19], v[174:177], v[208:211], v[16:19]
	v_mfma_f32_16x16x32_bf16 v[12:15], v[162:165], v[216:219], v[12:15]
	v_mfma_f32_16x16x32_bf16 v[8:11], v[174:177], v[216:219], v[8:11]
	v_mfma_f32_16x16x32_bf16 v[4:7], v[162:165], v[234:237], v[4:7]
	v_mfma_f32_16x16x32_bf16 v[0:3], v[174:177], v[234:237], v[0:3]
	s_add_i32 s33, 0, 0x18000
	s_add_i32 s61, 0, 0x1c000
	s_barrier
; #define PG8_STAGE(bufoff, gbase, voff) do { _Pragma("unroll") for (int _i = 0; _i < 2; ++_i) \
;         __builtin_amdgcn_global_load_lds((const unsigned*)((const char*)(gbase) + (voff)[_i]), (LAS unsigned*)(lds + (bufoff) + ldsw + _i * 8192), 16, 0, 0); } while (0)
; #define PG8_LDA(dst, b, h) do { _Pragma("unroll") for (int m = 0; m < 4; ++m) _Pragma("unroll") for (int k = 0; k < 2; ++k) dst[m][k] = *(const LAS bf16x8*)(lds + PG8_SA(b, h) + aoff + m * 2048 + k * 1024); } while (0)
; #define PG8_LDB(dst, b, h) do { _Pragma("unroll") for (int n = 0; n < 2; ++n) _Pragma("unroll") for (int k = 0; k < 2; ++k) dst[n][k] = *(const LAS bf16x8*)(lds + PG8_SB(b, h) + boff + n * 2048 + k * 1024); } while (0)
; #define PG8_MMA(ai, bj, At, Bt) do { __builtin_amdgcn_s_setprio(1); _Pragma("unroll") for (int m = 0; m < 4; ++m) _Pragma("unroll") for (int n = 0; n < 2; ++n) _Pragma("unroll") for (int k = 0; k < 2; ++k) \
;         acc[ai][bj][m][n] = __builtin_amdgcn_mfma_f32_16x16x32_bf16(Bt[n][k], At[m][k], acc[ai][bj][m][n], 0, 0, 0); __builtin_amdgcn_s_setprio(0); } while (0)
; #define PG8_WAIT_V(n) asm volatile("s_waitcnt vmcnt(" #n ")" ::: "memory")
; #define PG8_WAIT_L(n) asm volatile("s_waitcnt lgkmcnt(" #n ")" ::: "memory")
; #define PG8_BAR __builtin_amdgcn_s_barrier()
; #define PG8_SCHED __builtin_amdgcn_sched_barrier(0)
; template <class Epi, class Sched>
; DI void gemm_phase(LAS unsigned char* lds, const int wv, const int lda, const int ldb, const Sched& S, const Epi& E) {
;     ...
;             PG8_LDB(B0, 1, 0); PG8_LDB(B1, 1, 1); PG8_SCHED; PG8_LDA(At, 1, 0); PG8_STAGE(PG8_SA(0, 1), a2 + hstepA, voffA);
;             PG8_WAIT_V(8); PG8_WAIT_L(0); PG8_BAR; PG8_MMA(0, 0, At, B0); PG8_MMA(0, 1, At, B1); PG8_BAR; PG8_SCHED;
;             PG8_LDA(At, 1, 1); PG8_STAGE(PG8_SB(1, 0), b3, voffB); PG8_STAGE(PG8_SB(1, 1), b3 + hstepB, voffB); PG8_STAGE(PG8_SA(1, 0), a3, voffA);
;             PG8_WAIT_V(8); PG8_WAIT_L(0); PG8_BAR; PG8_MMA(1, 0, At, B0); PG8_MMA(1, 1, At, B1); PG8_BAR; PG8_SCHED;
;         }
	v_add_u32_e32 v154, s33, v170
	v_add_u32_e32 v173, s61, v170
	ds_read_b128 v[104:107], v154
	ds_read_b128 v[108:111], v154 offset:1024
	ds_read_b128 v[150:153], v154 offset:2048
	ds_read_b128 v[154:157], v154 offset:3072
	ds_read_b128 v[158:161], v173
	ds_read_b128 v[162:165], v173 offset:1024
	ds_read_b128 v[166:169], v173 offset:2048
	ds_read_b128 v[174:177], v173 offset:3072
	s_add_u32 s38, s38, 0x80000
	s_addc_u32 s39, s39, 0
	s_mov_b32 m0, s49
	v_lshl_add_u64 v[198:199], s[38:39], 0, v[136:137]
	ds_read_b128 v[178:181], v172 offset:32768
	ds_read_b128 v[200:203], v172 offset:33792
	ds_read_b128 v[204:207], v172 offset:34816
	ds_read_b128 v[208:211], v172 offset:35840
	ds_read_b128 v[212:215], v172 offset:36864
	ds_read_b128 v[216:219], v172 offset:37888
	ds_read_b128 v[220:223], v172 offset:38912
	ds_read_b128 v[234:237], v172 offset:39936
	global_load_lds_dwordx4 v[198:199], off
	s_mov_b32 m0, s50
	v_lshl_add_u64 v[198:199], s[38:39], 0, v[140:141]
	global_load_lds_dwordx4 v[198:199], off
	s_waitcnt vmcnt(8) lgkmcnt(0)
	s_barrier
	v_mfma_f32_16x16x32_bf16 v[132:135], v[104:107], v[178:181], v[132:135]
	v_mfma_f32_16x16x32_bf16 v[128:131], v[150:153], v[178:181], v[128:131]
	v_mfma_f32_16x16x32_bf16 v[124:127], v[104:107], v[204:207], v[124:127]
	v_mfma_f32_16x16x32_bf16 v[120:123], v[150:153], v[204:207], v[120:123]
	v_mfma_f32_16x16x32_bf16 v[116:119], v[104:107], v[212:215], v[116:119]
	v_mfma_f32_16x16x32_bf16 v[112:115], v[150:153], v[212:215], v[112:115]
	v_mfma_f32_16x16x32_bf16 v[100:103], v[104:107], v[220:223], v[100:103]
	v_mfma_f32_16x16x32_bf16 v[96:99], v[150:153], v[220:223], v[96:99]
	v_mfma_f32_16x16x32_bf16 v[132:135], v[108:111], v[200:203], v[132:135]
	v_mfma_f32_16x16x32_bf16 v[128:131], v[154:157], v[200:203], v[128:131]
	v_mfma_f32_16x16x32_bf16 v[124:127], v[108:111], v[208:211], v[124:127]
	v_mfma_f32_16x16x32_bf16 v[120:123], v[154:157], v[208:211], v[120:123]
	v_mfma_f32_16x16x32_bf16 v[116:119], v[108:111], v[216:219], v[116:119]
	v_mfma_f32_16x16x32_bf16 v[112:115], v[154:157], v[216:219], v[112:115]
	v_mfma_f32_16x16x32_bf16 v[100:103], v[108:111], v[234:237], v[100:103]
	v_mfma_f32_16x16x32_bf16 v[96:99], v[154:157], v[234:237], v[96:99]
	v_mfma_f32_16x16x32_bf16 v[60:63], v[158:161], v[178:181], v[60:63]
	v_mfma_f32_16x16x32_bf16 v[56:59], v[166:169], v[178:181], v[56:59]
	v_mfma_f32_16x16x32_bf16 v[52:55], v[158:161], v[204:207], v[52:55]
	v_mfma_f32_16x16x32_bf16 v[48:51], v[166:169], v[204:207], v[48:51]
	v_mfma_f32_16x16x32_bf16 v[44:47], v[158:161], v[212:215], v[44:47]
	v_mfma_f32_16x16x32_bf16 v[40:43], v[166:169], v[212:215], v[40:43]
	v_mfma_f32_16x16x32_bf16 v[36:39], v[158:161], v[220:223], v[36:39]
	v_mfma_f32_16x16x32_bf16 v[32:35], v[166:169], v[220:223], v[32:35]
	v_mfma_f32_16x16x32_bf16 v[60:63], v[162:165], v[200:203], v[60:63]
	v_mfma_f32_16x16x32_bf16 v[56:59], v[174:177], v[200:203], v[56:59]
	v_mfma_f32_16x16x32_bf16 v[52:55], v[162:165], v[208:211], v[52:55]
	v_mfma_f32_16x16x32_bf16 v[48:51], v[174:177], v[208:211], v[48:51]
	v_mfma_f32_16x16x32_bf16 v[44:47], v[162:165], v[216:219], v[44:47]
	v_mfma_f32_16x16x32_bf16 v[40:43], v[174:177], v[216:219], v[40:43]
	v_mfma_f32_16x16x32_bf16 v[36:39], v[162:165], v[234:237], v[36:39]
	v_mfma_f32_16x16x32_bf16 v[32:35], v[174:177], v[234:237], v[32:35]
	s_add_i32 s33, s33, s47
	v_lshl_add_u64 v[182:183], v[182:183], 0, s[28:29]
	s_mov_b32 m0, s33
	s_barrier
	ds_read_b128 v[178:181], v172 offset:49152
	ds_read_b128 v[200:203], v172 offset:50176
	ds_read_b128 v[204:207], v172 offset:51200
	ds_read_b128 v[208:211], v172 offset:52224
	ds_read_b128 v[212:215], v172 offset:53248
	ds_read_b128 v[216:219], v172 offset:54272
	ds_read_b128 v[220:223], v172 offset:55296
	ds_read_b128 v[234:237], v172 offset:56320
	global_load_lds_dwordx4 v[182:183], off
	s_add_i32 m0, s33, 0x2000
	s_add_u32 s36, s36, 0x80080
	v_lshl_add_u64 v[182:183], v[188:189], 0, s[28:29]
	s_addc_u32 s37, s37, 0
	s_add_i32 s33, s61, s47
	global_load_lds_dwordx4 v[182:183], off
	s_mov_b32 m0, s33
	v_lshl_add_u64 v[182:183], s[36:37], 0, v[138:139]
	global_load_lds_dwordx4 v[182:183], off
	s_add_i32 m0, s33, 0x2000
	v_lshl_add_u64 v[182:183], s[36:37], 0, v[142:143]
	global_load_lds_dwordx4 v[182:183], off
	s_mov_b32 m0, s52
	v_lshl_add_u64 v[182:183], v[190:191], 0, s[28:29]
	global_load_lds_dwordx4 v[182:183], off
	s_mov_b32 m0, s53
	v_lshl_add_u64 v[182:183], v[196:197], 0, s[28:29]
	global_load_lds_dwordx4 v[182:183], off
	s_waitcnt vmcnt(8) lgkmcnt(0)
	s_barrier
	v_mfma_f32_16x16x32_bf16 v[92:95], v[104:107], v[178:181], v[92:95]
	v_mfma_f32_16x16x32_bf16 v[88:91], v[150:153], v[178:181], v[88:91]
	v_mfma_f32_16x16x32_bf16 v[84:87], v[104:107], v[204:207], v[84:87]
	v_mfma_f32_16x16x32_bf16 v[80:83], v[150:153], v[204:207], v[80:83]
	v_mfma_f32_16x16x32_bf16 v[76:79], v[104:107], v[212:215], v[76:79]
	v_mfma_f32_16x16x32_bf16 v[72:75], v[150:153], v[212:215], v[72:75]
	v_mfma_f32_16x16x32_bf16 v[68:71], v[104:107], v[220:223], v[68:71]
	v_mfma_f32_16x16x32_bf16 v[64:67], v[150:153], v[220:223], v[64:67]
	v_mfma_f32_16x16x32_bf16 v[92:95], v[108:111], v[200:203], v[92:95]
	v_mfma_f32_16x16x32_bf16 v[88:91], v[154:157], v[200:203], v[88:91]
	v_mfma_f32_16x16x32_bf16 v[84:87], v[108:111], v[208:211], v[84:87]
	v_mfma_f32_16x16x32_bf16 v[80:83], v[154:157], v[208:211], v[80:83]
	v_mfma_f32_16x16x32_bf16 v[76:79], v[108:111], v[216:219], v[76:79]
	v_mfma_f32_16x16x32_bf16 v[72:75], v[154:157], v[216:219], v[72:75]
	v_mfma_f32_16x16x32_bf16 v[68:71], v[108:111], v[234:237], v[68:71]
	v_mfma_f32_16x16x32_bf16 v[64:67], v[154:157], v[234:237], v[64:67]
	v_mfma_f32_16x16x32_bf16 v[28:31], v[158:161], v[178:181], v[28:31]
	v_mfma_f32_16x16x32_bf16 v[24:27], v[166:169], v[178:181], v[24:27]
	v_mfma_f32_16x16x32_bf16 v[20:23], v[158:161], v[204:207], v[20:23]
	v_mfma_f32_16x16x32_bf16 v[16:19], v[166:169], v[204:207], v[16:19]
	v_mfma_f32_16x16x32_bf16 v[12:15], v[158:161], v[212:215], v[12:15]
	v_mfma_f32_16x16x32_bf16 v[8:11], v[166:169], v[212:215], v[8:11]
	v_mfma_f32_16x16x32_bf16 v[4:7], v[158:161], v[220:223], v[4:7]
	v_mfma_f32_16x16x32_bf16 v[0:3], v[166:169], v[220:223], v[0:3]
	v_mfma_f32_16x16x32_bf16 v[28:31], v[162:165], v[200:203], v[28:31]
	v_mfma_f32_16x16x32_bf16 v[24:27], v[174:177], v[200:203], v[24:27]
	v_mfma_f32_16x16x32_bf16 v[20:23], v[162:165], v[208:211], v[20:23]
	v_mfma_f32_16x16x32_bf16 v[16:19], v[174:177], v[208:211], v[16:19]
	v_mfma_f32_16x16x32_bf16 v[12:15], v[162:165], v[216:219], v[12:15]
	v_mfma_f32_16x16x32_bf16 v[8:11], v[174:177], v[216:219], v[8:11]
	v_mfma_f32_16x16x32_bf16 v[4:7], v[162:165], v[234:237], v[4:7]
	v_mfma_f32_16x16x32_bf16 v[0:3], v[174:177], v[234:237], v[0:3]
	s_add_i32 s23, s23, 2
	s_add_u32 s34, s34, 0x100
	s_addc_u32 s35, s35, 0
	s_add_u32 s17, s17, 0x100
	s_addc_u32 s19, s19, 0
	s_cmp_gt_u32 s23, 29
	s_barrier
	s_cbranch_scc0 .LBB0_378
	s_and_b64 vcc, exec, s[14:15]
	s_cbranch_vccz .LBB0_381
	s_barrier

;     DI bool next(int i, Unit& u) const { const long L = (long)i * G + c; if (L >= T.nwg) return false; T.map((int)L, u.pm, u.pn); u.seg = 0; return true; }
;     DI bool next(int i, Unit& u) const { const int ti = i / 3; const long L = (long)ti * G + c; if (L >= T.nwg) return false; T.map((int)L, u.pm, u.pn); u.seg = i - 3 * ti; return true; }
;     DI const char* aptr(const Unit& u) const { return A + (size_t)u.pm * ta + (size_t)kofs(u.seg) * 2; }
;     DI const char* bptr(const Unit& u) const { return B + (size_t)u.pn * tb + (size_t)kofs(u.seg) * 2; }
; #define PG8_STAGE(bufoff, gbase, voff) do { _Pragma("unroll") for (int _i = 0; _i < 2; ++_i) \
;         __builtin_amdgcn_global_load_lds((const unsigned*)((const char*)(gbase) + (voff)[_i]), (LAS unsigned*)(lds + (bufoff) + ldsw + _i * 8192), 16, 0, 0); } while (0)
; #define PG8_LDA(dst, b, h) do { _Pragma("unroll") for (int m = 0; m < 4; ++m) _Pragma("unroll") for (int k = 0; k < 2; ++k) dst[m][k] = *(const LAS bf16x8*)(lds + PG8_SA(b, h) + aoff + m * 2048 + k * 1024); } while (0)
; #define PG8_WAIT_V(n) asm volatile("s_waitcnt vmcnt(" #n ")" ::: "memory")
; #define PG8_WAIT_L(n) asm volatile("s_waitcnt lgkmcnt(" #n ")" ::: "memory")
; template <class Epi, class Sched>
; DI void gemm_phase(LAS unsigned char* lds, const int wv, const int lda, const int ldb, const Sched& S, const Epi& E) {
;     ...
;         const bool has_next = S.next(ui + 1, nxt);
;         const char* nA = has_next ? S.aptr(nxt) : cA; const char* nB = has_next ? S.bptr(nxt) : cB;
;         for (int t = 0; t < nt; t += 2) {
;             const bool last = (t == nt - 2);
;             const char* a1 = cA + (size_t)(t + 1) * kstep;
;             const char* a2 = last ? nA : cA + (size_t)(t + 2) * kstep; const char* b2 = last ? nB : cB + (size_t)(t + 2) * kstep;
;             const char* a3 = a2 + kstep; const char* b3 = b2 + kstep;
;             PG8_LDB(B0, 0, 0); PG8_LDB(B1, 0, 1); PG8_SCHED; PG8_LDA(At, 0, 0); PG8_STAGE(PG8_SA(1, 1), a1 + hstepA, voffA);
;             PG8_WAIT_V(8); PG8_WAIT_L(0); PG8_BAR; PG8_MMA(0, 0, At, B0); PG8_MMA(0, 1, At, B1); PG8_BAR; PG8_SCHED;
;             PG8_LDA(At, 0, 1); PG8_STAGE(PG8_SB(0, 0), b2, voffB); PG8_STAGE(PG8_SB(0, 1), b2 + hstepB, voffB); PG8_STAGE(PG8_SA(0, 0), a2, voffA);
;             PG8_WAIT_V(8); PG8_WAIT_L(0); PG8_BAR; PG8_MMA(1, 0, At, B0); PG8_MMA(1, 1, At, B1); PG8_BAR; PG8_SCHED;
.LBB0_1098:
	s_add_u32 s0, s24, 0x100
	s_addc_u32 s1, s25, 0
	s_mov_b32 s49, -2
	s_add_u32 s24, s22, 0x100
	s_addc_u32 s25, s23, 0
	s_add_i32 s50, 0, 0x10000
	s_cmp_eq_u32 s49, 8
	s_cselect_b32 s31, s7, s25
	s_cselect_b32 s30, s6, s24
	s_cselect_b32 s27, s19, s1
	s_cselect_b32 s26, s18, s0
	s_add_i32 s51, 0, 0x14000
	v_add_u32_e32 v108, s50, v204
	v_add_u32_e32 v156, s51, v204
	ds_read_b128 v[64:67], v108
	ds_read_b128 v[68:71], v108 offset:1024
	ds_read_b128 v[104:107], v108 offset:2048
	ds_read_b128 v[108:111], v108 offset:3072
	ds_read_b128 v[144:147], v156
	ds_read_b128 v[148:151], v156 offset:1024
	ds_read_b128 v[152:155], v156 offset:2048
	ds_read_b128 v[156:159], v156 offset:3072
	v_lshl_add_u64 v[182:183], s[22:23], 0, v[174:175]
	s_add_i32 m0, s38, 0xc000
	ds_read_b128 v[160:163], v206
	ds_read_b128 v[164:167], v206 offset:1024
	ds_read_b128 v[178:181], v206 offset:2048
	ds_read_b128 v[188:191], v206 offset:3072
	ds_read_b128 v[196:199], v206 offset:4096
	ds_read_b128 v[200:203], v206 offset:5120
	ds_read_b128 v[208:211], v206 offset:6144
	ds_read_b128 v[212:215], v206 offset:7168
	global_load_lds_dwordx4 v[182:183], off
	s_add_i32 m0, s38, 0xe000
	v_lshl_add_u64 v[182:183], s[22:23], 0, v[176:177]
	global_load_lds_dwordx4 v[182:183], off
	s_waitcnt vmcnt(8) lgkmcnt(0)
	s_barrier
	v_mfma_f32_16x16x32_bf16 v[140:143], v[64:67], v[160:163], 0
	v_mfma_f32_16x16x32_bf16 v[136:139], v[104:107], v[160:163], 0
	v_mfma_f32_16x16x32_bf16 v[132:135], v[64:67], v[178:181], 0
	v_mfma_f32_16x16x32_bf16 v[128:131], v[104:107], v[178:181], 0
	v_mfma_f32_16x16x32_bf16 v[124:127], v[64:67], v[196:199], 0
	v_mfma_f32_16x16x32_bf16 v[120:123], v[104:107], v[196:199], 0
	v_mfma_f32_16x16x32_bf16 v[116:119], v[64:67], v[208:211], 0
	v_mfma_f32_16x16x32_bf16 v[112:115], v[104:107], v[208:211], 0
	v_mfma_f32_16x16x32_bf16 v[140:143], v[68:71], v[164:167], v[140:143]
	v_mfma_f32_16x16x32_bf16 v[136:139], v[108:111], v[164:167], v[136:139]
	v_mfma_f32_16x16x32_bf16 v[132:135], v[68:71], v[188:191], v[132:135]
	v_mfma_f32_16x16x32_bf16 v[128:131], v[108:111], v[188:191], v[128:131]
	v_mfma_f32_16x16x32_bf16 v[124:127], v[68:71], v[200:203], v[124:127]
	v_mfma_f32_16x16x32_bf16 v[120:123], v[108:111], v[200:203], v[120:123]
	v_mfma_f32_16x16x32_bf16 v[116:119], v[68:71], v[212:215], v[116:119]
	v_mfma_f32_16x16x32_bf16 v[112:115], v[108:111], v[212:215], v[112:115]
	v_mfma_f32_16x16x32_bf16 v[100:103], v[144:147], v[160:163], 0
	v_mfma_f32_16x16x32_bf16 v[96:99], v[152:155], v[160:163], 0
	v_mfma_f32_16x16x32_bf16 v[92:95], v[144:147], v[178:181], 0
	v_mfma_f32_16x16x32_bf16 v[88:91], v[152:155], v[178:181], 0
	v_mfma_f32_16x16x32_bf16 v[84:87], v[144:147], v[196:199], 0
	v_mfma_f32_16x16x32_bf16 v[80:83], v[152:155], v[196:199], 0
	v_mfma_f32_16x16x32_bf16 v[76:79], v[144:147], v[208:211], 0
	v_mfma_f32_16x16x32_bf16 v[72:75], v[152:155], v[208:211], 0
	v_mfma_f32_16x16x32_bf16 v[100:103], v[148:151], v[164:167], v[100:103]
	v_mfma_f32_16x16x32_bf16 v[96:99], v[156:159], v[164:167], v[96:99]
	v_mfma_f32_16x16x32_bf16 v[92:95], v[148:151], v[188:191], v[92:95]
	v_mfma_f32_16x16x32_bf16 v[88:91], v[156:159], v[188:191], v[88:91]
	v_mfma_f32_16x16x32_bf16 v[84:87], v[148:151], v[200:203], v[84:87]
	v_mfma_f32_16x16x32_bf16 v[80:83], v[156:159], v[200:203], v[80:83]
	v_mfma_f32_16x16x32_bf16 v[76:79], v[148:151], v[212:215], v[76:79]
	v_mfma_f32_16x16x32_bf16 v[72:75], v[156:159], v[212:215], v[72:75]
	s_add_i32 s22, s50, s36
	v_lshl_add_u64 v[182:183], s[26:27], 0, v[184:185]
	s_mov_b32 m0, s22
	s_barrier
	ds_read_b128 v[160:163], v206 offset:16384
	ds_read_b128 v[164:167], v206 offset:17408
	ds_read_b128 v[178:181], v206 offset:18432
	ds_read_b128 v[188:191], v206 offset:19456
	ds_read_b128 v[196:199], v206 offset:20480
	ds_read_b128 v[200:203], v206 offset:21504
	ds_read_b128 v[208:211], v206 offset:22528
	ds_read_b128 v[212:215], v206 offset:23552
	global_load_lds_dwordx4 v[182:183], off
	s_add_i32 m0, s22, 0x2000
	s_add_u32 s22, s26, 0x30000
	v_lshl_add_u64 v[216:217], s[26:27], 0, v[168:169]
	s_addc_u32 s23, s27, 0
	s_add_i32 s50, s51, s36
	global_load_lds_dwordx4 v[216:217], off
	v_lshl_add_u64 v[218:219], s[22:23], 0, v[184:185]
	s_mov_b32 m0, s50
	v_lshl_add_u64 v[220:221], s[30:31], 0, v[170:171]
	global_load_lds_dwordx4 v[218:219], off
	s_add_i32 m0, s50, 0x2000
	v_lshl_add_u64 v[218:219], s[22:23], 0, v[168:169]
	global_load_lds_dwordx4 v[218:219], off
	s_mov_b32 m0, s38
	v_lshl_add_u64 v[218:219], s[30:31], 0, v[172:173]
	global_load_lds_dwordx4 v[218:219], off
	s_mov_b32 m0, s39
	s_nop 0
	global_load_lds_dwordx4 v[220:221], off
	s_waitcnt vmcnt(8) lgkmcnt(0)
	s_barrier
; #define PG8_STAGE(bufoff, gbase, voff) do { _Pragma("unroll") for (int _i = 0; _i < 2; ++_i) \
;         __builtin_amdgcn_global_load_lds((const unsigned*)((const char*)(gbase) + (voff)[_i]), (LAS unsigned*)(lds + (bufoff) + ldsw + _i * 8192), 16, 0, 0); } while (0)
; #define PG8_LDA(dst, b, h) do { _Pragma("unroll") for (int m = 0; m < 4; ++m) _Pragma("unroll") for (int k = 0; k < 2; ++k) dst[m][k] = *(const LAS bf16x8*)(lds + PG8_SA(b, h) + aoff + m * 2048 + k * 1024); } while (0)
; #define PG8_LDB(dst, b, h) do { _Pragma("unroll") for (int n = 0; n < 2; ++n) _Pragma("unroll") for (int k = 0; k < 2; ++k) dst[n][k] = *(const LAS bf16x8*)(lds + PG8_SB(b, h) + boff + n * 2048 + k * 1024); } while (0)
; #define PG8_MMA(ai, bj, At, Bt) do { __builtin_amdgcn_s_setprio(1); _Pragma("unroll") for (int m = 0; m < 4; ++m) _Pragma("unroll") for (int n = 0; n < 2; ++n) _Pragma("unroll") for (int k = 0; k < 2; ++k) \
;         acc[ai][bj][m][n] = __builtin_amdgcn_mfma_f32_16x16x32_bf16(Bt[n][k], At[m][k], acc[ai][bj][m][n], 0, 0, 0); __builtin_amdgcn_s_setprio(0); } while (0)
; #define PG8_WAIT_V(n) asm volatile("s_waitcnt vmcnt(" #n ")" ::: "memory")
; #define PG8_WAIT_L(n) asm volatile("s_waitcnt lgkmcnt(" #n ")" ::: "memory")
; #define PG8_BAR __builtin_amdgcn_s_barrier()
; #define PG8_SCHED __builtin_amdgcn_sched_barrier(0)
; template <class Epi, class Sched>
; DI void gemm_phase(LAS unsigned char* lds, const int wv, const int lda, const int ldb, const Sched& S, const Epi& E) {
;     ...
;             PG8_LDA(At, 0, 1); PG8_STAGE(PG8_SB(0, 0), b2, voffB); PG8_STAGE(PG8_SB(0, 1), b2 + hstepB, voffB); PG8_STAGE(PG8_SA(0, 0), a2, voffA);
;             PG8_WAIT_V(8); PG8_WAIT_L(0); PG8_BAR; PG8_MMA(1, 0, At, B0); PG8_MMA(1, 1, At, B1); PG8_BAR; PG8_SCHED;
;             PG8_LDB(B0, 1, 0); PG8_LDB(B1, 1, 1); PG8_SCHED; PG8_LDA(At, 1, 0); PG8_STAGE(PG8_SA(0, 1), a2 + hstepA, voffA);
;             PG8_WAIT_V(8); PG8_WAIT_L(0); PG8_BAR; PG8_MMA(0, 0, At, B0); PG8_MMA(0, 1, At, B1); PG8_BAR; PG8_SCHED;
	v_mfma_f32_16x16x32_bf16 v[60:63], v[64:67], v[160:163], 0
	v_mfma_f32_16x16x32_bf16 v[56:59], v[104:107], v[160:163], 0
	v_mfma_f32_16x16x32_bf16 v[52:55], v[64:67], v[178:181], 0
	v_mfma_f32_16x16x32_bf16 v[48:51], v[104:107], v[178:181], 0
	v_mfma_f32_16x16x32_bf16 v[44:47], v[64:67], v[196:199], 0
	v_mfma_f32_16x16x32_bf16 v[40:43], v[104:107], v[196:199], 0
	v_mfma_f32_16x16x32_bf16 v[36:39], v[64:67], v[208:211], 0
	v_mfma_f32_16x16x32_bf16 v[32:35], v[104:107], v[208:211], 0
	v_mfma_f32_16x16x32_bf16 v[60:63], v[68:71], v[164:167], v[60:63]
	v_mfma_f32_16x16x32_bf16 v[56:59], v[108:111], v[164:167], v[56:59]
	v_mfma_f32_16x16x32_bf16 v[52:55], v[68:71], v[188:191], v[52:55]
	v_mfma_f32_16x16x32_bf16 v[48:51], v[108:111], v[188:191], v[48:51]
	v_mfma_f32_16x16x32_bf16 v[44:47], v[68:71], v[200:203], v[44:47]
	v_mfma_f32_16x16x32_bf16 v[40:43], v[108:111], v[200:203], v[40:43]
	v_mfma_f32_16x16x32_bf16 v[36:39], v[68:71], v[212:215], v[36:39]
	v_mfma_f32_16x16x32_bf16 v[32:35], v[108:111], v[212:215], v[32:35]
	v_mfma_f32_16x16x32_bf16 v[28:31], v[144:147], v[160:163], 0
	v_mfma_f32_16x16x32_bf16 v[24:27], v[152:155], v[160:163], 0
	v_mfma_f32_16x16x32_bf16 v[20:23], v[144:147], v[178:181], 0
	v_mfma_f32_16x16x32_bf16 v[16:19], v[152:155], v[178:181], 0
	v_mfma_f32_16x16x32_bf16 v[12:15], v[144:147], v[196:199], 0
	v_mfma_f32_16x16x32_bf16 v[8:11], v[152:155], v[196:199], 0
	v_mfma_f32_16x16x32_bf16 v[4:7], v[144:147], v[208:211], 0
	v_mfma_f32_16x16x32_bf16 v[0:3], v[152:155], v[208:211], 0
	v_mfma_f32_16x16x32_bf16 v[28:31], v[148:151], v[164:167], v[28:31]
	v_mfma_f32_16x16x32_bf16 v[24:27], v[156:159], v[164:167], v[24:27]
	v_mfma_f32_16x16x32_bf16 v[20:23], v[148:151], v[188:191], v[20:23]
	v_mfma_f32_16x16x32_bf16 v[16:19], v[156:159], v[188:191], v[16:19]
	v_mfma_f32_16x16x32_bf16 v[12:15], v[148:151], v[200:203], v[12:15]
	v_mfma_f32_16x16x32_bf16 v[8:11], v[156:159], v[200:203], v[8:11]
	v_mfma_f32_16x16x32_bf16 v[4:7], v[148:151], v[212:215], v[4:7]
	v_mfma_f32_16x16x32_bf16 v[0:3], v[156:159], v[212:215], v[0:3]
	s_add_i32 s50, 0, 0x18000
	s_add_i32 s51, 0, 0x1c000
	s_barrier
	v_add_u32_e32 v108, s50, v204
	v_add_u32_e32 v156, s51, v204
	ds_read_b128 v[64:67], v108
	ds_read_b128 v[68:71], v108 offset:1024
	ds_read_b128 v[104:107], v108 offset:2048
	ds_read_b128 v[108:111], v108 offset:3072
	ds_read_b128 v[144:147], v156
	ds_read_b128 v[148:151], v156 offset:1024
	ds_read_b128 v[152:155], v156 offset:2048
	ds_read_b128 v[156:159], v156 offset:3072
	s_add_u32 s22, s30, 0x30000
	s_addc_u32 s23, s31, 0
	s_mov_b32 m0, s40
	v_lshl_add_u64 v[222:223], s[22:23], 0, v[172:173]
	ds_read_b128 v[160:163], v206 offset:32768
	ds_read_b128 v[164:167], v206 offset:33792
	ds_read_b128 v[178:181], v206 offset:34816
	ds_read_b128 v[188:191], v206 offset:35840
	ds_read_b128 v[196:199], v206 offset:36864
	ds_read_b128 v[200:203], v206 offset:37888
	ds_read_b128 v[208:211], v206 offset:38912
	ds_read_b128 v[212:215], v206 offset:39936
	global_load_lds_dwordx4 v[222:223], off
	s_mov_b32 m0, s41
	v_lshl_add_u64 v[222:223], s[22:23], 0, v[170:171]
	global_load_lds_dwordx4 v[222:223], off
	s_waitcnt vmcnt(8) lgkmcnt(0)
	s_barrier
	v_mfma_f32_16x16x32_bf16 v[140:143], v[64:67], v[160:163], v[140:143]
	v_mfma_f32_16x16x32_bf16 v[136:139], v[104:107], v[160:163], v[136:139]
	v_mfma_f32_16x16x32_bf16 v[132:135], v[64:67], v[178:181], v[132:135]
	v_mfma_f32_16x16x32_bf16 v[128:131], v[104:107], v[178:181], v[128:131]
	v_mfma_f32_16x16x32_bf16 v[124:127], v[64:67], v[196:199], v[124:127]
	v_mfma_f32_16x16x32_bf16 v[120:123], v[104:107], v[196:199], v[120:123]
	v_mfma_f32_16x16x32_bf16 v[116:119], v[64:67], v[208:211], v[116:119]
	v_mfma_f32_16x16x32_bf16 v[112:115], v[104:107], v[208:211], v[112:115]
	v_mfma_f32_16x16x32_bf16 v[140:143], v[68:71], v[164:167], v[140:143]
	v_mfma_f32_16x16x32_bf16 v[136:139], v[108:111], v[164:167], v[136:139]
	v_mfma_f32_16x16x32_bf16 v[132:135], v[68:71], v[188:191], v[132:135]
	v_mfma_f32_16x16x32_bf16 v[128:131], v[108:111], v[188:191], v[128:131]
	v_mfma_f32_16x16x32_bf16 v[124:127], v[68:71], v[200:203], v[124:127]
	v_mfma_f32_16x16x32_bf16 v[120:123], v[108:111], v[200:203], v[120:123]
	v_mfma_f32_16x16x32_bf16 v[116:119], v[68:71], v[212:215], v[116:119]
	v_mfma_f32_16x16x32_bf16 v[112:115], v[108:111], v[212:215], v[112:115]
	v_mfma_f32_16x16x32_bf16 v[100:103], v[144:147], v[160:163], v[100:103]
	v_mfma_f32_16x16x32_bf16 v[96:99], v[152:155], v[160:163], v[96:99]
	v_mfma_f32_16x16x32_bf16 v[92:95], v[144:147], v[178:181], v[92:95]
	v_mfma_f32_16x16x32_bf16 v[88:91], v[152:155], v[178:181], v[88:91]
	v_mfma_f32_16x16x32_bf16 v[84:87], v[144:147], v[196:199], v[84:87]
	v_mfma_f32_16x16x32_bf16 v[80:83], v[152:155], v[196:199], v[80:83]
	v_mfma_f32_16x16x32_bf16 v[76:79], v[144:147], v[208:211], v[76:79]
	v_mfma_f32_16x16x32_bf16 v[72:75], v[152:155], v[208:211], v[72:75]
	v_mfma_f32_16x16x32_bf16 v[100:103], v[148:151], v[164:167], v[100:103]
	v_mfma_f32_16x16x32_bf16 v[96:99], v[156:159], v[164:167], v[96:99]
	v_mfma_f32_16x16x32_bf16 v[92:95], v[148:151], v[188:191], v[92:95]
	v_mfma_f32_16x16x32_bf16 v[88:91], v[156:159], v[188:191], v[88:91]
	v_mfma_f32_16x16x32_bf16 v[84:87], v[148:151], v[200:203], v[84:87]
	v_mfma_f32_16x16x32_bf16 v[80:83], v[156:159], v[200:203], v[80:83]
	v_mfma_f32_16x16x32_bf16 v[76:79], v[148:151], v[212:215], v[76:79]
	v_mfma_f32_16x16x32_bf16 v[72:75], v[156:159], v[212:215], v[72:75]
	s_add_i32 s22, s50, s36
	v_lshl_add_u64 v[182:183], v[182:183], 0, s[28:29]
	s_mov_b32 m0, s22
	s_barrier
; #define PG8_STAGE(bufoff, gbase, voff) do { _Pragma("unroll") for (int _i = 0; _i < 2; ++_i) \
;         __builtin_amdgcn_global_load_lds((const unsigned*)((const char*)(gbase) + (voff)[_i]), (LAS unsigned*)(lds + (bufoff) + ldsw + _i * 8192), 16, 0, 0); } while (0)
; #define PG8_LDA(dst, b, h) do { _Pragma("unroll") for (int m = 0; m < 4; ++m) _Pragma("unroll") for (int k = 0; k < 2; ++k) dst[m][k] = *(const LAS bf16x8*)(lds + PG8_SA(b, h) + aoff + m * 2048 + k * 1024); } while (0)
; #define PG8_LDB(dst, b, h) do { _Pragma("unroll") for (int n = 0; n < 2; ++n) _Pragma("unroll") for (int k = 0; k < 2; ++k) dst[n][k] = *(const LAS bf16x8*)(lds + PG8_SB(b, h) + boff + n * 2048 + k * 1024); } while (0)
; #define PG8_WAIT_V(n) asm volatile("s_waitcnt vmcnt(" #n ")" ::: "memory")
; #define PG8_BAR __builtin_amdgcn_s_barrier()
; template <class Epi, class Sched>
; DI void gemm_phase(LAS unsigned char* lds, const int wv, const int lda, const int ldb, const Sched& S, const Epi& E) {
;     ...
;         for (int t = 0; t < nt; t += 2) {
;             const bool last = (t == nt - 2);
;             const char* a1 = cA + (size_t)(t + 1) * kstep;
;             const char* a2 = last ? nA : cA + (size_t)(t + 2) * kstep; const char* b2 = last ? nB : cB + (size_t)(t + 2) * kstep;
;             const char* a3 = a2 + kstep; const char* b3 = b2 + kstep;
;             PG8_LDB(B0, 0, 0); PG8_LDB(B1, 0, 1); PG8_SCHED; PG8_LDA(At, 0, 0); PG8_STAGE(PG8_SA(1, 1), a1 + hstepA, voffA);
;             PG8_WAIT_V(8); PG8_WAIT_L(0); PG8_BAR; PG8_MMA(0, 0, At, B0); PG8_MMA(0, 1, At, B1); PG8_BAR; PG8_SCHED;
;             PG8_LDA(At, 0, 1); PG8_STAGE(PG8_SB(0, 0), b2, voffB); PG8_STAGE(PG8_SB(0, 1), b2 + hstepB, voffB); PG8_STAGE(PG8_SA(0, 0), a2, voffA);
;             PG8_WAIT_V(8); PG8_WAIT_L(0); PG8_BAR; PG8_MMA(1, 0, At, B0); PG8_MMA(1, 1, At, B1); PG8_BAR; PG8_SCHED;
;             PG8_LDB(B0, 1, 0); PG8_LDB(B1, 1, 1); PG8_SCHED; PG8_LDA(At, 1, 0); PG8_STAGE(PG8_SA(0, 1), a2 + hstepA, voffA);
;             PG8_WAIT_V(8); PG8_WAIT_L(0); PG8_BAR; PG8_MMA(0, 0, At, B0); PG8_MMA(0, 1, At, B1); PG8_BAR; PG8_SCHED;
;             PG8_LDA(At, 1, 1); PG8_STAGE(PG8_SB(1, 0), b3, voffB); PG8_STAGE(PG8_SB(1, 1), b3 + hstepB, voffB); PG8_STAGE(PG8_SA(1, 0), a3, voffA);
;             PG8_WAIT_V(8); PG8_WAIT_L(0); PG8_BAR; PG8_MMA(1, 0, At, B0); PG8_MMA(1, 1, At, B1); PG8_BAR; PG8_SCHED;
	ds_read_b128 v[160:163], v206 offset:49152
	ds_read_b128 v[164:167], v206 offset:50176
	ds_read_b128 v[178:181], v206 offset:51200
	ds_read_b128 v[188:191], v206 offset:52224
	ds_read_b128 v[196:199], v206 offset:53248
	ds_read_b128 v[200:203], v206 offset:54272
	ds_read_b128 v[208:211], v206 offset:55296
	ds_read_b128 v[212:215], v206 offset:56320
	global_load_lds_dwordx4 v[182:183], off
	s_add_i32 m0, s22, 0x2000
	s_add_u32 s22, s26, 0x30080
	v_lshl_add_u64 v[182:183], v[216:217], 0, s[28:29]
	s_addc_u32 s23, s27, 0
	s_add_i32 s26, s51, s36
	global_load_lds_dwordx4 v[182:183], off
	s_mov_b32 m0, s26
	v_lshl_add_u64 v[182:183], s[22:23], 0, v[184:185]
	global_load_lds_dwordx4 v[182:183], off
	s_add_i32 m0, s26, 0x2000
	v_lshl_add_u64 v[182:183], s[22:23], 0, v[168:169]
	global_load_lds_dwordx4 v[182:183], off
	s_mov_b32 m0, s20
	v_lshl_add_u64 v[182:183], v[218:219], 0, s[28:29]
	global_load_lds_dwordx4 v[182:183], off
	s_mov_b32 m0, s42
	v_lshl_add_u64 v[182:183], v[220:221], 0, s[28:29]
	global_load_lds_dwordx4 v[182:183], off
	s_waitcnt vmcnt(8) lgkmcnt(0)
	s_barrier
	v_mfma_f32_16x16x32_bf16 v[60:63], v[64:67], v[160:163], v[60:63]
	v_mfma_f32_16x16x32_bf16 v[56:59], v[104:107], v[160:163], v[56:59]
	v_mfma_f32_16x16x32_bf16 v[52:55], v[64:67], v[178:181], v[52:55]
	v_mfma_f32_16x16x32_bf16 v[48:51], v[104:107], v[178:181], v[48:51]
	v_mfma_f32_16x16x32_bf16 v[44:47], v[64:67], v[196:199], v[44:47]
	v_mfma_f32_16x16x32_bf16 v[40:43], v[104:107], v[196:199], v[40:43]
	v_mfma_f32_16x16x32_bf16 v[36:39], v[64:67], v[208:211], v[36:39]
	v_mfma_f32_16x16x32_bf16 v[32:35], v[104:107], v[208:211], v[32:35]
	v_mfma_f32_16x16x32_bf16 v[60:63], v[68:71], v[164:167], v[60:63]
	v_mfma_f32_16x16x32_bf16 v[56:59], v[108:111], v[164:167], v[56:59]
	v_mfma_f32_16x16x32_bf16 v[52:55], v[68:71], v[188:191], v[52:55]
	v_mfma_f32_16x16x32_bf16 v[48:51], v[108:111], v[188:191], v[48:51]
	v_mfma_f32_16x16x32_bf16 v[44:47], v[68:71], v[200:203], v[44:47]
	v_mfma_f32_16x16x32_bf16 v[40:43], v[108:111], v[200:203], v[40:43]
	v_mfma_f32_16x16x32_bf16 v[36:39], v[68:71], v[212:215], v[36:39]
	v_mfma_f32_16x16x32_bf16 v[32:35], v[108:111], v[212:215], v[32:35]
	v_mfma_f32_16x16x32_bf16 v[28:31], v[144:147], v[160:163], v[28:31]
	v_mfma_f32_16x16x32_bf16 v[24:27], v[152:155], v[160:163], v[24:27]
	v_mfma_f32_16x16x32_bf16 v[20:23], v[144:147], v[178:181], v[20:23]
	v_mfma_f32_16x16x32_bf16 v[16:19], v[152:155], v[178:181], v[16:19]
	v_mfma_f32_16x16x32_bf16 v[12:15], v[144:147], v[196:199], v[12:15]
	v_mfma_f32_16x16x32_bf16 v[8:11], v[152:155], v[196:199], v[8:11]
	v_mfma_f32_16x16x32_bf16 v[4:7], v[144:147], v[208:211], v[4:7]
	v_mfma_f32_16x16x32_bf16 v[0:3], v[152:155], v[208:211], v[0:3]
	v_mfma_f32_16x16x32_bf16 v[28:31], v[148:151], v[164:167], v[28:31]
	v_mfma_f32_16x16x32_bf16 v[24:27], v[156:159], v[164:167], v[24:27]
	v_mfma_f32_16x16x32_bf16 v[20:23], v[148:151], v[188:191], v[20:23]
	v_mfma_f32_16x16x32_bf16 v[16:19], v[156:159], v[188:191], v[16:19]
	v_mfma_f32_16x16x32_bf16 v[12:15], v[148:151], v[200:203], v[12:15]
	v_mfma_f32_16x16x32_bf16 v[8:11], v[156:159], v[200:203], v[8:11]
	v_mfma_f32_16x16x32_bf16 v[4:7], v[148:151], v[212:215], v[4:7]
	v_mfma_f32_16x16x32_bf16 v[0:3], v[156:159], v[212:215], v[0:3]
	s_add_i32 s49, s49, 2
	s_add_u32 s0, s0, 0x100
	s_addc_u32 s1, s1, 0
	s_barrier
	s_mov_b64 s[22:23], s[24:25]
.LBB0_1099:
	s_add_u32 s24, s22, 0x100
	s_addc_u32 s25, s23, 0
	s_add_i32 s50, 0, 0x10000
	s_cmp_eq_u32 s49, 8
	s_cselect_b32 s31, s7, s25
	s_cselect_b32 s30, s6, s24
	s_cselect_b32 s27, s19, s1
	s_cselect_b32 s26, s18, s0
	s_add_i32 s51, 0, 0x14000
	v_add_u32_e32 v108, s50, v204
	v_add_u32_e32 v156, s51, v204
	ds_read_b128 v[64:67], v108
	ds_read_b128 v[68:71], v108 offset:1024
	ds_read_b128 v[104:107], v108 offset:2048
	ds_read_b128 v[108:111], v108 offset:3072
	ds_read_b128 v[144:147], v156
	ds_read_b128 v[148:151], v156 offset:1024
	ds_read_b128 v[152:155], v156 offset:2048
	ds_read_b128 v[156:159], v156 offset:3072
	v_lshl_add_u64 v[182:183], s[22:23], 0, v[174:175]
	s_add_i32 m0, s38, 0xc000
	ds_read_b128 v[160:163], v206
	ds_read_b128 v[164:167], v206 offset:1024
	ds_read_b128 v[178:181], v206 offset:2048
	ds_read_b128 v[188:191], v206 offset:3072
	ds_read_b128 v[196:199], v206 offset:4096
	ds_read_b128 v[200:203], v206 offset:5120
	ds_read_b128 v[208:211], v206 offset:6144
	ds_read_b128 v[212:215], v206 offset:7168
	global_load_lds_dwordx4 v[182:183], off
	s_add_i32 m0, s38, 0xe000
	v_lshl_add_u64 v[182:183], s[22:23], 0, v[176:177]
	global_load_lds_dwordx4 v[182:183], off
	s_waitcnt vmcnt(8) lgkmcnt(0)
	s_barrier
; #define PG8_STAGE(bufoff, gbase, voff) do { _Pragma("unroll") for (int _i = 0; _i < 2; ++_i) \
;         __builtin_amdgcn_global_load_lds((const unsigned*)((const char*)(gbase) + (voff)[_i]), (LAS unsigned*)(lds + (bufoff) + ldsw + _i * 8192), 16, 0, 0); } while (0)
; #define PG8_LDA(dst, b, h) do { _Pragma("unroll") for (int m = 0; m < 4; ++m) _Pragma("unroll") for (int k = 0; k < 2; ++k) dst[m][k] = *(const LAS bf16x8*)(lds + PG8_SA(b, h) + aoff + m * 2048 + k * 1024); } while (0)
; #define PG8_MMA(ai, bj, At, Bt) do { __builtin_amdgcn_s_setprio(1); _Pragma("unroll") for (int m = 0; m < 4; ++m) _Pragma("unroll") for (int n = 0; n < 2; ++n) _Pragma("unroll") for (int k = 0; k < 2; ++k) \
;         acc[ai][bj][m][n] = __builtin_amdgcn_mfma_f32_16x16x32_bf16(Bt[n][k], At[m][k], acc[ai][bj][m][n], 0, 0, 0); __builtin_amdgcn_s_setprio(0); } while (0)
; #define PG8_WAIT_V(n) asm volatile("s_waitcnt vmcnt(" #n ")" ::: "memory")
; #define PG8_WAIT_L(n) asm volatile("s_waitcnt lgkmcnt(" #n ")" ::: "memory")
; #define PG8_BAR __builtin_amdgcn_s_barrier()
; #define PG8_SCHED __builtin_amdgcn_sched_barrier(0)
; template <class Epi, class Sched>
; DI void gemm_phase(LAS unsigned char* lds, const int wv, const int lda, const int ldb, const Sched& S, const Epi& E) {
;     ...
;             PG8_WAIT_V(8); PG8_WAIT_L(0); PG8_BAR; PG8_MMA(0, 0, At, B0); PG8_MMA(0, 1, At, B1); PG8_BAR; PG8_SCHED;
;             PG8_LDA(At, 0, 1); PG8_STAGE(PG8_SB(0, 0), b2, voffB); PG8_STAGE(PG8_SB(0, 1), b2 + hstepB, voffB); PG8_STAGE(PG8_SA(0, 0), a2, voffA);
;             PG8_WAIT_V(8); PG8_WAIT_L(0); PG8_BAR; PG8_MMA(1, 0, At, B0); PG8_MMA(1, 1, At, B1); PG8_BAR; PG8_SCHED;
	v_mfma_f32_16x16x32_bf16 v[140:143], v[64:67], v[160:163], v[140:143]
	v_mfma_f32_16x16x32_bf16 v[136:139], v[104:107], v[160:163], v[136:139]
	v_mfma_f32_16x16x32_bf16 v[132:135], v[64:67], v[178:181], v[132:135]
	v_mfma_f32_16x16x32_bf16 v[128:131], v[104:107], v[178:181], v[128:131]
	v_mfma_f32_16x16x32_bf16 v[124:127], v[64:67], v[196:199], v[124:127]
	v_mfma_f32_16x16x32_bf16 v[120:123], v[104:107], v[196:199], v[120:123]
	v_mfma_f32_16x16x32_bf16 v[116:119], v[64:67], v[208:211], v[116:119]
	v_mfma_f32_16x16x32_bf16 v[112:115], v[104:107], v[208:211], v[112:115]
	v_mfma_f32_16x16x32_bf16 v[140:143], v[68:71], v[164:167], v[140:143]
	v_mfma_f32_16x16x32_bf16 v[136:139], v[108:111], v[164:167], v[136:139]
	v_mfma_f32_16x16x32_bf16 v[132:135], v[68:71], v[188:191], v[132:135]
	v_mfma_f32_16x16x32_bf16 v[128:131], v[108:111], v[188:191], v[128:131]
	v_mfma_f32_16x16x32_bf16 v[124:127], v[68:71], v[200:203], v[124:127]
	v_mfma_f32_16x16x32_bf16 v[120:123], v[108:111], v[200:203], v[120:123]
	v_mfma_f32_16x16x32_bf16 v[116:119], v[68:71], v[212:215], v[116:119]
	v_mfma_f32_16x16x32_bf16 v[112:115], v[108:111], v[212:215], v[112:115]
	v_mfma_f32_16x16x32_bf16 v[100:103], v[144:147], v[160:163], v[100:103]
	v_mfma_f32_16x16x32_bf16 v[96:99], v[152:155], v[160:163], v[96:99]
	v_mfma_f32_16x16x32_bf16 v[92:95], v[144:147], v[178:181], v[92:95]
	v_mfma_f32_16x16x32_bf16 v[88:91], v[152:155], v[178:181], v[88:91]
	v_mfma_f32_16x16x32_bf16 v[84:87], v[144:147], v[196:199], v[84:87]
	v_mfma_f32_16x16x32_bf16 v[80:83], v[152:155], v[196:199], v[80:83]
	v_mfma_f32_16x16x32_bf16 v[76:79], v[144:147], v[208:211], v[76:79]
	v_mfma_f32_16x16x32_bf16 v[72:75], v[152:155], v[208:211], v[72:75]
	v_mfma_f32_16x16x32_bf16 v[100:103], v[148:151], v[164:167], v[100:103]
	v_mfma_f32_16x16x32_bf16 v[96:99], v[156:159], v[164:167], v[96:99]
	v_mfma_f32_16x16x32_bf16 v[92:95], v[148:151], v[188:191], v[92:95]
	v_mfma_f32_16x16x32_bf16 v[88:91], v[156:159], v[188:191], v[88:91]
	v_mfma_f32_16x16x32_bf16 v[84:87], v[148:151], v[200:203], v[84:87]
	v_mfma_f32_16x16x32_bf16 v[80:83], v[156:159], v[200:203], v[80:83]
	v_mfma_f32_16x16x32_bf16 v[76:79], v[148:151], v[212:215], v[76:79]
	v_mfma_f32_16x16x32_bf16 v[72:75], v[156:159], v[212:215], v[72:75]
	s_add_i32 s22, s50, s36
	v_lshl_add_u64 v[182:183], s[26:27], 0, v[184:185]
	s_mov_b32 m0, s22
	s_barrier
	ds_read_b128 v[160:163], v206 offset:16384
	ds_read_b128 v[164:167], v206 offset:17408
	ds_read_b128 v[178:181], v206 offset:18432
	ds_read_b128 v[188:191], v206 offset:19456
	ds_read_b128 v[196:199], v206 offset:20480
	ds_read_b128 v[200:203], v206 offset:21504
	ds_read_b128 v[208:211], v206 offset:22528
	ds_read_b128 v[212:215], v206 offset:23552
	global_load_lds_dwordx4 v[182:183], off
	s_add_i32 m0, s22, 0x2000
	s_add_u32 s22, s26, 0x30000
	v_lshl_add_u64 v[216:217], s[26:27], 0, v[168:169]
	s_addc_u32 s23, s27, 0
	s_add_i32 s50, s51, s36
	global_load_lds_dwordx4 v[216:217], off
	v_lshl_add_u64 v[218:219], s[22:23], 0, v[184:185]
	s_mov_b32 m0, s50
	v_lshl_add_u64 v[220:221], s[30:31], 0, v[170:171]
	global_load_lds_dwordx4 v[218:219], off
	s_add_i32 m0, s50, 0x2000
	v_lshl_add_u64 v[218:219], s[22:23], 0, v[168:169]
	global_load_lds_dwordx4 v[218:219], off
	s_mov_b32 m0, s38
	v_lshl_add_u64 v[218:219], s[30:31], 0, v[172:173]
	global_load_lds_dwordx4 v[218:219], off
	s_mov_b32 m0, s39
	s_nop 0
	global_load_lds_dwordx4 v[220:221], off
	s_waitcnt vmcnt(8) lgkmcnt(0)
	s_barrier
	v_mfma_f32_16x16x32_bf16 v[60:63], v[64:67], v[160:163], v[60:63]
	v_mfma_f32_16x16x32_bf16 v[56:59], v[104:107], v[160:163], v[56:59]
	v_mfma_f32_16x16x32_bf16 v[52:55], v[64:67], v[178:181], v[52:55]
	v_mfma_f32_16x16x32_bf16 v[48:51], v[104:107], v[178:181], v[48:51]
	v_mfma_f32_16x16x32_bf16 v[44:47], v[64:67], v[196:199], v[44:47]
	v_mfma_f32_16x16x32_bf16 v[40:43], v[104:107], v[196:199], v[40:43]
	v_mfma_f32_16x16x32_bf16 v[36:39], v[64:67], v[208:211], v[36:39]
	v_mfma_f32_16x16x32_bf16 v[32:35], v[104:107], v[208:211], v[32:35]
	v_mfma_f32_16x16x32_bf16 v[60:63], v[68:71], v[164:167], v[60:63]
	v_mfma_f32_16x16x32_bf16 v[56:59], v[108:111], v[164:167], v[56:59]
	v_mfma_f32_16x16x32_bf16 v[52:55], v[68:71], v[188:191], v[52:55]
	v_mfma_f32_16x16x32_bf16 v[48:51], v[108:111], v[188:191], v[48:51]
	v_mfma_f32_16x16x32_bf16 v[44:47], v[68:71], v[200:203], v[44:47]
	v_mfma_f32_16x16x32_bf16 v[40:43], v[108:111], v[200:203], v[40:43]
	v_mfma_f32_16x16x32_bf16 v[36:39], v[68:71], v[212:215], v[36:39]
	v_mfma_f32_16x16x32_bf16 v[32:35], v[108:111], v[212:215], v[32:35]
	v_mfma_f32_16x16x32_bf16 v[28:31], v[144:147], v[160:163], v[28:31]
	v_mfma_f32_16x16x32_bf16 v[24:27], v[152:155], v[160:163], v[24:27]
	v_mfma_f32_16x16x32_bf16 v[20:23], v[144:147], v[178:181], v[20:23]
	v_mfma_f32_16x16x32_bf16 v[16:19], v[152:155], v[178:181], v[16:19]
	v_mfma_f32_16x16x32_bf16 v[12:15], v[144:147], v[196:199], v[12:15]
	v_mfma_f32_16x16x32_bf16 v[8:11], v[152:155], v[196:199], v[8:11]
	v_mfma_f32_16x16x32_bf16 v[4:7], v[144:147], v[208:211], v[4:7]
	v_mfma_f32_16x16x32_bf16 v[0:3], v[152:155], v[208:211], v[0:3]
	v_mfma_f32_16x16x32_bf16 v[28:31], v[148:151], v[164:167], v[28:31]
	v_mfma_f32_16x16x32_bf16 v[24:27], v[156:159], v[164:167], v[24:27]
	v_mfma_f32_16x16x32_bf16 v[20:23], v[148:151], v[188:191], v[20:23]
	v_mfma_f32_16x16x32_bf16 v[16:19], v[156:159], v[188:191], v[16:19]
	v_mfma_f32_16x16x32_bf16 v[12:15], v[148:151], v[200:203], v[12:15]
	v_mfma_f32_16x16x32_bf16 v[8:11], v[156:159], v[200:203], v[8:11]
	v_mfma_f32_16x16x32_bf16 v[4:7], v[148:151], v[212:215], v[4:7]
	v_mfma_f32_16x16x32_bf16 v[0:3], v[156:159], v[212:215], v[0:3]
	s_add_i32 s50, 0, 0x18000
	s_add_i32 s51, 0, 0x1c000
	s_barrier
; #define PG8_STAGE(bufoff, gbase, voff) do { _Pragma("unroll") for (int _i = 0; _i < 2; ++_i) \
;         __builtin_amdgcn_global_load_lds((const unsigned*)((const char*)(gbase) + (voff)[_i]), (LAS unsigned*)(lds + (bufoff) + ldsw + _i * 8192), 16, 0, 0); } while (0)
; #define PG8_LDA(dst, b, h) do { _Pragma("unroll") for (int m = 0; m < 4; ++m) _Pragma("unroll") for (int k = 0; k < 2; ++k) dst[m][k] = *(const LAS bf16x8*)(lds + PG8_SA(b, h) + aoff + m * 2048 + k * 1024); } while (0)
; #define PG8_LDB(dst, b, h) do { _Pragma("unroll") for (int n = 0; n < 2; ++n) _Pragma("unroll") for (int k = 0; k < 2; ++k) dst[n][k] = *(const LAS bf16x8*)(lds + PG8_SB(b, h) + boff + n * 2048 + k * 1024); } while (0)
; #define PG8_MMA(ai, bj, At, Bt) do { __builtin_amdgcn_s_setprio(1); _Pragma("unroll") for (int m = 0; m < 4; ++m) _Pragma("unroll") for (int n = 0; n < 2; ++n) _Pragma("unroll") for (int k = 0; k < 2; ++k) \
;         acc[ai][bj][m][n] = __builtin_amdgcn_mfma_f32_16x16x32_bf16(Bt[n][k], At[m][k], acc[ai][bj][m][n], 0, 0, 0); __builtin_amdgcn_s_setprio(0); } while (0)
; #define PG8_WAIT_V(n) asm volatile("s_waitcnt vmcnt(" #n ")" ::: "memory")
; #define PG8_WAIT_L(n) asm volatile("s_waitcnt lgkmcnt(" #n ")" ::: "memory")
; #define PG8_BAR __builtin_amdgcn_s_barrier()
; #define PG8_SCHED __builtin_amdgcn_sched_barrier(0)
; template <class Epi, class Sched>
; DI void gemm_phase(LAS unsigned char* lds, const int wv, const int lda, const int ldb, const Sched& S, const Epi& E) {
;     ...
;             PG8_LDB(B0, 1, 0); PG8_LDB(B1, 1, 1); PG8_SCHED; PG8_LDA(At, 1, 0); PG8_STAGE(PG8_SA(0, 1), a2 + hstepA, voffA);
;             PG8_WAIT_V(8); PG8_WAIT_L(0); PG8_BAR; PG8_MMA(0, 0, At, B0); PG8_MMA(0, 1, At, B1); PG8_BAR; PG8_SCHED;
;             PG8_LDA(At, 1, 1); PG8_STAGE(PG8_SB(1, 0), b3, voffB); PG8_STAGE(PG8_SB(1, 1), b3 + hstepB, voffB); PG8_STAGE(PG8_SA(1, 0), a3, voffA);
;             PG8_WAIT_V(8); PG8_WAIT_L(0); PG8_BAR; PG8_MMA(1, 0, At, B0); PG8_MMA(1, 1, At, B1); PG8_BAR; PG8_SCHED;
;         }
	v_add_u32_e32 v108, s50, v204
	v_add_u32_e32 v156, s51, v204
	ds_read_b128 v[64:67], v108
	ds_read_b128 v[68:71], v108 offset:1024
	ds_read_b128 v[104:107], v108 offset:2048
	ds_read_b128 v[108:111], v108 offset:3072
	ds_read_b128 v[144:147], v156
	ds_read_b128 v[148:151], v156 offset:1024
	ds_read_b128 v[152:155], v156 offset:2048
	ds_read_b128 v[156:159], v156 offset:3072
	s_add_u32 s22, s30, 0x30000
	s_addc_u32 s23, s31, 0
	s_mov_b32 m0, s40
	v_lshl_add_u64 v[222:223], s[22:23], 0, v[172:173]
	ds_read_b128 v[160:163], v206 offset:32768
	ds_read_b128 v[164:167], v206 offset:33792
	ds_read_b128 v[178:181], v206 offset:34816
	ds_read_b128 v[188:191], v206 offset:35840
	ds_read_b128 v[196:199], v206 offset:36864
	ds_read_b128 v[200:203], v206 offset:37888
	ds_read_b128 v[208:211], v206 offset:38912
	ds_read_b128 v[212:215], v206 offset:39936
	global_load_lds_dwordx4 v[222:223], off
	s_mov_b32 m0, s41
	v_lshl_add_u64 v[222:223], s[22:23], 0, v[170:171]
	global_load_lds_dwordx4 v[222:223], off
	s_waitcnt vmcnt(8) lgkmcnt(0)
	s_barrier
	v_mfma_f32_16x16x32_bf16 v[140:143], v[64:67], v[160:163], v[140:143]
	v_mfma_f32_16x16x32_bf16 v[136:139], v[104:107], v[160:163], v[136:139]
	v_mfma_f32_16x16x32_bf16 v[132:135], v[64:67], v[178:181], v[132:135]
	v_mfma_f32_16x16x32_bf16 v[128:131], v[104:107], v[178:181], v[128:131]
	v_mfma_f32_16x16x32_bf16 v[124:127], v[64:67], v[196:199], v[124:127]
	v_mfma_f32_16x16x32_bf16 v[120:123], v[104:107], v[196:199], v[120:123]
	v_mfma_f32_16x16x32_bf16 v[116:119], v[64:67], v[208:211], v[116:119]
	v_mfma_f32_16x16x32_bf16 v[112:115], v[104:107], v[208:211], v[112:115]
	v_mfma_f32_16x16x32_bf16 v[140:143], v[68:71], v[164:167], v[140:143]
	v_mfma_f32_16x16x32_bf16 v[136:139], v[108:111], v[164:167], v[136:139]
	v_mfma_f32_16x16x32_bf16 v[132:135], v[68:71], v[188:191], v[132:135]
	v_mfma_f32_16x16x32_bf16 v[128:131], v[108:111], v[188:191], v[128:131]
	v_mfma_f32_16x16x32_bf16 v[124:127], v[68:71], v[200:203], v[124:127]
	v_mfma_f32_16x16x32_bf16 v[120:123], v[108:111], v[200:203], v[120:123]
	v_mfma_f32_16x16x32_bf16 v[116:119], v[68:71], v[212:215], v[116:119]
	v_mfma_f32_16x16x32_bf16 v[112:115], v[108:111], v[212:215], v[112:115]
	v_mfma_f32_16x16x32_bf16 v[100:103], v[144:147], v[160:163], v[100:103]
	v_mfma_f32_16x16x32_bf16 v[96:99], v[152:155], v[160:163], v[96:99]
	v_mfma_f32_16x16x32_bf16 v[92:95], v[144:147], v[178:181], v[92:95]
	v_mfma_f32_16x16x32_bf16 v[88:91], v[152:155], v[178:181], v[88:91]
	v_mfma_f32_16x16x32_bf16 v[84:87], v[144:147], v[196:199], v[84:87]
	v_mfma_f32_16x16x32_bf16 v[80:83], v[152:155], v[196:199], v[80:83]
	v_mfma_f32_16x16x32_bf16 v[76:79], v[144:147], v[208:211], v[76:79]
	v_mfma_f32_16x16x32_bf16 v[72:75], v[152:155], v[208:211], v[72:75]
	v_mfma_f32_16x16x32_bf16 v[100:103], v[148:151], v[164:167], v[100:103]
	v_mfma_f32_16x16x32_bf16 v[96:99], v[156:159], v[164:167], v[96:99]
	v_mfma_f32_16x16x32_bf16 v[92:95], v[148:151], v[188:191], v[92:95]
	v_mfma_f32_16x16x32_bf16 v[88:91], v[156:159], v[188:191], v[88:91]
	v_mfma_f32_16x16x32_bf16 v[84:87], v[148:151], v[200:203], v[84:87]
	v_mfma_f32_16x16x32_bf16 v[80:83], v[156:159], v[200:203], v[80:83]
	v_mfma_f32_16x16x32_bf16 v[76:79], v[148:151], v[212:215], v[76:79]
	v_mfma_f32_16x16x32_bf16 v[72:75], v[156:159], v[212:215], v[72:75]
	s_add_i32 s22, s50, s36
	v_lshl_add_u64 v[182:183], v[182:183], 0, s[28:29]
	s_mov_b32 m0, s22
	s_barrier
	ds_read_b128 v[160:163], v206 offset:49152
	ds_read_b128 v[164:167], v206 offset:50176
	ds_read_b128 v[178:181], v206 offset:51200
	ds_read_b128 v[188:191], v206 offset:52224
	ds_read_b128 v[196:199], v206 offset:53248
	ds_read_b128 v[200:203], v206 offset:54272
	ds_read_b128 v[208:211], v206 offset:55296
	ds_read_b128 v[212:215], v206 offset:56320
	global_load_lds_dwordx4 v[182:183], off
	s_add_i32 m0, s22, 0x2000
	s_add_u32 s22, s26, 0x30080
	v_lshl_add_u64 v[182:183], v[216:217], 0, s[28:29]
	s_addc_u32 s23, s27, 0
	s_add_i32 s26, s51, s36
	global_load_lds_dwordx4 v[182:183], off
	s_mov_b32 m0, s26
	v_lshl_add_u64 v[182:183], s[22:23], 0, v[184:185]
	global_load_lds_dwordx4 v[182:183], off
	s_add_i32 m0, s26, 0x2000
	v_lshl_add_u64 v[182:183], s[22:23], 0, v[168:169]
	global_load_lds_dwordx4 v[182:183], off
	s_mov_b32 m0, s20
	v_lshl_add_u64 v[182:183], v[218:219], 0, s[28:29]
	global_load_lds_dwordx4 v[182:183], off
	s_mov_b32 m0, s42
	v_lshl_add_u64 v[182:183], v[220:221], 0, s[28:29]
	global_load_lds_dwordx4 v[182:183], off
	s_waitcnt vmcnt(8) lgkmcnt(0)
	s_barrier
	v_mfma_f32_16x16x32_bf16 v[60:63], v[64:67], v[160:163], v[60:63]
	v_mfma_f32_16x16x32_bf16 v[56:59], v[104:107], v[160:163], v[56:59]
	v_mfma_f32_16x16x32_bf16 v[52:55], v[64:67], v[178:181], v[52:55]
	v_mfma_f32_16x16x32_bf16 v[48:51], v[104:107], v[178:181], v[48:51]
	v_mfma_f32_16x16x32_bf16 v[44:47], v[64:67], v[196:199], v[44:47]
	v_mfma_f32_16x16x32_bf16 v[40:43], v[104:107], v[196:199], v[40:43]
	v_mfma_f32_16x16x32_bf16 v[36:39], v[64:67], v[208:211], v[36:39]
	v_mfma_f32_16x16x32_bf16 v[32:35], v[104:107], v[208:211], v[32:35]
	v_mfma_f32_16x16x32_bf16 v[60:63], v[68:71], v[164:167], v[60:63]
	v_mfma_f32_16x16x32_bf16 v[56:59], v[108:111], v[164:167], v[56:59]
	v_mfma_f32_16x16x32_bf16 v[52:55], v[68:71], v[188:191], v[52:55]
	v_mfma_f32_16x16x32_bf16 v[48:51], v[108:111], v[188:191], v[48:51]
	v_mfma_f32_16x16x32_bf16 v[44:47], v[68:71], v[200:203], v[44:47]
	v_mfma_f32_16x16x32_bf16 v[40:43], v[108:111], v[200:203], v[40:43]
	v_mfma_f32_16x16x32_bf16 v[36:39], v[68:71], v[212:215], v[36:39]
	v_mfma_f32_16x16x32_bf16 v[32:35], v[108:111], v[212:215], v[32:35]
	v_mfma_f32_16x16x32_bf16 v[28:31], v[144:147], v[160:163], v[28:31]
	v_mfma_f32_16x16x32_bf16 v[24:27], v[152:155], v[160:163], v[24:27]
	v_mfma_f32_16x16x32_bf16 v[20:23], v[144:147], v[178:181], v[20:23]
	v_mfma_f32_16x16x32_bf16 v[16:19], v[152:155], v[178:181], v[16:19]
	v_mfma_f32_16x16x32_bf16 v[12:15], v[144:147], v[196:199], v[12:15]
	v_mfma_f32_16x16x32_bf16 v[8:11], v[152:155], v[196:199], v[8:11]
	v_mfma_f32_16x16x32_bf16 v[4:7], v[144:147], v[208:211], v[4:7]
	v_mfma_f32_16x16x32_bf16 v[0:3], v[152:155], v[208:211], v[0:3]
	v_mfma_f32_16x16x32_bf16 v[28:31], v[148:151], v[164:167], v[28:31]
	v_mfma_f32_16x16x32_bf16 v[24:27], v[156:159], v[164:167], v[24:27]
	v_mfma_f32_16x16x32_bf16 v[20:23], v[148:151], v[188:191], v[20:23]
	v_mfma_f32_16x16x32_bf16 v[16:19], v[156:159], v[188:191], v[16:19]
	v_mfma_f32_16x16x32_bf16 v[12:15], v[148:151], v[200:203], v[12:15]
	v_mfma_f32_16x16x32_bf16 v[8:11], v[156:159], v[200:203], v[8:11]
	v_mfma_f32_16x16x32_bf16 v[4:7], v[148:151], v[212:215], v[4:7]
	v_mfma_f32_16x16x32_bf16 v[0:3], v[156:159], v[212:215], v[0:3]
	s_add_i32 s49, s49, 2
	s_add_u32 s0, s0, 0x100
	s_addc_u32 s1, s1, 0
	s_cmp_gt_u32 s49, 9
	s_barrier
	s_mov_b64 s[22:23], s[24:25]
	s_cbranch_scc0 .LBB0_1099
	s_and_b64 vcc, exec, s[14:15]
	s_cbranch_vccz .LBB0_1102
	s_barrier

; #define PG8_STAGE(bufoff, gbase, voff) do { _Pragma("unroll") for (int _i = 0; _i < 2; ++_i) \
;         __builtin_amdgcn_global_load_lds((const unsigned*)((const char*)(gbase) + (voff)[_i]), (LAS unsigned*)(lds + (bufoff) + ldsw + _i * 8192), 16, 0, 0); } while (0)
; #define PG8_LDA(dst, b, h) do { _Pragma("unroll") for (int m = 0; m < 4; ++m) _Pragma("unroll") for (int k = 0; k < 2; ++k) dst[m][k] = *(const LAS bf16x8*)(lds + PG8_SA(b, h) + aoff + m * 2048 + k * 1024); } while (0)
; #define PG8_LDB(dst, b, h) do { _Pragma("unroll") for (int n = 0; n < 2; ++n) _Pragma("unroll") for (int k = 0; k < 2; ++k) dst[n][k] = *(const LAS bf16x8*)(lds + PG8_SB(b, h) + boff + n * 2048 + k * 1024); } while (0)
; #define PG8_MMA(ai, bj, At, Bt) do { __builtin_amdgcn_s_setprio(1); _Pragma("unroll") for (int m = 0; m < 4; ++m) _Pragma("unroll") for (int n = 0; n < 2; ++n) _Pragma("unroll") for (int k = 0; k < 2; ++k) \
;         acc[ai][bj][m][n] = __builtin_amdgcn_mfma_f32_16x16x32_bf16(Bt[n][k], At[m][k], acc[ai][bj][m][n], 0, 0, 0); __builtin_amdgcn_s_setprio(0); } while (0)
; #define PG8_WAIT_V(n) asm volatile("s_waitcnt vmcnt(" #n ")" ::: "memory")
; #define PG8_WAIT_L(n) asm volatile("s_waitcnt lgkmcnt(" #n ")" ::: "memory")
; #define PG8_BAR __builtin_amdgcn_s_barrier()
; #define PG8_SCHED __builtin_amdgcn_sched_barrier(0)
; template <class Epi, class Sched>
; DI void gemm_phase(LAS unsigned char* lds, const int wv, const int lda, const int ldb, const Sched& S, const Epi& E) {
;     ...
;         for (int t = 0; t < nt; t += 2) {
;             const bool last = (t == nt - 2);
;             const char* a1 = cA + (size_t)(t + 1) * kstep;
;             const char* a2 = last ? nA : cA + (size_t)(t + 2) * kstep; const char* b2 = last ? nB : cB + (size_t)(t + 2) * kstep;
;             const char* a3 = a2 + kstep; const char* b3 = b2 + kstep;
;             PG8_LDB(B0, 0, 0); PG8_LDB(B1, 0, 1); PG8_SCHED; PG8_LDA(At, 0, 0); PG8_STAGE(PG8_SA(1, 1), a1 + hstepA, voffA);
;             PG8_WAIT_V(8); PG8_WAIT_L(0); PG8_BAR; PG8_MMA(0, 0, At, B0); PG8_MMA(0, 1, At, B1); PG8_BAR; PG8_SCHED;
;             PG8_LDA(At, 0, 1); PG8_STAGE(PG8_SB(0, 0), b2, voffB); PG8_STAGE(PG8_SB(0, 1), b2 + hstepB, voffB); PG8_STAGE(PG8_SA(0, 0), a2, voffA);
;             PG8_WAIT_V(8); PG8_WAIT_L(0); PG8_BAR; PG8_MMA(1, 0, At, B0); PG8_MMA(1, 1, At, B1); PG8_BAR; PG8_SCHED;
.LBB0_1185:
	s_add_i32 s31, s19, 2
	s_add_u32 s34, s6, 0xfff80080
	s_addc_u32 s35, s7, -1
	s_add_i32 s40, 0, 0x10000
	s_cmp_eq_u32 s0, s19
	s_cselect_b32 s37, s23, s35
	s_cselect_b32 s36, s22, s34
	s_cselect_b32 s35, s25, s15
	s_cselect_b32 s34, s24, s1
	s_add_i32 s19, 0, 0x14000
	v_add_u32_e32 v140, s40, v233
	v_add_u32_e32 v156, s19, v233
	ds_read_b128 v[128:131], v140
	ds_read_b128 v[132:135], v140 offset:1024
	ds_read_b128 v[136:139], v140 offset:2048
	ds_read_b128 v[140:143], v140 offset:3072
	ds_read_b128 v[144:147], v156
	ds_read_b128 v[148:151], v156 offset:1024
	ds_read_b128 v[152:155], v156 offset:2048
	ds_read_b128 v[156:159], v156 offset:3072
	v_lshl_add_u64 v[210:211], s[6:7], 0, v[206:207]
	s_add_i32 m0, s45, 0xc000
	ds_read_b128 v[160:163], v235
	ds_read_b128 v[164:167], v235 offset:1024
	ds_read_b128 v[168:171], v235 offset:2048
	ds_read_b128 v[172:175], v235 offset:3072
	ds_read_b128 v[176:179], v235 offset:4096
	ds_read_b128 v[180:183], v235 offset:5120
	ds_read_b128 v[188:191], v235 offset:6144
	ds_read_b128 v[196:199], v235 offset:7168
	global_load_lds_dwordx4 v[210:211], off
	s_add_i32 m0, s45, 0xe000
	v_lshl_add_u64 v[210:211], s[6:7], 0, v[208:209]
	global_load_lds_dwordx4 v[210:211], off
	s_waitcnt vmcnt(8) lgkmcnt(0)
	s_barrier
	v_mfma_f32_16x16x32_bf16 v[124:127], v[128:131], v[160:163], v[124:127]
	v_mfma_f32_16x16x32_bf16 v[120:123], v[136:139], v[160:163], v[120:123]
	v_mfma_f32_16x16x32_bf16 v[116:119], v[128:131], v[168:171], v[116:119]
	v_mfma_f32_16x16x32_bf16 v[112:115], v[136:139], v[168:171], v[112:115]
	v_mfma_f32_16x16x32_bf16 v[108:111], v[128:131], v[176:179], v[108:111]
	v_mfma_f32_16x16x32_bf16 v[104:107], v[136:139], v[176:179], v[104:107]
	v_mfma_f32_16x16x32_bf16 v[100:103], v[128:131], v[188:191], v[100:103]
	v_mfma_f32_16x16x32_bf16 v[96:99], v[136:139], v[188:191], v[96:99]
	v_mfma_f32_16x16x32_bf16 v[124:127], v[132:135], v[164:167], v[124:127]
	v_mfma_f32_16x16x32_bf16 v[120:123], v[140:143], v[164:167], v[120:123]
	v_mfma_f32_16x16x32_bf16 v[116:119], v[132:135], v[172:175], v[116:119]
	v_mfma_f32_16x16x32_bf16 v[112:115], v[140:143], v[172:175], v[112:115]
	v_mfma_f32_16x16x32_bf16 v[108:111], v[132:135], v[180:183], v[108:111]
	v_mfma_f32_16x16x32_bf16 v[104:107], v[140:143], v[180:183], v[104:107]
	v_mfma_f32_16x16x32_bf16 v[100:103], v[132:135], v[196:199], v[100:103]
	v_mfma_f32_16x16x32_bf16 v[96:99], v[140:143], v[196:199], v[96:99]
	v_mfma_f32_16x16x32_bf16 v[92:95], v[144:147], v[160:163], v[92:95]
	v_mfma_f32_16x16x32_bf16 v[88:91], v[152:155], v[160:163], v[88:91]
	v_mfma_f32_16x16x32_bf16 v[84:87], v[144:147], v[168:171], v[84:87]
	v_mfma_f32_16x16x32_bf16 v[80:83], v[152:155], v[168:171], v[80:83]
	v_mfma_f32_16x16x32_bf16 v[76:79], v[144:147], v[176:179], v[76:79]
	v_mfma_f32_16x16x32_bf16 v[72:75], v[152:155], v[176:179], v[72:75]
	v_mfma_f32_16x16x32_bf16 v[68:71], v[144:147], v[188:191], v[68:71]
	v_mfma_f32_16x16x32_bf16 v[64:67], v[152:155], v[188:191], v[64:67]
	v_mfma_f32_16x16x32_bf16 v[92:95], v[148:151], v[164:167], v[92:95]
	v_mfma_f32_16x16x32_bf16 v[88:91], v[156:159], v[164:167], v[88:91]
	v_mfma_f32_16x16x32_bf16 v[84:87], v[148:151], v[172:175], v[84:87]
	v_mfma_f32_16x16x32_bf16 v[80:83], v[156:159], v[172:175], v[80:83]
	v_mfma_f32_16x16x32_bf16 v[76:79], v[148:151], v[180:183], v[76:79]
	v_mfma_f32_16x16x32_bf16 v[72:75], v[156:159], v[180:183], v[72:75]
	v_mfma_f32_16x16x32_bf16 v[68:71], v[148:151], v[196:199], v[68:71]
	v_mfma_f32_16x16x32_bf16 v[64:67], v[156:159], v[196:199], v[64:67]
	s_add_i32 s40, s40, s44
	v_lshl_add_u64 v[210:211], s[34:35], 0, v[184:185]
	s_mov_b32 m0, s40
	s_barrier
	ds_read_b128 v[160:163], v235 offset:16384
	ds_read_b128 v[164:167], v235 offset:17408
	ds_read_b128 v[168:171], v235 offset:18432
	ds_read_b128 v[172:175], v235 offset:19456
	ds_read_b128 v[176:179], v235 offset:20480
	ds_read_b128 v[180:183], v235 offset:21504
	ds_read_b128 v[188:191], v235 offset:22528
	ds_read_b128 v[196:199], v235 offset:23552
	global_load_lds_dwordx4 v[210:211], off
	s_add_i32 m0, s40, 0x2000
	s_add_u32 s40, s34, 0x80000
	v_lshl_add_u64 v[212:213], s[34:35], 0, v[204:205]
	s_addc_u32 s41, s35, 0
	s_add_i32 s19, s19, s44
	global_load_lds_dwordx4 v[212:213], off
	v_lshl_add_u64 v[214:215], s[40:41], 0, v[184:185]
	s_mov_b32 m0, s19
	v_lshl_add_u64 v[216:217], s[36:37], 0, v[202:203]
	global_load_lds_dwordx4 v[214:215], off
	s_add_i32 m0, s19, 0x2000
	v_lshl_add_u64 v[214:215], s[40:41], 0, v[204:205]
	global_load_lds_dwordx4 v[214:215], off
	s_mov_b32 m0, s45
	v_lshl_add_u64 v[214:215], s[36:37], 0, v[200:201]
	global_load_lds_dwordx4 v[214:215], off
	s_mov_b32 m0, s46
	s_nop 0
	global_load_lds_dwordx4 v[216:217], off
	s_waitcnt vmcnt(8) lgkmcnt(0)
	s_barrier
; #define PG8_STAGE(bufoff, gbase, voff) do { _Pragma("unroll") for (int _i = 0; _i < 2; ++_i) \
;         __builtin_amdgcn_global_load_lds((const unsigned*)((const char*)(gbase) + (voff)[_i]), (LAS unsigned*)(lds + (bufoff) + ldsw + _i * 8192), 16, 0, 0); } while (0)
; #define PG8_LDA(dst, b, h) do { _Pragma("unroll") for (int m = 0; m < 4; ++m) _Pragma("unroll") for (int k = 0; k < 2; ++k) dst[m][k] = *(const LAS bf16x8*)(lds + PG8_SA(b, h) + aoff + m * 2048 + k * 1024); } while (0)
; #define PG8_LDB(dst, b, h) do { _Pragma("unroll") for (int n = 0; n < 2; ++n) _Pragma("unroll") for (int k = 0; k < 2; ++k) dst[n][k] = *(const LAS bf16x8*)(lds + PG8_SB(b, h) + boff + n * 2048 + k * 1024); } while (0)
; #define PG8_MMA(ai, bj, At, Bt) do { __builtin_amdgcn_s_setprio(1); _Pragma("unroll") for (int m = 0; m < 4; ++m) _Pragma("unroll") for (int n = 0; n < 2; ++n) _Pragma("unroll") for (int k = 0; k < 2; ++k) \
;         acc[ai][bj][m][n] = __builtin_amdgcn_mfma_f32_16x16x32_bf16(Bt[n][k], At[m][k], acc[ai][bj][m][n], 0, 0, 0); __builtin_amdgcn_s_setprio(0); } while (0)
; #define PG8_WAIT_V(n) asm volatile("s_waitcnt vmcnt(" #n ")" ::: "memory")
; #define PG8_WAIT_L(n) asm volatile("s_waitcnt lgkmcnt(" #n ")" ::: "memory")
; #define PG8_BAR __builtin_amdgcn_s_barrier()
; #define PG8_SCHED __builtin_amdgcn_sched_barrier(0)
; template <class Epi, class Sched>
; DI void gemm_phase(LAS unsigned char* lds, const int wv, const int lda, const int ldb, const Sched& S, const Epi& E) {
;     ...
;             PG8_WAIT_V(8); PG8_WAIT_L(0); PG8_BAR; PG8_MMA(1, 0, At, B0); PG8_MMA(1, 1, At, B1); PG8_BAR; PG8_SCHED;
;             PG8_LDB(B0, 1, 0); PG8_LDB(B1, 1, 1); PG8_SCHED; PG8_LDA(At, 1, 0); PG8_STAGE(PG8_SA(0, 1), a2 + hstepA, voffA);
;             PG8_WAIT_V(8); PG8_WAIT_L(0); PG8_BAR; PG8_MMA(0, 0, At, B0); PG8_MMA(0, 1, At, B1); PG8_BAR; PG8_SCHED;
;             PG8_LDA(At, 1, 1); PG8_STAGE(PG8_SB(1, 0), b3, voffB); PG8_STAGE(PG8_SB(1, 1), b3 + hstepB, voffB); PG8_STAGE(PG8_SA(1, 0), a3, voffA);
	v_mfma_f32_16x16x32_bf16 v[60:63], v[128:131], v[160:163], v[60:63]
	v_mfma_f32_16x16x32_bf16 v[56:59], v[136:139], v[160:163], v[56:59]
	v_mfma_f32_16x16x32_bf16 v[52:55], v[128:131], v[168:171], v[52:55]
	v_mfma_f32_16x16x32_bf16 v[48:51], v[136:139], v[168:171], v[48:51]
	v_mfma_f32_16x16x32_bf16 v[44:47], v[128:131], v[176:179], v[44:47]
	v_mfma_f32_16x16x32_bf16 v[40:43], v[136:139], v[176:179], v[40:43]
	v_mfma_f32_16x16x32_bf16 v[36:39], v[128:131], v[188:191], v[36:39]
	v_mfma_f32_16x16x32_bf16 v[32:35], v[136:139], v[188:191], v[32:35]
	v_mfma_f32_16x16x32_bf16 v[60:63], v[132:135], v[164:167], v[60:63]
	v_mfma_f32_16x16x32_bf16 v[56:59], v[140:143], v[164:167], v[56:59]
	v_mfma_f32_16x16x32_bf16 v[52:55], v[132:135], v[172:175], v[52:55]
	v_mfma_f32_16x16x32_bf16 v[48:51], v[140:143], v[172:175], v[48:51]
	v_mfma_f32_16x16x32_bf16 v[44:47], v[132:135], v[180:183], v[44:47]
	v_mfma_f32_16x16x32_bf16 v[40:43], v[140:143], v[180:183], v[40:43]
	v_mfma_f32_16x16x32_bf16 v[36:39], v[132:135], v[196:199], v[36:39]
	v_mfma_f32_16x16x32_bf16 v[32:35], v[140:143], v[196:199], v[32:35]
	v_mfma_f32_16x16x32_bf16 v[28:31], v[144:147], v[160:163], v[28:31]
	v_mfma_f32_16x16x32_bf16 v[24:27], v[152:155], v[160:163], v[24:27]
	v_mfma_f32_16x16x32_bf16 v[20:23], v[144:147], v[168:171], v[20:23]
	v_mfma_f32_16x16x32_bf16 v[16:19], v[152:155], v[168:171], v[16:19]
	v_mfma_f32_16x16x32_bf16 v[12:15], v[144:147], v[176:179], v[12:15]
	v_mfma_f32_16x16x32_bf16 v[8:11], v[152:155], v[176:179], v[8:11]
	v_mfma_f32_16x16x32_bf16 v[4:7], v[144:147], v[188:191], v[4:7]
	v_mfma_f32_16x16x32_bf16 v[0:3], v[152:155], v[188:191], v[0:3]
	v_mfma_f32_16x16x32_bf16 v[28:31], v[148:151], v[164:167], v[28:31]
	v_mfma_f32_16x16x32_bf16 v[24:27], v[156:159], v[164:167], v[24:27]
	v_mfma_f32_16x16x32_bf16 v[20:23], v[148:151], v[172:175], v[20:23]
	v_mfma_f32_16x16x32_bf16 v[16:19], v[156:159], v[172:175], v[16:19]
	v_mfma_f32_16x16x32_bf16 v[12:15], v[148:151], v[180:183], v[12:15]
	v_mfma_f32_16x16x32_bf16 v[8:11], v[156:159], v[180:183], v[8:11]
	v_mfma_f32_16x16x32_bf16 v[4:7], v[148:151], v[196:199], v[4:7]
	v_mfma_f32_16x16x32_bf16 v[0:3], v[156:159], v[196:199], v[0:3]
	s_add_i32 s19, 0, 0x18000
	s_add_i32 s40, 0, 0x1c000
	s_barrier
	v_add_u32_e32 v140, s19, v233
	v_add_u32_e32 v156, s40, v233
	ds_read_b128 v[128:131], v140
	ds_read_b128 v[132:135], v140 offset:1024
	ds_read_b128 v[136:139], v140 offset:2048
	ds_read_b128 v[140:143], v140 offset:3072
	ds_read_b128 v[144:147], v156
	ds_read_b128 v[148:151], v156 offset:1024
	ds_read_b128 v[152:155], v156 offset:2048
	ds_read_b128 v[156:159], v156 offset:3072
	s_add_u32 s36, s36, 0x80000
	s_addc_u32 s37, s37, 0
	s_mov_b32 m0, s47
	v_lshl_add_u64 v[218:219], s[36:37], 0, v[200:201]
	ds_read_b128 v[160:163], v235 offset:32768
	ds_read_b128 v[164:167], v235 offset:33792
	ds_read_b128 v[168:171], v235 offset:34816
	ds_read_b128 v[172:175], v235 offset:35840
	ds_read_b128 v[176:179], v235 offset:36864
	ds_read_b128 v[180:183], v235 offset:37888
	ds_read_b128 v[188:191], v235 offset:38912
	ds_read_b128 v[196:199], v235 offset:39936
	global_load_lds_dwordx4 v[218:219], off
	s_mov_b32 m0, s48
	v_lshl_add_u64 v[218:219], s[36:37], 0, v[202:203]
	global_load_lds_dwordx4 v[218:219], off
	s_waitcnt vmcnt(8) lgkmcnt(0)
	s_barrier
	v_mfma_f32_16x16x32_bf16 v[124:127], v[128:131], v[160:163], v[124:127]
	v_mfma_f32_16x16x32_bf16 v[120:123], v[136:139], v[160:163], v[120:123]
	v_mfma_f32_16x16x32_bf16 v[116:119], v[128:131], v[168:171], v[116:119]
	v_mfma_f32_16x16x32_bf16 v[112:115], v[136:139], v[168:171], v[112:115]
	v_mfma_f32_16x16x32_bf16 v[108:111], v[128:131], v[176:179], v[108:111]
	v_mfma_f32_16x16x32_bf16 v[104:107], v[136:139], v[176:179], v[104:107]
	v_mfma_f32_16x16x32_bf16 v[100:103], v[128:131], v[188:191], v[100:103]
	v_mfma_f32_16x16x32_bf16 v[96:99], v[136:139], v[188:191], v[96:99]
	v_mfma_f32_16x16x32_bf16 v[124:127], v[132:135], v[164:167], v[124:127]
	v_mfma_f32_16x16x32_bf16 v[120:123], v[140:143], v[164:167], v[120:123]
	v_mfma_f32_16x16x32_bf16 v[116:119], v[132:135], v[172:175], v[116:119]
	v_mfma_f32_16x16x32_bf16 v[112:115], v[140:143], v[172:175], v[112:115]
	v_mfma_f32_16x16x32_bf16 v[108:111], v[132:135], v[180:183], v[108:111]
	v_mfma_f32_16x16x32_bf16 v[104:107], v[140:143], v[180:183], v[104:107]
	v_mfma_f32_16x16x32_bf16 v[100:103], v[132:135], v[196:199], v[100:103]
	v_mfma_f32_16x16x32_bf16 v[96:99], v[140:143], v[196:199], v[96:99]
	v_mfma_f32_16x16x32_bf16 v[92:95], v[144:147], v[160:163], v[92:95]
	v_mfma_f32_16x16x32_bf16 v[88:91], v[152:155], v[160:163], v[88:91]
	v_mfma_f32_16x16x32_bf16 v[84:87], v[144:147], v[168:171], v[84:87]
	v_mfma_f32_16x16x32_bf16 v[80:83], v[152:155], v[168:171], v[80:83]
	v_mfma_f32_16x16x32_bf16 v[76:79], v[144:147], v[176:179], v[76:79]
	v_mfma_f32_16x16x32_bf16 v[72:75], v[152:155], v[176:179], v[72:75]
	v_mfma_f32_16x16x32_bf16 v[68:71], v[144:147], v[188:191], v[68:71]
	v_mfma_f32_16x16x32_bf16 v[64:67], v[152:155], v[188:191], v[64:67]
	v_mfma_f32_16x16x32_bf16 v[92:95], v[148:151], v[164:167], v[92:95]
	v_mfma_f32_16x16x32_bf16 v[88:91], v[156:159], v[164:167], v[88:91]
	v_mfma_f32_16x16x32_bf16 v[84:87], v[148:151], v[172:175], v[84:87]
	v_mfma_f32_16x16x32_bf16 v[80:83], v[156:159], v[172:175], v[80:83]
	v_mfma_f32_16x16x32_bf16 v[76:79], v[148:151], v[180:183], v[76:79]
	v_mfma_f32_16x16x32_bf16 v[72:75], v[156:159], v[180:183], v[72:75]
	v_mfma_f32_16x16x32_bf16 v[68:71], v[148:151], v[196:199], v[68:71]
	v_mfma_f32_16x16x32_bf16 v[64:67], v[156:159], v[196:199], v[64:67]
	s_add_i32 s19, s19, s44
	v_lshl_add_u64 v[210:211], v[210:211], 0, s[28:29]
	s_mov_b32 m0, s19
	s_barrier
; #define PG8_STAGE(bufoff, gbase, voff) do { _Pragma("unroll") for (int _i = 0; _i < 2; ++_i) \
;         __builtin_amdgcn_global_load_lds((const unsigned*)((const char*)(gbase) + (voff)[_i]), (LAS unsigned*)(lds + (bufoff) + ldsw + _i * 8192), 16, 0, 0); } while (0)
; #define PG8_LDA(dst, b, h) do { _Pragma("unroll") for (int m = 0; m < 4; ++m) _Pragma("unroll") for (int k = 0; k < 2; ++k) dst[m][k] = *(const LAS bf16x8*)(lds + PG8_SA(b, h) + aoff + m * 2048 + k * 1024); } while (0)
; #define PG8_MMA(ai, bj, At, Bt) do { __builtin_amdgcn_s_setprio(1); _Pragma("unroll") for (int m = 0; m < 4; ++m) _Pragma("unroll") for (int n = 0; n < 2; ++n) _Pragma("unroll") for (int k = 0; k < 2; ++k) \
;         acc[ai][bj][m][n] = __builtin_amdgcn_mfma_f32_16x16x32_bf16(Bt[n][k], At[m][k], acc[ai][bj][m][n], 0, 0, 0); __builtin_amdgcn_s_setprio(0); } while (0)
; #define PG8_WAIT_V(n) asm volatile("s_waitcnt vmcnt(" #n ")" ::: "memory")
; #define PG8_WAIT_L(n) asm volatile("s_waitcnt lgkmcnt(" #n ")" ::: "memory")
; #define PG8_BAR __builtin_amdgcn_s_barrier()
; #define PG8_SCHED __builtin_amdgcn_sched_barrier(0)
; template <class Epi, class Sched>
; DI void gemm_phase(LAS unsigned char* lds, const int wv, const int lda, const int ldb, const Sched& S, const Epi& E) {
;     ...
;             PG8_LDA(At, 1, 1); PG8_STAGE(PG8_SB(1, 0), b3, voffB); PG8_STAGE(PG8_SB(1, 1), b3 + hstepB, voffB); PG8_STAGE(PG8_SA(1, 0), a3, voffA);
;             PG8_WAIT_V(8); PG8_WAIT_L(0); PG8_BAR; PG8_MMA(1, 0, At, B0); PG8_MMA(1, 1, At, B1); PG8_BAR; PG8_SCHED;
;         }
	ds_read_b128 v[160:163], v235 offset:49152
	ds_read_b128 v[164:167], v235 offset:50176
	ds_read_b128 v[168:171], v235 offset:51200
	ds_read_b128 v[172:175], v235 offset:52224
	ds_read_b128 v[176:179], v235 offset:53248
	ds_read_b128 v[180:183], v235 offset:54272
	ds_read_b128 v[188:191], v235 offset:55296
	ds_read_b128 v[196:199], v235 offset:56320
	global_load_lds_dwordx4 v[210:211], off
	s_add_i32 m0, s19, 0x2000
	s_add_u32 s34, s34, 0x80080
	v_lshl_add_u64 v[210:211], v[212:213], 0, s[28:29]
	s_addc_u32 s35, s35, 0
	s_add_i32 s19, s40, s44
	global_load_lds_dwordx4 v[210:211], off
	s_mov_b32 m0, s19
	v_lshl_add_u64 v[210:211], s[34:35], 0, v[184:185]
	global_load_lds_dwordx4 v[210:211], off
	s_add_i32 m0, s19, 0x2000
	v_lshl_add_u64 v[210:211], s[34:35], 0, v[204:205]
	global_load_lds_dwordx4 v[210:211], off
	s_mov_b32 m0, s49
	v_lshl_add_u64 v[210:211], v[214:215], 0, s[28:29]
	global_load_lds_dwordx4 v[210:211], off
	s_mov_b32 m0, s50
	v_lshl_add_u64 v[210:211], v[216:217], 0, s[28:29]
	global_load_lds_dwordx4 v[210:211], off
	s_waitcnt vmcnt(8) lgkmcnt(0)
	s_barrier
	v_mfma_f32_16x16x32_bf16 v[60:63], v[128:131], v[160:163], v[60:63]
	v_mfma_f32_16x16x32_bf16 v[56:59], v[136:139], v[160:163], v[56:59]
	v_mfma_f32_16x16x32_bf16 v[52:55], v[128:131], v[168:171], v[52:55]
	v_mfma_f32_16x16x32_bf16 v[48:51], v[136:139], v[168:171], v[48:51]
	v_mfma_f32_16x16x32_bf16 v[44:47], v[128:131], v[176:179], v[44:47]
	v_mfma_f32_16x16x32_bf16 v[40:43], v[136:139], v[176:179], v[40:43]
	v_mfma_f32_16x16x32_bf16 v[36:39], v[128:131], v[188:191], v[36:39]
	v_mfma_f32_16x16x32_bf16 v[32:35], v[136:139], v[188:191], v[32:35]
	v_mfma_f32_16x16x32_bf16 v[60:63], v[132:135], v[164:167], v[60:63]
	v_mfma_f32_16x16x32_bf16 v[56:59], v[140:143], v[164:167], v[56:59]
	v_mfma_f32_16x16x32_bf16 v[52:55], v[132:135], v[172:175], v[52:55]
	v_mfma_f32_16x16x32_bf16 v[48:51], v[140:143], v[172:175], v[48:51]
	v_mfma_f32_16x16x32_bf16 v[44:47], v[132:135], v[180:183], v[44:47]
	v_mfma_f32_16x16x32_bf16 v[40:43], v[140:143], v[180:183], v[40:43]
	v_mfma_f32_16x16x32_bf16 v[36:39], v[132:135], v[196:199], v[36:39]
	v_mfma_f32_16x16x32_bf16 v[32:35], v[140:143], v[196:199], v[32:35]
	v_mfma_f32_16x16x32_bf16 v[28:31], v[144:147], v[160:163], v[28:31]
	v_mfma_f32_16x16x32_bf16 v[24:27], v[152:155], v[160:163], v[24:27]
	v_mfma_f32_16x16x32_bf16 v[20:23], v[144:147], v[168:171], v[20:23]
	v_mfma_f32_16x16x32_bf16 v[16:19], v[152:155], v[168:171], v[16:19]
	v_mfma_f32_16x16x32_bf16 v[12:15], v[144:147], v[176:179], v[12:15]
	v_mfma_f32_16x16x32_bf16 v[8:11], v[152:155], v[176:179], v[8:11]
	v_mfma_f32_16x16x32_bf16 v[4:7], v[144:147], v[188:191], v[4:7]
	v_mfma_f32_16x16x32_bf16 v[0:3], v[152:155], v[188:191], v[0:3]
	v_mfma_f32_16x16x32_bf16 v[28:31], v[148:151], v[164:167], v[28:31]
	v_mfma_f32_16x16x32_bf16 v[24:27], v[156:159], v[164:167], v[24:27]
	v_mfma_f32_16x16x32_bf16 v[20:23], v[148:151], v[172:175], v[20:23]
	v_mfma_f32_16x16x32_bf16 v[16:19], v[156:159], v[172:175], v[16:19]
	v_mfma_f32_16x16x32_bf16 v[12:15], v[148:151], v[180:183], v[12:15]
	v_mfma_f32_16x16x32_bf16 v[8:11], v[156:159], v[180:183], v[8:11]
	v_mfma_f32_16x16x32_bf16 v[4:7], v[148:151], v[196:199], v[4:7]
	v_mfma_f32_16x16x32_bf16 v[0:3], v[156:159], v[196:199], v[0:3]
	s_add_u32 s6, s6, 0x100
	s_addc_u32 s7, s7, 0
	s_add_u32 s1, s1, 0x100
	s_addc_u32 s15, s15, 0
	s_cmp_ge_u32 s31, s27
	s_barrier
	s_mov_b32 s19, s31
	s_cbranch_scc0 .LBB0_1185
	s_and_b64 vcc, exec, s[12:13]
	s_cbranch_vccz .LBB0_1188
	s_barrier

;     DI bool next(int i, Unit& u) const { const long L = (long)i * G + c; if (L >= T.nwg) return false; T.map((int)L, u.pm, u.pn); u.seg = 0; return true; }
;     DI bool next(int i, Unit& u) const { const int ti = i / 3; const long L = (long)ti * G + c; if (L >= T.nwg) return false; T.map((int)L, u.pm, u.pn); u.seg = i - 3 * ti; return true; }
;     DI const char* aptr(const Unit& u) const { return A + (size_t)u.pm * ta + (size_t)kofs(u.seg) * 2; }
;     DI const char* bptr(const Unit& u) const { return B + (size_t)u.pn * tb + (size_t)kofs(u.seg) * 2; }
; #define PG8_WAIT_V(n) asm volatile("s_waitcnt vmcnt(" #n ")" ::: "memory")
; #define PG8_BAR __builtin_amdgcn_s_barrier()
; template <class Epi, class Sched>
; DI void gemm_phase(LAS unsigned char* lds, const int wv, const int lda, const int ldb, const Sched& S, const Epi& E) {
;     ...
;         const bool has_next = S.next(ui + 1, nxt);
;         const char* nA = has_next ? S.aptr(nxt) : cA; const char* nB = has_next ? S.bptr(nxt) : cB;
;         for (int t = 0; t < nt; t += 2) {
;             const bool last = (t == nt - 2);
;             const char* a1 = cA + (size_t)(t + 1) * kstep;
;             const char* a2 = last ? nA : cA + (size_t)(t + 2) * kstep; const char* b2 = last ? nB : cB + (size_t)(t + 2) * kstep;
;             const char* a3 = a2 + kstep; const char* b3 = b2 + kstep;
;             PG8_LDB(B0, 0, 0); PG8_LDB(B1, 0, 1); PG8_SCHED; PG8_LDA(At, 0, 0); PG8_STAGE(PG8_SA(1, 1), a1 + hstepA, voffA);
;             PG8_WAIT_V(8); PG8_WAIT_L(0); PG8_BAR; PG8_MMA(0, 0, At, B0); PG8_MMA(0, 1, At, B1); PG8_BAR; PG8_SCHED;
;             PG8_LDA(At, 0, 1); PG8_STAGE(PG8_SB(0, 0), b2, voffB); PG8_STAGE(PG8_SB(0, 1), b2 + hstepB, voffB); PG8_STAGE(PG8_SA(0, 0), a2, voffA);
;             PG8_WAIT_V(8); PG8_WAIT_L(0); PG8_BAR; PG8_MMA(1, 0, At, B0); PG8_MMA(1, 1, At, B1); PG8_BAR; PG8_SCHED;
;             PG8_LDB(B0, 1, 0); PG8_LDB(B1, 1, 1); PG8_SCHED; PG8_LDA(At, 1, 0); PG8_STAGE(PG8_SA(0, 1), a2 + hstepA, voffA);
;             PG8_WAIT_V(8); PG8_WAIT_L(0); PG8_BAR; PG8_MMA(0, 0, At, B0); PG8_MMA(0, 1, At, B1); PG8_BAR; PG8_SCHED;
;             PG8_LDA(At, 1, 1); PG8_STAGE(PG8_SB(1, 0), b3, voffB); PG8_STAGE(PG8_SB(1, 1), b3 + hstepB, voffB); PG8_STAGE(PG8_SA(1, 0), a3, voffA);
;             PG8_WAIT_V(8); PG8_WAIT_L(0); PG8_BAR; PG8_MMA(1, 0, At, B0); PG8_MMA(1, 1, At, B1); PG8_BAR; PG8_SCHED;
.LBB0_1298:
	s_ashr_i32 s19, s18, 31
	s_lshl_b64 s[0:1], s[18:19], 20
	s_add_u32 s22, s33, s0
	s_addc_u32 s23, s38, s1
	s_and_b64 s[0:1], s[6:7], exec
	s_cselect_b32 s0, s23, s31
	s_cselect_b32 s1, s22, s30
	s_ashr_i32 s11, s10, 31
	s_lshl_b64 s[24:25], s[10:11], 20
	s_add_u32 s24, s39, s24
	s_addc_u32 s25, s40, s25
	s_and_b64 s[36:37], s[6:7], exec
	s_cselect_b32 s11, s25, s35
	s_cselect_b32 s15, s24, s34
	s_add_u32 s30, s30, 0x80080
	s_addc_u32 s31, s31, 0
	s_add_u32 s19, s34, 0x100
	s_addc_u32 s52, s35, 0
	s_mov_b32 s53, -2
	s_waitcnt lgkmcnt(0)
	s_add_u32 s34, s30, 0xfff80080
	s_addc_u32 s35, s31, -1
	s_add_i32 s54, 0, 0x10000
	s_cmp_eq_u32 s53, 28
	s_cselect_b32 s37, s0, s35
	s_cselect_b32 s36, s1, s34
	s_cselect_b32 s35, s11, s52
	s_cselect_b32 s34, s15, s19
	s_add_i32 s56, 0, 0x14000
	v_add_u32_e32 v150, s54, v155
	v_add_u32_e32 v172, s56, v155
	ds_read_b128 v[128:131], v150
	ds_read_b128 v[142:145], v150 offset:1024
	ds_read_b128 v[146:149], v150 offset:2048
	ds_read_b128 v[150:153], v150 offset:3072
	ds_read_b128 v[160:163], v172
	ds_read_b128 v[164:167], v172 offset:1024
	ds_read_b128 v[168:171], v172 offset:2048
	ds_read_b128 v[172:175], v172 offset:3072
	v_lshl_add_u64 v[216:217], s[30:31], 0, v[138:139]
	s_add_i32 m0, s27, 0xc000
	ds_read_b128 v[176:179], v159
	ds_read_b128 v[180:183], v159 offset:1024
	ds_read_b128 v[188:191], v159 offset:2048
	ds_read_b128 v[196:199], v159 offset:3072
	ds_read_b128 v[200:203], v159 offset:4096
	ds_read_b128 v[204:207], v159 offset:5120
	ds_read_b128 v[208:211], v159 offset:6144
	ds_read_b128 v[212:215], v159 offset:7168
	global_load_lds_dwordx4 v[216:217], off
	s_add_i32 m0, s27, 0xe000
	v_lshl_add_u64 v[216:217], s[30:31], 0, v[140:141]
	global_load_lds_dwordx4 v[216:217], off
	s_waitcnt vmcnt(8) lgkmcnt(0)
	s_barrier
	v_mfma_f32_16x16x32_bf16 v[124:127], v[128:131], v[176:179], 0
	v_mfma_f32_16x16x32_bf16 v[120:123], v[146:149], v[176:179], 0
	v_mfma_f32_16x16x32_bf16 v[108:111], v[128:131], v[188:191], 0
	v_mfma_f32_16x16x32_bf16 v[104:107], v[146:149], v[188:191], 0
	v_mfma_f32_16x16x32_bf16 v[96:99], v[128:131], v[200:203], 0
	v_mfma_f32_16x16x32_bf16 v[88:91], v[146:149], v[200:203], 0
	v_mfma_f32_16x16x32_bf16 v[80:83], v[128:131], v[208:211], 0
	v_mfma_f32_16x16x32_bf16 v[72:75], v[146:149], v[208:211], 0
	v_mfma_f32_16x16x32_bf16 v[124:127], v[142:145], v[180:183], v[124:127]
	v_mfma_f32_16x16x32_bf16 v[120:123], v[150:153], v[180:183], v[120:123]
	v_mfma_f32_16x16x32_bf16 v[108:111], v[142:145], v[196:199], v[108:111]
	v_mfma_f32_16x16x32_bf16 v[104:107], v[150:153], v[196:199], v[104:107]
	v_mfma_f32_16x16x32_bf16 v[96:99], v[142:145], v[204:207], v[96:99]
	v_mfma_f32_16x16x32_bf16 v[88:91], v[150:153], v[204:207], v[88:91]
	v_mfma_f32_16x16x32_bf16 v[80:83], v[142:145], v[212:215], v[80:83]
	v_mfma_f32_16x16x32_bf16 v[72:75], v[150:153], v[212:215], v[72:75]
	v_mfma_f32_16x16x32_bf16 v[116:119], v[160:163], v[176:179], 0
	v_mfma_f32_16x16x32_bf16 v[112:115], v[168:171], v[176:179], 0
	v_mfma_f32_16x16x32_bf16 v[100:103], v[160:163], v[188:191], 0
	v_mfma_f32_16x16x32_bf16 v[92:95], v[168:171], v[188:191], 0
	v_mfma_f32_16x16x32_bf16 v[84:87], v[160:163], v[200:203], 0
	v_mfma_f32_16x16x32_bf16 v[76:79], v[168:171], v[200:203], 0
	v_mfma_f32_16x16x32_bf16 v[68:71], v[160:163], v[208:211], 0
	v_mfma_f32_16x16x32_bf16 v[64:67], v[168:171], v[208:211], 0
	v_mfma_f32_16x16x32_bf16 v[116:119], v[164:167], v[180:183], v[116:119]
	v_mfma_f32_16x16x32_bf16 v[112:115], v[172:175], v[180:183], v[112:115]
	v_mfma_f32_16x16x32_bf16 v[100:103], v[164:167], v[196:199], v[100:103]
	v_mfma_f32_16x16x32_bf16 v[92:95], v[172:175], v[196:199], v[92:95]
	v_mfma_f32_16x16x32_bf16 v[84:87], v[164:167], v[204:207], v[84:87]
	v_mfma_f32_16x16x32_bf16 v[76:79], v[172:175], v[204:207], v[76:79]
	v_mfma_f32_16x16x32_bf16 v[68:71], v[164:167], v[212:215], v[68:71]
	v_mfma_f32_16x16x32_bf16 v[64:67], v[172:175], v[212:215], v[64:67]
	s_add_i32 s54, s54, s41
	v_lshl_add_u64 v[216:217], s[34:35], 0, v[184:185]
	s_mov_b32 m0, s54
	s_barrier
	ds_read_b128 v[176:179], v159 offset:16384
	ds_read_b128 v[180:183], v159 offset:17408
	ds_read_b128 v[188:191], v159 offset:18432
	ds_read_b128 v[196:199], v159 offset:19456
	ds_read_b128 v[200:203], v159 offset:20480
	ds_read_b128 v[204:207], v159 offset:21504
	ds_read_b128 v[208:211], v159 offset:22528
	ds_read_b128 v[212:215], v159 offset:23552
	global_load_lds_dwordx4 v[216:217], off
	s_add_i32 m0, s54, 0x2000
	s_add_u32 s54, s34, 0x80000
	v_lshl_add_u64 v[218:219], s[34:35], 0, v[136:137]
	s_addc_u32 s55, s35, 0
	s_add_i32 s56, s56, s41
	global_load_lds_dwordx4 v[218:219], off
	v_lshl_add_u64 v[220:221], s[54:55], 0, v[184:185]
	s_mov_b32 m0, s56
	v_lshl_add_u64 v[222:223], s[36:37], 0, v[134:135]
	global_load_lds_dwordx4 v[220:221], off
	s_add_i32 m0, s56, 0x2000
	v_lshl_add_u64 v[220:221], s[54:55], 0, v[136:137]
	global_load_lds_dwordx4 v[220:221], off
	s_mov_b32 m0, s27
	v_lshl_add_u64 v[220:221], s[36:37], 0, v[132:133]
	global_load_lds_dwordx4 v[220:221], off
	s_mov_b32 m0, s42
	s_nop 0
	global_load_lds_dwordx4 v[222:223], off
	s_waitcnt vmcnt(8) lgkmcnt(0)
	s_barrier
; #define PG8_STAGE(bufoff, gbase, voff) do { _Pragma("unroll") for (int _i = 0; _i < 2; ++_i) \
;         __builtin_amdgcn_global_load_lds((const unsigned*)((const char*)(gbase) + (voff)[_i]), (LAS unsigned*)(lds + (bufoff) + ldsw + _i * 8192), 16, 0, 0); } while (0)
; #define PG8_LDA(dst, b, h) do { _Pragma("unroll") for (int m = 0; m < 4; ++m) _Pragma("unroll") for (int k = 0; k < 2; ++k) dst[m][k] = *(const LAS bf16x8*)(lds + PG8_SA(b, h) + aoff + m * 2048 + k * 1024); } while (0)
; #define PG8_LDB(dst, b, h) do { _Pragma("unroll") for (int n = 0; n < 2; ++n) _Pragma("unroll") for (int k = 0; k < 2; ++k) dst[n][k] = *(const LAS bf16x8*)(lds + PG8_SB(b, h) + boff + n * 2048 + k * 1024); } while (0)
; #define PG8_MMA(ai, bj, At, Bt) do { __builtin_amdgcn_s_setprio(1); _Pragma("unroll") for (int m = 0; m < 4; ++m) _Pragma("unroll") for (int n = 0; n < 2; ++n) _Pragma("unroll") for (int k = 0; k < 2; ++k) \
;         acc[ai][bj][m][n] = __builtin_amdgcn_mfma_f32_16x16x32_bf16(Bt[n][k], At[m][k], acc[ai][bj][m][n], 0, 0, 0); __builtin_amdgcn_s_setprio(0); } while (0)
; #define PG8_WAIT_V(n) asm volatile("s_waitcnt vmcnt(" #n ")" ::: "memory")
; #define PG8_WAIT_L(n) asm volatile("s_waitcnt lgkmcnt(" #n ")" ::: "memory")
; #define PG8_BAR __builtin_amdgcn_s_barrier()
; #define PG8_SCHED __builtin_amdgcn_sched_barrier(0)
; template <class Epi, class Sched>
; DI void gemm_phase(LAS unsigned char* lds, const int wv, const int lda, const int ldb, const Sched& S, const Epi& E) {
;     ...
;             PG8_WAIT_V(8); PG8_WAIT_L(0); PG8_BAR; PG8_MMA(0, 0, At, B0); PG8_MMA(0, 1, At, B1); PG8_BAR; PG8_SCHED;
;             PG8_LDA(At, 0, 1); PG8_STAGE(PG8_SB(0, 0), b2, voffB); PG8_STAGE(PG8_SB(0, 1), b2 + hstepB, voffB); PG8_STAGE(PG8_SA(0, 0), a2, voffA);
;             PG8_WAIT_V(8); PG8_WAIT_L(0); PG8_BAR; PG8_MMA(1, 0, At, B0); PG8_MMA(1, 1, At, B1); PG8_BAR; PG8_SCHED;
;             PG8_LDB(B0, 1, 0); PG8_LDB(B1, 1, 1); PG8_SCHED; PG8_LDA(At, 1, 0); PG8_STAGE(PG8_SA(0, 1), a2 + hstepA, voffA);
;             PG8_WAIT_V(8); PG8_WAIT_L(0); PG8_BAR; PG8_MMA(0, 0, At, B0); PG8_MMA(0, 1, At, B1); PG8_BAR; PG8_SCHED;
	v_mfma_f32_16x16x32_bf16 v[60:63], v[128:131], v[176:179], 0
	v_mfma_f32_16x16x32_bf16 v[56:59], v[146:149], v[176:179], 0
	v_mfma_f32_16x16x32_bf16 v[48:51], v[128:131], v[188:191], 0
	v_mfma_f32_16x16x32_bf16 v[40:43], v[146:149], v[188:191], 0
	v_mfma_f32_16x16x32_bf16 v[32:35], v[128:131], v[200:203], 0
	v_mfma_f32_16x16x32_bf16 v[24:27], v[146:149], v[200:203], 0
	v_mfma_f32_16x16x32_bf16 v[16:19], v[128:131], v[208:211], 0
	v_mfma_f32_16x16x32_bf16 v[8:11], v[146:149], v[208:211], 0
	v_mfma_f32_16x16x32_bf16 v[60:63], v[142:145], v[180:183], v[60:63]
	v_mfma_f32_16x16x32_bf16 v[56:59], v[150:153], v[180:183], v[56:59]
	v_mfma_f32_16x16x32_bf16 v[48:51], v[142:145], v[196:199], v[48:51]
	v_mfma_f32_16x16x32_bf16 v[40:43], v[150:153], v[196:199], v[40:43]
	v_mfma_f32_16x16x32_bf16 v[32:35], v[142:145], v[204:207], v[32:35]
	v_mfma_f32_16x16x32_bf16 v[24:27], v[150:153], v[204:207], v[24:27]
	v_mfma_f32_16x16x32_bf16 v[16:19], v[142:145], v[212:215], v[16:19]
	v_mfma_f32_16x16x32_bf16 v[8:11], v[150:153], v[212:215], v[8:11]
	v_mfma_f32_16x16x32_bf16 v[52:55], v[160:163], v[176:179], 0
	v_mfma_f32_16x16x32_bf16 v[44:47], v[168:171], v[176:179], 0
	v_mfma_f32_16x16x32_bf16 v[36:39], v[160:163], v[188:191], 0
	v_mfma_f32_16x16x32_bf16 v[28:31], v[168:171], v[188:191], 0
	v_mfma_f32_16x16x32_bf16 v[20:23], v[160:163], v[200:203], 0
	v_mfma_f32_16x16x32_bf16 v[12:15], v[168:171], v[200:203], 0
	v_mfma_f32_16x16x32_bf16 v[4:7], v[160:163], v[208:211], 0
	v_mfma_f32_16x16x32_bf16 v[0:3], v[168:171], v[208:211], 0
	v_mfma_f32_16x16x32_bf16 v[52:55], v[164:167], v[180:183], v[52:55]
	v_mfma_f32_16x16x32_bf16 v[44:47], v[172:175], v[180:183], v[44:47]
	v_mfma_f32_16x16x32_bf16 v[36:39], v[164:167], v[196:199], v[36:39]
	v_mfma_f32_16x16x32_bf16 v[28:31], v[172:175], v[196:199], v[28:31]
	v_mfma_f32_16x16x32_bf16 v[20:23], v[164:167], v[204:207], v[20:23]
	v_mfma_f32_16x16x32_bf16 v[12:15], v[172:175], v[204:207], v[12:15]
	v_mfma_f32_16x16x32_bf16 v[4:7], v[164:167], v[212:215], v[4:7]
	v_mfma_f32_16x16x32_bf16 v[0:3], v[172:175], v[212:215], v[0:3]
	s_add_i32 s54, 0, 0x18000
	s_add_i32 s55, 0, 0x1c000
	s_barrier
	v_add_u32_e32 v150, s54, v155
	v_add_u32_e32 v172, s55, v155
	ds_read_b128 v[128:131], v150
	ds_read_b128 v[142:145], v150 offset:1024
	ds_read_b128 v[146:149], v150 offset:2048
	ds_read_b128 v[150:153], v150 offset:3072
	ds_read_b128 v[160:163], v172
	ds_read_b128 v[164:167], v172 offset:1024
	ds_read_b128 v[168:171], v172 offset:2048
	ds_read_b128 v[172:175], v172 offset:3072
	s_add_u32 s36, s36, 0x80000
	s_addc_u32 s37, s37, 0
	s_mov_b32 m0, s43
	v_lshl_add_u64 v[234:235], s[36:37], 0, v[132:133]
	ds_read_b128 v[176:179], v159 offset:32768
	ds_read_b128 v[180:183], v159 offset:33792
	ds_read_b128 v[188:191], v159 offset:34816
	ds_read_b128 v[196:199], v159 offset:35840
	ds_read_b128 v[200:203], v159 offset:36864
	ds_read_b128 v[204:207], v159 offset:37888
	ds_read_b128 v[208:211], v159 offset:38912
	ds_read_b128 v[212:215], v159 offset:39936
	global_load_lds_dwordx4 v[234:235], off
	s_mov_b32 m0, s44
	v_lshl_add_u64 v[234:235], s[36:37], 0, v[134:135]
	global_load_lds_dwordx4 v[234:235], off
	s_waitcnt vmcnt(8) lgkmcnt(0)
	s_barrier
	v_mfma_f32_16x16x32_bf16 v[124:127], v[128:131], v[176:179], v[124:127]
	v_mfma_f32_16x16x32_bf16 v[120:123], v[146:149], v[176:179], v[120:123]
	v_mfma_f32_16x16x32_bf16 v[108:111], v[128:131], v[188:191], v[108:111]
	v_mfma_f32_16x16x32_bf16 v[104:107], v[146:149], v[188:191], v[104:107]
	v_mfma_f32_16x16x32_bf16 v[96:99], v[128:131], v[200:203], v[96:99]
	v_mfma_f32_16x16x32_bf16 v[88:91], v[146:149], v[200:203], v[88:91]
	v_mfma_f32_16x16x32_bf16 v[80:83], v[128:131], v[208:211], v[80:83]
	v_mfma_f32_16x16x32_bf16 v[72:75], v[146:149], v[208:211], v[72:75]
	v_mfma_f32_16x16x32_bf16 v[124:127], v[142:145], v[180:183], v[124:127]
	v_mfma_f32_16x16x32_bf16 v[120:123], v[150:153], v[180:183], v[120:123]
	v_mfma_f32_16x16x32_bf16 v[108:111], v[142:145], v[196:199], v[108:111]
	v_mfma_f32_16x16x32_bf16 v[104:107], v[150:153], v[196:199], v[104:107]
	v_mfma_f32_16x16x32_bf16 v[96:99], v[142:145], v[204:207], v[96:99]
	v_mfma_f32_16x16x32_bf16 v[88:91], v[150:153], v[204:207], v[88:91]
	v_mfma_f32_16x16x32_bf16 v[80:83], v[142:145], v[212:215], v[80:83]
	v_mfma_f32_16x16x32_bf16 v[72:75], v[150:153], v[212:215], v[72:75]
	v_mfma_f32_16x16x32_bf16 v[116:119], v[160:163], v[176:179], v[116:119]
	v_mfma_f32_16x16x32_bf16 v[112:115], v[168:171], v[176:179], v[112:115]
	v_mfma_f32_16x16x32_bf16 v[100:103], v[160:163], v[188:191], v[100:103]
	v_mfma_f32_16x16x32_bf16 v[92:95], v[168:171], v[188:191], v[92:95]
	v_mfma_f32_16x16x32_bf16 v[84:87], v[160:163], v[200:203], v[84:87]
	v_mfma_f32_16x16x32_bf16 v[76:79], v[168:171], v[200:203], v[76:79]
	v_mfma_f32_16x16x32_bf16 v[68:71], v[160:163], v[208:211], v[68:71]
	v_mfma_f32_16x16x32_bf16 v[64:67], v[168:171], v[208:211], v[64:67]
	v_mfma_f32_16x16x32_bf16 v[116:119], v[164:167], v[180:183], v[116:119]
	v_mfma_f32_16x16x32_bf16 v[112:115], v[172:175], v[180:183], v[112:115]
	v_mfma_f32_16x16x32_bf16 v[100:103], v[164:167], v[196:199], v[100:103]
	v_mfma_f32_16x16x32_bf16 v[92:95], v[172:175], v[196:199], v[92:95]
	v_mfma_f32_16x16x32_bf16 v[84:87], v[164:167], v[204:207], v[84:87]
	v_mfma_f32_16x16x32_bf16 v[76:79], v[172:175], v[204:207], v[76:79]
	v_mfma_f32_16x16x32_bf16 v[68:71], v[164:167], v[212:215], v[68:71]
	v_mfma_f32_16x16x32_bf16 v[64:67], v[172:175], v[212:215], v[64:67]
	s_add_i32 s36, s54, s41
	v_lshl_add_u64 v[216:217], v[216:217], 0, s[28:29]
	s_mov_b32 m0, s36
	s_barrier
; #define PG8_STAGE(bufoff, gbase, voff) do { _Pragma("unroll") for (int _i = 0; _i < 2; ++_i) \
;         __builtin_amdgcn_global_load_lds((const unsigned*)((const char*)(gbase) + (voff)[_i]), (LAS unsigned*)(lds + (bufoff) + ldsw + _i * 8192), 16, 0, 0); } while (0)
; #define PG8_LDA(dst, b, h) do { _Pragma("unroll") for (int m = 0; m < 4; ++m) _Pragma("unroll") for (int k = 0; k < 2; ++k) dst[m][k] = *(const LAS bf16x8*)(lds + PG8_SA(b, h) + aoff + m * 2048 + k * 1024); } while (0)
; #define PG8_LDB(dst, b, h) do { _Pragma("unroll") for (int n = 0; n < 2; ++n) _Pragma("unroll") for (int k = 0; k < 2; ++k) dst[n][k] = *(const LAS bf16x8*)(lds + PG8_SB(b, h) + boff + n * 2048 + k * 1024); } while (0)
; #define PG8_MMA(ai, bj, At, Bt) do { __builtin_amdgcn_s_setprio(1); _Pragma("unroll") for (int m = 0; m < 4; ++m) _Pragma("unroll") for (int n = 0; n < 2; ++n) _Pragma("unroll") for (int k = 0; k < 2; ++k) \
;         acc[ai][bj][m][n] = __builtin_amdgcn_mfma_f32_16x16x32_bf16(Bt[n][k], At[m][k], acc[ai][bj][m][n], 0, 0, 0); __builtin_amdgcn_s_setprio(0); } while (0)
; #define PG8_WAIT_V(n) asm volatile("s_waitcnt vmcnt(" #n ")" ::: "memory")
; #define PG8_WAIT_L(n) asm volatile("s_waitcnt lgkmcnt(" #n ")" ::: "memory")
; template <class Epi, class Sched>
; DI void gemm_phase(LAS unsigned char* lds, const int wv, const int lda, const int ldb, const Sched& S, const Epi& E) {
;     ...
;         for (int t = 0; t < nt; t += 2) {
;             const bool last = (t == nt - 2);
;             const char* a1 = cA + (size_t)(t + 1) * kstep;
;             const char* a2 = last ? nA : cA + (size_t)(t + 2) * kstep; const char* b2 = last ? nB : cB + (size_t)(t + 2) * kstep;
;             const char* a3 = a2 + kstep; const char* b3 = b2 + kstep;
;             PG8_LDB(B0, 0, 0); PG8_LDB(B1, 0, 1); PG8_SCHED; PG8_LDA(At, 0, 0); PG8_STAGE(PG8_SA(1, 1), a1 + hstepA, voffA);
;             PG8_WAIT_V(8); PG8_WAIT_L(0); PG8_BAR; PG8_MMA(0, 0, At, B0); PG8_MMA(0, 1, At, B1); PG8_BAR; PG8_SCHED;
;     ...
;             PG8_WAIT_V(8); PG8_WAIT_L(0); PG8_BAR; PG8_MMA(0, 0, At, B0); PG8_MMA(0, 1, At, B1); PG8_BAR; PG8_SCHED;
;             PG8_LDA(At, 1, 1); PG8_STAGE(PG8_SB(1, 0), b3, voffB); PG8_STAGE(PG8_SB(1, 1), b3 + hstepB, voffB); PG8_STAGE(PG8_SA(1, 0), a3, voffA);
;             PG8_WAIT_V(8); PG8_WAIT_L(0); PG8_BAR; PG8_MMA(1, 0, At, B0); PG8_MMA(1, 1, At, B1); PG8_BAR; PG8_SCHED;
	ds_read_b128 v[176:179], v159 offset:49152
	ds_read_b128 v[180:183], v159 offset:50176
	ds_read_b128 v[188:191], v159 offset:51200
	ds_read_b128 v[196:199], v159 offset:52224
	ds_read_b128 v[200:203], v159 offset:53248
	ds_read_b128 v[204:207], v159 offset:54272
	ds_read_b128 v[208:211], v159 offset:55296
	ds_read_b128 v[212:215], v159 offset:56320
	global_load_lds_dwordx4 v[216:217], off
	s_add_i32 m0, s36, 0x2000
	s_add_u32 s34, s34, 0x80080
	v_lshl_add_u64 v[216:217], v[218:219], 0, s[28:29]
	s_addc_u32 s35, s35, 0
	s_add_i32 s36, s55, s41
	global_load_lds_dwordx4 v[216:217], off
	s_mov_b32 m0, s36
	v_lshl_add_u64 v[216:217], s[34:35], 0, v[184:185]
	global_load_lds_dwordx4 v[216:217], off
	s_add_i32 m0, s36, 0x2000
	v_lshl_add_u64 v[216:217], s[34:35], 0, v[136:137]
	global_load_lds_dwordx4 v[216:217], off
	s_mov_b32 m0, s45
	v_lshl_add_u64 v[216:217], v[220:221], 0, s[28:29]
	global_load_lds_dwordx4 v[216:217], off
	s_mov_b32 m0, s46
	v_lshl_add_u64 v[216:217], v[222:223], 0, s[28:29]
	global_load_lds_dwordx4 v[216:217], off
	s_waitcnt vmcnt(8) lgkmcnt(0)
	s_barrier
	v_mfma_f32_16x16x32_bf16 v[60:63], v[128:131], v[176:179], v[60:63]
	v_mfma_f32_16x16x32_bf16 v[56:59], v[146:149], v[176:179], v[56:59]
	v_mfma_f32_16x16x32_bf16 v[48:51], v[128:131], v[188:191], v[48:51]
	v_mfma_f32_16x16x32_bf16 v[40:43], v[146:149], v[188:191], v[40:43]
	v_mfma_f32_16x16x32_bf16 v[32:35], v[128:131], v[200:203], v[32:35]
	v_mfma_f32_16x16x32_bf16 v[24:27], v[146:149], v[200:203], v[24:27]
	v_mfma_f32_16x16x32_bf16 v[16:19], v[128:131], v[208:211], v[16:19]
	v_mfma_f32_16x16x32_bf16 v[8:11], v[146:149], v[208:211], v[8:11]
	v_mfma_f32_16x16x32_bf16 v[60:63], v[142:145], v[180:183], v[60:63]
	v_mfma_f32_16x16x32_bf16 v[56:59], v[150:153], v[180:183], v[56:59]
	v_mfma_f32_16x16x32_bf16 v[48:51], v[142:145], v[196:199], v[48:51]
	v_mfma_f32_16x16x32_bf16 v[40:43], v[150:153], v[196:199], v[40:43]
	v_mfma_f32_16x16x32_bf16 v[32:35], v[142:145], v[204:207], v[32:35]
	v_mfma_f32_16x16x32_bf16 v[24:27], v[150:153], v[204:207], v[24:27]
	v_mfma_f32_16x16x32_bf16 v[16:19], v[142:145], v[212:215], v[16:19]
	v_mfma_f32_16x16x32_bf16 v[8:11], v[150:153], v[212:215], v[8:11]
	v_mfma_f32_16x16x32_bf16 v[52:55], v[160:163], v[176:179], v[52:55]
	v_mfma_f32_16x16x32_bf16 v[44:47], v[168:171], v[176:179], v[44:47]
	v_mfma_f32_16x16x32_bf16 v[36:39], v[160:163], v[188:191], v[36:39]
	v_mfma_f32_16x16x32_bf16 v[28:31], v[168:171], v[188:191], v[28:31]
	v_mfma_f32_16x16x32_bf16 v[20:23], v[160:163], v[200:203], v[20:23]
	v_mfma_f32_16x16x32_bf16 v[12:15], v[168:171], v[200:203], v[12:15]
	v_mfma_f32_16x16x32_bf16 v[4:7], v[160:163], v[208:211], v[4:7]
	v_mfma_f32_16x16x32_bf16 v[0:3], v[168:171], v[208:211], v[0:3]
	v_mfma_f32_16x16x32_bf16 v[52:55], v[164:167], v[180:183], v[52:55]
	v_mfma_f32_16x16x32_bf16 v[44:47], v[172:175], v[180:183], v[44:47]
	v_mfma_f32_16x16x32_bf16 v[36:39], v[164:167], v[196:199], v[36:39]
	v_mfma_f32_16x16x32_bf16 v[28:31], v[172:175], v[196:199], v[28:31]
	v_mfma_f32_16x16x32_bf16 v[20:23], v[164:167], v[204:207], v[20:23]
	v_mfma_f32_16x16x32_bf16 v[12:15], v[172:175], v[204:207], v[12:15]
	v_mfma_f32_16x16x32_bf16 v[4:7], v[164:167], v[212:215], v[4:7]
	v_mfma_f32_16x16x32_bf16 v[0:3], v[172:175], v[212:215], v[0:3]
	s_add_i32 s53, s53, 2
	s_add_u32 s30, s30, 0x100
	s_addc_u32 s31, s31, 0
	s_add_u32 s19, s19, 0x100
	s_addc_u32 s52, s52, 0
	s_barrier
.LBB0_1299:
	s_add_u32 s34, s30, 0xfff80080
	s_addc_u32 s35, s31, -1
	s_add_i32 s54, 0, 0x10000
	s_cmp_eq_u32 s53, 28
	s_cselect_b32 s37, s0, s35
	s_cselect_b32 s36, s1, s34
	s_cselect_b32 s35, s11, s52
	s_cselect_b32 s34, s15, s19
	s_add_i32 s56, 0, 0x14000
	v_add_u32_e32 v150, s54, v155
	v_add_u32_e32 v172, s56, v155
	ds_read_b128 v[128:131], v150
	ds_read_b128 v[142:145], v150 offset:1024
	ds_read_b128 v[146:149], v150 offset:2048
	ds_read_b128 v[150:153], v150 offset:3072
	ds_read_b128 v[160:163], v172
	ds_read_b128 v[164:167], v172 offset:1024
	ds_read_b128 v[168:171], v172 offset:2048
	ds_read_b128 v[172:175], v172 offset:3072
	v_lshl_add_u64 v[216:217], s[30:31], 0, v[138:139]
	s_add_i32 m0, s27, 0xc000
	ds_read_b128 v[176:179], v159
	ds_read_b128 v[180:183], v159 offset:1024
	ds_read_b128 v[188:191], v159 offset:2048
	ds_read_b128 v[196:199], v159 offset:3072
	ds_read_b128 v[200:203], v159 offset:4096
	ds_read_b128 v[204:207], v159 offset:5120
	ds_read_b128 v[208:211], v159 offset:6144
	ds_read_b128 v[212:215], v159 offset:7168
	global_load_lds_dwordx4 v[216:217], off
	s_add_i32 m0, s27, 0xe000
	v_lshl_add_u64 v[216:217], s[30:31], 0, v[140:141]
	global_load_lds_dwordx4 v[216:217], off
	s_waitcnt vmcnt(8) lgkmcnt(0)
	s_barrier
; #define PG8_STAGE(bufoff, gbase, voff) do { _Pragma("unroll") for (int _i = 0; _i < 2; ++_i) \
;         __builtin_amdgcn_global_load_lds((const unsigned*)((const char*)(gbase) + (voff)[_i]), (LAS unsigned*)(lds + (bufoff) + ldsw + _i * 8192), 16, 0, 0); } while (0)
; #define PG8_LDA(dst, b, h) do { _Pragma("unroll") for (int m = 0; m < 4; ++m) _Pragma("unroll") for (int k = 0; k < 2; ++k) dst[m][k] = *(const LAS bf16x8*)(lds + PG8_SA(b, h) + aoff + m * 2048 + k * 1024); } while (0)
; #define PG8_LDB(dst, b, h) do { _Pragma("unroll") for (int n = 0; n < 2; ++n) _Pragma("unroll") for (int k = 0; k < 2; ++k) dst[n][k] = *(const LAS bf16x8*)(lds + PG8_SB(b, h) + boff + n * 2048 + k * 1024); } while (0)
; #define PG8_MMA(ai, bj, At, Bt) do { __builtin_amdgcn_s_setprio(1); _Pragma("unroll") for (int m = 0; m < 4; ++m) _Pragma("unroll") for (int n = 0; n < 2; ++n) _Pragma("unroll") for (int k = 0; k < 2; ++k) \
;         acc[ai][bj][m][n] = __builtin_amdgcn_mfma_f32_16x16x32_bf16(Bt[n][k], At[m][k], acc[ai][bj][m][n], 0, 0, 0); __builtin_amdgcn_s_setprio(0); } while (0)
; #define PG8_WAIT_V(n) asm volatile("s_waitcnt vmcnt(" #n ")" ::: "memory")
; #define PG8_WAIT_L(n) asm volatile("s_waitcnt lgkmcnt(" #n ")" ::: "memory")
; #define PG8_BAR __builtin_amdgcn_s_barrier()
; #define PG8_SCHED __builtin_amdgcn_sched_barrier(0)
; template <class Epi, class Sched>
; DI void gemm_phase(LAS unsigned char* lds, const int wv, const int lda, const int ldb, const Sched& S, const Epi& E) {
;     ...
;             PG8_WAIT_V(8); PG8_WAIT_L(0); PG8_BAR; PG8_MMA(0, 0, At, B0); PG8_MMA(0, 1, At, B1); PG8_BAR; PG8_SCHED;
;             PG8_LDA(At, 0, 1); PG8_STAGE(PG8_SB(0, 0), b2, voffB); PG8_STAGE(PG8_SB(0, 1), b2 + hstepB, voffB); PG8_STAGE(PG8_SA(0, 0), a2, voffA);
;             PG8_WAIT_V(8); PG8_WAIT_L(0); PG8_BAR; PG8_MMA(1, 0, At, B0); PG8_MMA(1, 1, At, B1); PG8_BAR; PG8_SCHED;
;             PG8_LDB(B0, 1, 0); PG8_LDB(B1, 1, 1); PG8_SCHED; PG8_LDA(At, 1, 0); PG8_STAGE(PG8_SA(0, 1), a2 + hstepA, voffA);
;             PG8_WAIT_V(8); PG8_WAIT_L(0); PG8_BAR; PG8_MMA(0, 0, At, B0); PG8_MMA(0, 1, At, B1); PG8_BAR; PG8_SCHED;
	v_mfma_f32_16x16x32_bf16 v[124:127], v[128:131], v[176:179], v[124:127]
	v_mfma_f32_16x16x32_bf16 v[120:123], v[146:149], v[176:179], v[120:123]
	v_mfma_f32_16x16x32_bf16 v[108:111], v[128:131], v[188:191], v[108:111]
	v_mfma_f32_16x16x32_bf16 v[104:107], v[146:149], v[188:191], v[104:107]
	v_mfma_f32_16x16x32_bf16 v[96:99], v[128:131], v[200:203], v[96:99]
	v_mfma_f32_16x16x32_bf16 v[88:91], v[146:149], v[200:203], v[88:91]
	v_mfma_f32_16x16x32_bf16 v[80:83], v[128:131], v[208:211], v[80:83]
	v_mfma_f32_16x16x32_bf16 v[72:75], v[146:149], v[208:211], v[72:75]
	v_mfma_f32_16x16x32_bf16 v[124:127], v[142:145], v[180:183], v[124:127]
	v_mfma_f32_16x16x32_bf16 v[120:123], v[150:153], v[180:183], v[120:123]
	v_mfma_f32_16x16x32_bf16 v[108:111], v[142:145], v[196:199], v[108:111]
	v_mfma_f32_16x16x32_bf16 v[104:107], v[150:153], v[196:199], v[104:107]
	v_mfma_f32_16x16x32_bf16 v[96:99], v[142:145], v[204:207], v[96:99]
	v_mfma_f32_16x16x32_bf16 v[88:91], v[150:153], v[204:207], v[88:91]
	v_mfma_f32_16x16x32_bf16 v[80:83], v[142:145], v[212:215], v[80:83]
	v_mfma_f32_16x16x32_bf16 v[72:75], v[150:153], v[212:215], v[72:75]
	v_mfma_f32_16x16x32_bf16 v[116:119], v[160:163], v[176:179], v[116:119]
	v_mfma_f32_16x16x32_bf16 v[112:115], v[168:171], v[176:179], v[112:115]
	v_mfma_f32_16x16x32_bf16 v[100:103], v[160:163], v[188:191], v[100:103]
	v_mfma_f32_16x16x32_bf16 v[92:95], v[168:171], v[188:191], v[92:95]
	v_mfma_f32_16x16x32_bf16 v[84:87], v[160:163], v[200:203], v[84:87]
	v_mfma_f32_16x16x32_bf16 v[76:79], v[168:171], v[200:203], v[76:79]
	v_mfma_f32_16x16x32_bf16 v[68:71], v[160:163], v[208:211], v[68:71]
	v_mfma_f32_16x16x32_bf16 v[64:67], v[168:171], v[208:211], v[64:67]
	v_mfma_f32_16x16x32_bf16 v[116:119], v[164:167], v[180:183], v[116:119]
	v_mfma_f32_16x16x32_bf16 v[112:115], v[172:175], v[180:183], v[112:115]
	v_mfma_f32_16x16x32_bf16 v[100:103], v[164:167], v[196:199], v[100:103]
	v_mfma_f32_16x16x32_bf16 v[92:95], v[172:175], v[196:199], v[92:95]
	v_mfma_f32_16x16x32_bf16 v[84:87], v[164:167], v[204:207], v[84:87]
	v_mfma_f32_16x16x32_bf16 v[76:79], v[172:175], v[204:207], v[76:79]
	v_mfma_f32_16x16x32_bf16 v[68:71], v[164:167], v[212:215], v[68:71]
	v_mfma_f32_16x16x32_bf16 v[64:67], v[172:175], v[212:215], v[64:67]
	s_add_i32 s54, s54, s41
	v_lshl_add_u64 v[216:217], s[34:35], 0, v[184:185]
	s_mov_b32 m0, s54
	s_barrier
	ds_read_b128 v[176:179], v159 offset:16384
	ds_read_b128 v[180:183], v159 offset:17408
	ds_read_b128 v[188:191], v159 offset:18432
	ds_read_b128 v[196:199], v159 offset:19456
	ds_read_b128 v[200:203], v159 offset:20480
	ds_read_b128 v[204:207], v159 offset:21504
	ds_read_b128 v[208:211], v159 offset:22528
	ds_read_b128 v[212:215], v159 offset:23552
	global_load_lds_dwordx4 v[216:217], off
	s_add_i32 m0, s54, 0x2000
	s_add_u32 s54, s34, 0x80000
	v_lshl_add_u64 v[218:219], s[34:35], 0, v[136:137]
	s_addc_u32 s55, s35, 0
	s_add_i32 s56, s56, s41
	global_load_lds_dwordx4 v[218:219], off
	v_lshl_add_u64 v[220:221], s[54:55], 0, v[184:185]
	s_mov_b32 m0, s56
	v_lshl_add_u64 v[222:223], s[36:37], 0, v[134:135]
	global_load_lds_dwordx4 v[220:221], off
	s_add_i32 m0, s56, 0x2000
	v_lshl_add_u64 v[220:221], s[54:55], 0, v[136:137]
	global_load_lds_dwordx4 v[220:221], off
	s_mov_b32 m0, s27
	v_lshl_add_u64 v[220:221], s[36:37], 0, v[132:133]
	global_load_lds_dwordx4 v[220:221], off
	s_mov_b32 m0, s42
	s_nop 0
	global_load_lds_dwordx4 v[222:223], off
	s_waitcnt vmcnt(8) lgkmcnt(0)
	s_barrier
	v_mfma_f32_16x16x32_bf16 v[60:63], v[128:131], v[176:179], v[60:63]
	v_mfma_f32_16x16x32_bf16 v[56:59], v[146:149], v[176:179], v[56:59]
	v_mfma_f32_16x16x32_bf16 v[48:51], v[128:131], v[188:191], v[48:51]
	v_mfma_f32_16x16x32_bf16 v[40:43], v[146:149], v[188:191], v[40:43]
	v_mfma_f32_16x16x32_bf16 v[32:35], v[128:131], v[200:203], v[32:35]
	v_mfma_f32_16x16x32_bf16 v[24:27], v[146:149], v[200:203], v[24:27]
	v_mfma_f32_16x16x32_bf16 v[16:19], v[128:131], v[208:211], v[16:19]
	v_mfma_f32_16x16x32_bf16 v[8:11], v[146:149], v[208:211], v[8:11]
	v_mfma_f32_16x16x32_bf16 v[60:63], v[142:145], v[180:183], v[60:63]
	v_mfma_f32_16x16x32_bf16 v[56:59], v[150:153], v[180:183], v[56:59]
	v_mfma_f32_16x16x32_bf16 v[48:51], v[142:145], v[196:199], v[48:51]
	v_mfma_f32_16x16x32_bf16 v[40:43], v[150:153], v[196:199], v[40:43]
	v_mfma_f32_16x16x32_bf16 v[32:35], v[142:145], v[204:207], v[32:35]
	v_mfma_f32_16x16x32_bf16 v[24:27], v[150:153], v[204:207], v[24:27]
	v_mfma_f32_16x16x32_bf16 v[16:19], v[142:145], v[212:215], v[16:19]
	v_mfma_f32_16x16x32_bf16 v[8:11], v[150:153], v[212:215], v[8:11]
	v_mfma_f32_16x16x32_bf16 v[52:55], v[160:163], v[176:179], v[52:55]
	v_mfma_f32_16x16x32_bf16 v[44:47], v[168:171], v[176:179], v[44:47]
	v_mfma_f32_16x16x32_bf16 v[36:39], v[160:163], v[188:191], v[36:39]
	v_mfma_f32_16x16x32_bf16 v[28:31], v[168:171], v[188:191], v[28:31]
	v_mfma_f32_16x16x32_bf16 v[20:23], v[160:163], v[200:203], v[20:23]
	v_mfma_f32_16x16x32_bf16 v[12:15], v[168:171], v[200:203], v[12:15]
	v_mfma_f32_16x16x32_bf16 v[4:7], v[160:163], v[208:211], v[4:7]
	v_mfma_f32_16x16x32_bf16 v[0:3], v[168:171], v[208:211], v[0:3]
	v_mfma_f32_16x16x32_bf16 v[52:55], v[164:167], v[180:183], v[52:55]
	v_mfma_f32_16x16x32_bf16 v[44:47], v[172:175], v[180:183], v[44:47]
	v_mfma_f32_16x16x32_bf16 v[36:39], v[164:167], v[196:199], v[36:39]
	v_mfma_f32_16x16x32_bf16 v[28:31], v[172:175], v[196:199], v[28:31]
	v_mfma_f32_16x16x32_bf16 v[20:23], v[164:167], v[204:207], v[20:23]
	v_mfma_f32_16x16x32_bf16 v[12:15], v[172:175], v[204:207], v[12:15]
	v_mfma_f32_16x16x32_bf16 v[4:7], v[164:167], v[212:215], v[4:7]
	v_mfma_f32_16x16x32_bf16 v[0:3], v[172:175], v[212:215], v[0:3]
	s_add_i32 s54, 0, 0x18000
	s_add_i32 s55, 0, 0x1c000
	s_barrier
; #define PG8_STAGE(bufoff, gbase, voff) do { _Pragma("unroll") for (int _i = 0; _i < 2; ++_i) \
;         __builtin_amdgcn_global_load_lds((const unsigned*)((const char*)(gbase) + (voff)[_i]), (LAS unsigned*)(lds + (bufoff) + ldsw + _i * 8192), 16, 0, 0); } while (0)
; #define PG8_LDA(dst, b, h) do { _Pragma("unroll") for (int m = 0; m < 4; ++m) _Pragma("unroll") for (int k = 0; k < 2; ++k) dst[m][k] = *(const LAS bf16x8*)(lds + PG8_SA(b, h) + aoff + m * 2048 + k * 1024); } while (0)
; #define PG8_LDB(dst, b, h) do { _Pragma("unroll") for (int n = 0; n < 2; ++n) _Pragma("unroll") for (int k = 0; k < 2; ++k) dst[n][k] = *(const LAS bf16x8*)(lds + PG8_SB(b, h) + boff + n * 2048 + k * 1024); } while (0)
; #define PG8_MMA(ai, bj, At, Bt) do { __builtin_amdgcn_s_setprio(1); _Pragma("unroll") for (int m = 0; m < 4; ++m) _Pragma("unroll") for (int n = 0; n < 2; ++n) _Pragma("unroll") for (int k = 0; k < 2; ++k) \
;         acc[ai][bj][m][n] = __builtin_amdgcn_mfma_f32_16x16x32_bf16(Bt[n][k], At[m][k], acc[ai][bj][m][n], 0, 0, 0); __builtin_amdgcn_s_setprio(0); } while (0)
; #define PG8_WAIT_V(n) asm volatile("s_waitcnt vmcnt(" #n ")" ::: "memory")
; #define PG8_WAIT_L(n) asm volatile("s_waitcnt lgkmcnt(" #n ")" ::: "memory")
; #define PG8_BAR __builtin_amdgcn_s_barrier()
; #define PG8_SCHED __builtin_amdgcn_sched_barrier(0)
; template <class Epi, class Sched>
; DI void gemm_phase(LAS unsigned char* lds, const int wv, const int lda, const int ldb, const Sched& S, const Epi& E) {
;     ...
;             PG8_LDB(B0, 1, 0); PG8_LDB(B1, 1, 1); PG8_SCHED; PG8_LDA(At, 1, 0); PG8_STAGE(PG8_SA(0, 1), a2 + hstepA, voffA);
;             PG8_WAIT_V(8); PG8_WAIT_L(0); PG8_BAR; PG8_MMA(0, 0, At, B0); PG8_MMA(0, 1, At, B1); PG8_BAR; PG8_SCHED;
;             PG8_LDA(At, 1, 1); PG8_STAGE(PG8_SB(1, 0), b3, voffB); PG8_STAGE(PG8_SB(1, 1), b3 + hstepB, voffB); PG8_STAGE(PG8_SA(1, 0), a3, voffA);
;             PG8_WAIT_V(8); PG8_WAIT_L(0); PG8_BAR; PG8_MMA(1, 0, At, B0); PG8_MMA(1, 1, At, B1); PG8_BAR; PG8_SCHED;
;         }
	v_add_u32_e32 v150, s54, v155
	v_add_u32_e32 v172, s55, v155
	ds_read_b128 v[128:131], v150
	ds_read_b128 v[142:145], v150 offset:1024
	ds_read_b128 v[146:149], v150 offset:2048
	ds_read_b128 v[150:153], v150 offset:3072
	ds_read_b128 v[160:163], v172
	ds_read_b128 v[164:167], v172 offset:1024
	ds_read_b128 v[168:171], v172 offset:2048
	ds_read_b128 v[172:175], v172 offset:3072
	s_add_u32 s36, s36, 0x80000
	s_addc_u32 s37, s37, 0
	s_mov_b32 m0, s43
	v_lshl_add_u64 v[234:235], s[36:37], 0, v[132:133]
	ds_read_b128 v[176:179], v159 offset:32768
	ds_read_b128 v[180:183], v159 offset:33792
	ds_read_b128 v[188:191], v159 offset:34816
	ds_read_b128 v[196:199], v159 offset:35840
	ds_read_b128 v[200:203], v159 offset:36864
	ds_read_b128 v[204:207], v159 offset:37888
	ds_read_b128 v[208:211], v159 offset:38912
	ds_read_b128 v[212:215], v159 offset:39936
	global_load_lds_dwordx4 v[234:235], off
	s_mov_b32 m0, s44
	v_lshl_add_u64 v[234:235], s[36:37], 0, v[134:135]
	global_load_lds_dwordx4 v[234:235], off
	s_waitcnt vmcnt(8) lgkmcnt(0)
	s_barrier
	v_mfma_f32_16x16x32_bf16 v[124:127], v[128:131], v[176:179], v[124:127]
	v_mfma_f32_16x16x32_bf16 v[120:123], v[146:149], v[176:179], v[120:123]
	v_mfma_f32_16x16x32_bf16 v[108:111], v[128:131], v[188:191], v[108:111]
	v_mfma_f32_16x16x32_bf16 v[104:107], v[146:149], v[188:191], v[104:107]
	v_mfma_f32_16x16x32_bf16 v[96:99], v[128:131], v[200:203], v[96:99]
	v_mfma_f32_16x16x32_bf16 v[88:91], v[146:149], v[200:203], v[88:91]
	v_mfma_f32_16x16x32_bf16 v[80:83], v[128:131], v[208:211], v[80:83]
	v_mfma_f32_16x16x32_bf16 v[72:75], v[146:149], v[208:211], v[72:75]
	v_mfma_f32_16x16x32_bf16 v[124:127], v[142:145], v[180:183], v[124:127]
	v_mfma_f32_16x16x32_bf16 v[120:123], v[150:153], v[180:183], v[120:123]
	v_mfma_f32_16x16x32_bf16 v[108:111], v[142:145], v[196:199], v[108:111]
	v_mfma_f32_16x16x32_bf16 v[104:107], v[150:153], v[196:199], v[104:107]
	v_mfma_f32_16x16x32_bf16 v[96:99], v[142:145], v[204:207], v[96:99]
	v_mfma_f32_16x16x32_bf16 v[88:91], v[150:153], v[204:207], v[88:91]
	v_mfma_f32_16x16x32_bf16 v[80:83], v[142:145], v[212:215], v[80:83]
	v_mfma_f32_16x16x32_bf16 v[72:75], v[150:153], v[212:215], v[72:75]
	v_mfma_f32_16x16x32_bf16 v[116:119], v[160:163], v[176:179], v[116:119]
	v_mfma_f32_16x16x32_bf16 v[112:115], v[168:171], v[176:179], v[112:115]
	v_mfma_f32_16x16x32_bf16 v[100:103], v[160:163], v[188:191], v[100:103]
	v_mfma_f32_16x16x32_bf16 v[92:95], v[168:171], v[188:191], v[92:95]
	v_mfma_f32_16x16x32_bf16 v[84:87], v[160:163], v[200:203], v[84:87]
	v_mfma_f32_16x16x32_bf16 v[76:79], v[168:171], v[200:203], v[76:79]
	v_mfma_f32_16x16x32_bf16 v[68:71], v[160:163], v[208:211], v[68:71]
	v_mfma_f32_16x16x32_bf16 v[64:67], v[168:171], v[208:211], v[64:67]
	v_mfma_f32_16x16x32_bf16 v[116:119], v[164:167], v[180:183], v[116:119]
	v_mfma_f32_16x16x32_bf16 v[112:115], v[172:175], v[180:183], v[112:115]
	v_mfma_f32_16x16x32_bf16 v[100:103], v[164:167], v[196:199], v[100:103]
	v_mfma_f32_16x16x32_bf16 v[92:95], v[172:175], v[196:199], v[92:95]
	v_mfma_f32_16x16x32_bf16 v[84:87], v[164:167], v[204:207], v[84:87]
	v_mfma_f32_16x16x32_bf16 v[76:79], v[172:175], v[204:207], v[76:79]
	v_mfma_f32_16x16x32_bf16 v[68:71], v[164:167], v[212:215], v[68:71]
	v_mfma_f32_16x16x32_bf16 v[64:67], v[172:175], v[212:215], v[64:67]
	s_add_i32 s36, s54, s41
	v_lshl_add_u64 v[216:217], v[216:217], 0, s[28:29]
	s_mov_b32 m0, s36
	s_barrier
	ds_read_b128 v[176:179], v159 offset:49152
	ds_read_b128 v[180:183], v159 offset:50176
	ds_read_b128 v[188:191], v159 offset:51200
	ds_read_b128 v[196:199], v159 offset:52224
	ds_read_b128 v[200:203], v159 offset:53248
	ds_read_b128 v[204:207], v159 offset:54272
	ds_read_b128 v[208:211], v159 offset:55296
	ds_read_b128 v[212:215], v159 offset:56320
	global_load_lds_dwordx4 v[216:217], off
	s_add_i32 m0, s36, 0x2000
	s_add_u32 s34, s34, 0x80080
	v_lshl_add_u64 v[216:217], v[218:219], 0, s[28:29]
	s_addc_u32 s35, s35, 0
	s_add_i32 s36, s55, s41
	global_load_lds_dwordx4 v[216:217], off
	s_mov_b32 m0, s36
	v_lshl_add_u64 v[216:217], s[34:35], 0, v[184:185]
	global_load_lds_dwordx4 v[216:217], off
	s_add_i32 m0, s36, 0x2000
	v_lshl_add_u64 v[216:217], s[34:35], 0, v[136:137]
	global_load_lds_dwordx4 v[216:217], off
	s_mov_b32 m0, s45
	v_lshl_add_u64 v[216:217], v[220:221], 0, s[28:29]
	global_load_lds_dwordx4 v[216:217], off
	s_mov_b32 m0, s46
	v_lshl_add_u64 v[216:217], v[222:223], 0, s[28:29]
	global_load_lds_dwordx4 v[216:217], off
	s_waitcnt vmcnt(8) lgkmcnt(0)
	s_barrier
	v_mfma_f32_16x16x32_bf16 v[60:63], v[128:131], v[176:179], v[60:63]
	v_mfma_f32_16x16x32_bf16 v[56:59], v[146:149], v[176:179], v[56:59]
	v_mfma_f32_16x16x32_bf16 v[48:51], v[128:131], v[188:191], v[48:51]
	v_mfma_f32_16x16x32_bf16 v[40:43], v[146:149], v[188:191], v[40:43]
	v_mfma_f32_16x16x32_bf16 v[32:35], v[128:131], v[200:203], v[32:35]
	v_mfma_f32_16x16x32_bf16 v[24:27], v[146:149], v[200:203], v[24:27]
	v_mfma_f32_16x16x32_bf16 v[16:19], v[128:131], v[208:211], v[16:19]
	v_mfma_f32_16x16x32_bf16 v[8:11], v[146:149], v[208:211], v[8:11]
	v_mfma_f32_16x16x32_bf16 v[60:63], v[142:145], v[180:183], v[60:63]
	v_mfma_f32_16x16x32_bf16 v[56:59], v[150:153], v[180:183], v[56:59]
	v_mfma_f32_16x16x32_bf16 v[48:51], v[142:145], v[196:199], v[48:51]
	v_mfma_f32_16x16x32_bf16 v[40:43], v[150:153], v[196:199], v[40:43]
	v_mfma_f32_16x16x32_bf16 v[32:35], v[142:145], v[204:207], v[32:35]
	v_mfma_f32_16x16x32_bf16 v[24:27], v[150:153], v[204:207], v[24:27]
	v_mfma_f32_16x16x32_bf16 v[16:19], v[142:145], v[212:215], v[16:19]
	v_mfma_f32_16x16x32_bf16 v[8:11], v[150:153], v[212:215], v[8:11]
	v_mfma_f32_16x16x32_bf16 v[52:55], v[160:163], v[176:179], v[52:55]
	v_mfma_f32_16x16x32_bf16 v[44:47], v[168:171], v[176:179], v[44:47]
	v_mfma_f32_16x16x32_bf16 v[36:39], v[160:163], v[188:191], v[36:39]
	v_mfma_f32_16x16x32_bf16 v[28:31], v[168:171], v[188:191], v[28:31]
	v_mfma_f32_16x16x32_bf16 v[20:23], v[160:163], v[200:203], v[20:23]
	v_mfma_f32_16x16x32_bf16 v[12:15], v[168:171], v[200:203], v[12:15]
	v_mfma_f32_16x16x32_bf16 v[4:7], v[160:163], v[208:211], v[4:7]
	v_mfma_f32_16x16x32_bf16 v[0:3], v[168:171], v[208:211], v[0:3]
	v_mfma_f32_16x16x32_bf16 v[52:55], v[164:167], v[180:183], v[52:55]
	v_mfma_f32_16x16x32_bf16 v[44:47], v[172:175], v[180:183], v[44:47]
	v_mfma_f32_16x16x32_bf16 v[36:39], v[164:167], v[196:199], v[36:39]
	v_mfma_f32_16x16x32_bf16 v[28:31], v[172:175], v[196:199], v[28:31]
	v_mfma_f32_16x16x32_bf16 v[20:23], v[164:167], v[204:207], v[20:23]
	v_mfma_f32_16x16x32_bf16 v[12:15], v[172:175], v[204:207], v[12:15]
	v_mfma_f32_16x16x32_bf16 v[4:7], v[164:167], v[212:215], v[4:7]
	v_mfma_f32_16x16x32_bf16 v[0:3], v[172:175], v[212:215], v[0:3]
	s_add_i32 s53, s53, 2
	s_add_u32 s30, s30, 0x100
	s_addc_u32 s31, s31, 0
	s_add_u32 s19, s19, 0x100
	s_addc_u32 s52, s52, 0
	s_cmp_gt_u32 s53, 29
	s_barrier
	s_cbranch_scc0 .LBB0_1299
	s_and_b64 vcc, exec, s[12:13]
	s_cbranch_vccz .LBB0_1302
	s_barrier

;     DI bool next(int i, Unit& u) const { const long L = (long)i * G + c; if (L >= T.nwg) return false; T.map((int)L, u.pm, u.pn); u.seg = 0; return true; }
;     DI bool next(int i, Unit& u) const { const int ti = i / 3; const long L = (long)ti * G + c; if (L >= T.nwg) return false; T.map((int)L, u.pm, u.pn); u.seg = i - 3 * ti; return true; }
;     DI const char* aptr(const Unit& u) const { return A + (size_t)u.pm * ta + (size_t)kofs(u.seg) * 2; }
;     DI const char* bptr(const Unit& u) const { return B + (size_t)u.pn * tb + (size_t)kofs(u.seg) * 2; }
; #define PG8_WAIT_V(n) asm volatile("s_waitcnt vmcnt(" #n ")" ::: "memory")
; #define PG8_BAR __builtin_amdgcn_s_barrier()
; template <class Epi, class Sched>
; DI void gemm_phase(LAS unsigned char* lds, const int wv, const int lda, const int ldb, const Sched& S, const Epi& E) {
;     ...
;         const bool has_next = S.next(ui + 1, nxt);
;         const char* nA = has_next ? S.aptr(nxt) : cA; const char* nB = has_next ? S.bptr(nxt) : cB;
;         for (int t = 0; t < nt; t += 2) {
;             const bool last = (t == nt - 2);
;             const char* a1 = cA + (size_t)(t + 1) * kstep;
;             const char* a2 = last ? nA : cA + (size_t)(t + 2) * kstep; const char* b2 = last ? nB : cB + (size_t)(t + 2) * kstep;
;             const char* a3 = a2 + kstep; const char* b3 = b2 + kstep;
;             PG8_LDB(B0, 0, 0); PG8_LDB(B1, 0, 1); PG8_SCHED; PG8_LDA(At, 0, 0); PG8_STAGE(PG8_SA(1, 1), a1 + hstepA, voffA);
;             PG8_WAIT_V(8); PG8_WAIT_L(0); PG8_BAR; PG8_MMA(0, 0, At, B0); PG8_MMA(0, 1, At, B1); PG8_BAR; PG8_SCHED;
;             PG8_LDA(At, 0, 1); PG8_STAGE(PG8_SB(0, 0), b2, voffB); PG8_STAGE(PG8_SB(0, 1), b2 + hstepB, voffB); PG8_STAGE(PG8_SA(0, 0), a2, voffA);
;             PG8_WAIT_V(8); PG8_WAIT_L(0); PG8_BAR; PG8_MMA(1, 0, At, B0); PG8_MMA(1, 1, At, B1); PG8_BAR; PG8_SCHED;
;             PG8_LDB(B0, 1, 0); PG8_LDB(B1, 1, 1); PG8_SCHED; PG8_LDA(At, 1, 0); PG8_STAGE(PG8_SA(0, 1), a2 + hstepA, voffA);
;             PG8_WAIT_V(8); PG8_WAIT_L(0); PG8_BAR; PG8_MMA(0, 0, At, B0); PG8_MMA(0, 1, At, B1); PG8_BAR; PG8_SCHED;
;             PG8_LDA(At, 1, 1); PG8_STAGE(PG8_SB(1, 0), b3, voffB); PG8_STAGE(PG8_SB(1, 1), b3 + hstepB, voffB); PG8_STAGE(PG8_SA(1, 0), a3, voffA);
;             PG8_WAIT_V(8); PG8_WAIT_L(0); PG8_BAR; PG8_MMA(1, 0, At, B0); PG8_MMA(1, 1, At, B1); PG8_BAR; PG8_SCHED;
.LBB0_1396:
	s_ashr_i32 s15, s14, 31
	s_lshl_b64 s[0:1], s[14:15], 20
	s_add_u32 s18, s8, s0
	s_addc_u32 s19, s9, s1
	s_and_b64 s[0:1], s[4:5], exec
	s_cselect_b32 s0, s19, s27
	s_cselect_b32 s1, s18, s26
	s_ashr_i32 s13, s12, 31
	s_lshl_b64 s[22:23], s[12:13], 20
	s_add_u32 s22, s36, s22
	s_addc_u32 s23, s37, s23
	s_and_b64 s[34:35], s[4:5], exec
	s_cselect_b32 s13, s23, s31
	s_cselect_b32 s15, s22, s30
	s_add_u32 s26, s26, 0x80080
	s_addc_u32 s27, s27, 0
	s_add_u32 s48, s30, 0x100
	s_addc_u32 s49, s31, 0
	s_mov_b32 s50, -2
	s_add_u32 s30, s26, 0xfff80080
	s_addc_u32 s31, s27, -1
	s_add_i32 s51, 0, 0x10000
	s_cmp_eq_u32 s50, 28
	s_cselect_b32 s35, s0, s31
	s_cselect_b32 s34, s1, s30
	v_add_u32_e32 v142, s51, v145
	s_cselect_b32 s31, s13, s49
	s_cselect_b32 s30, s15, s48
	s_add_i32 s54, 0, 0x14000
	ds_read_b128 v[138:141], v142
	ds_read_b128 v[148:151], v142 offset:1024
	ds_read_b128 v[152:155], v142 offset:2048
	ds_read_b128 v[156:159], v142 offset:3072
	v_add_u32_e32 v142, s54, v145
	ds_read_b128 v[160:163], v142
	ds_read_b128 v[164:167], v142 offset:1024
	ds_read_b128 v[168:171], v142 offset:2048
	ds_read_b128 v[172:175], v142 offset:3072
	v_lshl_add_u64 v[142:143], s[26:27], 0, v[134:135]
	s_add_i32 m0, s25, 0xc000
	ds_read_b128 v[176:179], v147
	ds_read_b128 v[180:183], v147 offset:1024
	ds_read_b128 v[188:191], v147 offset:2048
	ds_read_b128 v[196:199], v147 offset:3072
	ds_read_b128 v[200:203], v147 offset:4096
	ds_read_b128 v[204:207], v147 offset:5120
	ds_read_b128 v[208:211], v147 offset:6144
	ds_read_b128 v[212:215], v147 offset:7168
	global_load_lds_dwordx4 v[142:143], off
	s_add_i32 m0, s25, 0xe000
	v_lshl_add_u64 v[142:143], s[26:27], 0, v[136:137]
	global_load_lds_dwordx4 v[142:143], off
	s_waitcnt vmcnt(8) lgkmcnt(0)
	s_barrier
	v_mfma_f32_16x16x32_bf16 v[124:127], v[138:141], v[176:179], 0
	v_mfma_f32_16x16x32_bf16 v[120:123], v[152:155], v[176:179], 0
	v_mfma_f32_16x16x32_bf16 v[108:111], v[138:141], v[188:191], 0
	v_mfma_f32_16x16x32_bf16 v[104:107], v[152:155], v[188:191], 0
	v_mfma_f32_16x16x32_bf16 v[92:95], v[138:141], v[200:203], 0
	v_mfma_f32_16x16x32_bf16 v[88:91], v[152:155], v[200:203], 0
	v_mfma_f32_16x16x32_bf16 v[76:79], v[138:141], v[208:211], 0
	v_mfma_f32_16x16x32_bf16 v[72:75], v[152:155], v[208:211], 0
	v_mfma_f32_16x16x32_bf16 v[124:127], v[148:151], v[180:183], v[124:127]
	v_mfma_f32_16x16x32_bf16 v[120:123], v[156:159], v[180:183], v[120:123]
	v_mfma_f32_16x16x32_bf16 v[108:111], v[148:151], v[196:199], v[108:111]
	v_mfma_f32_16x16x32_bf16 v[104:107], v[156:159], v[196:199], v[104:107]
	v_mfma_f32_16x16x32_bf16 v[92:95], v[148:151], v[204:207], v[92:95]
	v_mfma_f32_16x16x32_bf16 v[88:91], v[156:159], v[204:207], v[88:91]
	v_mfma_f32_16x16x32_bf16 v[76:79], v[148:151], v[212:215], v[76:79]
	v_mfma_f32_16x16x32_bf16 v[72:75], v[156:159], v[212:215], v[72:75]
	v_mfma_f32_16x16x32_bf16 v[116:119], v[160:163], v[176:179], 0
	v_mfma_f32_16x16x32_bf16 v[112:115], v[168:171], v[176:179], 0
	v_mfma_f32_16x16x32_bf16 v[100:103], v[160:163], v[188:191], 0
	v_mfma_f32_16x16x32_bf16 v[96:99], v[168:171], v[188:191], 0
	v_mfma_f32_16x16x32_bf16 v[84:87], v[160:163], v[200:203], 0
	v_mfma_f32_16x16x32_bf16 v[80:83], v[168:171], v[200:203], 0
	v_mfma_f32_16x16x32_bf16 v[68:71], v[160:163], v[208:211], 0
	v_mfma_f32_16x16x32_bf16 v[64:67], v[168:171], v[208:211], 0
	v_mfma_f32_16x16x32_bf16 v[116:119], v[164:167], v[180:183], v[116:119]
	v_mfma_f32_16x16x32_bf16 v[112:115], v[172:175], v[180:183], v[112:115]
	v_mfma_f32_16x16x32_bf16 v[100:103], v[164:167], v[196:199], v[100:103]
	v_mfma_f32_16x16x32_bf16 v[96:99], v[172:175], v[196:199], v[96:99]
	v_mfma_f32_16x16x32_bf16 v[84:87], v[164:167], v[204:207], v[84:87]
	v_mfma_f32_16x16x32_bf16 v[80:83], v[172:175], v[204:207], v[80:83]
	v_mfma_f32_16x16x32_bf16 v[68:71], v[164:167], v[212:215], v[68:71]
	v_mfma_f32_16x16x32_bf16 v[64:67], v[172:175], v[212:215], v[64:67]
	s_add_i32 s51, s51, s38
	v_lshl_add_u64 v[142:143], s[30:31], 0, v[184:185]
	s_mov_b32 m0, s51
	s_barrier
	ds_read_b128 v[176:179], v147 offset:16384
	ds_read_b128 v[180:183], v147 offset:17408
	ds_read_b128 v[188:191], v147 offset:18432
	ds_read_b128 v[196:199], v147 offset:19456
	ds_read_b128 v[200:203], v147 offset:20480
	ds_read_b128 v[204:207], v147 offset:21504
	ds_read_b128 v[208:211], v147 offset:22528
	ds_read_b128 v[212:215], v147 offset:23552
	global_load_lds_dwordx4 v[142:143], off
	s_add_i32 m0, s51, 0x2000
	s_add_u32 s52, s30, 0x80000
	v_lshl_add_u64 v[216:217], s[30:31], 0, v[132:133]
	s_addc_u32 s53, s31, 0
	s_add_i32 s51, s54, s38
	global_load_lds_dwordx4 v[216:217], off
	v_lshl_add_u64 v[218:219], s[52:53], 0, v[184:185]
	s_mov_b32 m0, s51
	v_lshl_add_u64 v[220:221], s[34:35], 0, v[130:131]
	global_load_lds_dwordx4 v[218:219], off
	s_add_i32 m0, s51, 0x2000
	v_lshl_add_u64 v[218:219], s[52:53], 0, v[132:133]
	global_load_lds_dwordx4 v[218:219], off
	s_mov_b32 m0, s25
	v_lshl_add_u64 v[218:219], s[34:35], 0, v[128:129]
	global_load_lds_dwordx4 v[218:219], off
	s_mov_b32 m0, s39
	s_nop 0
	global_load_lds_dwordx4 v[220:221], off
	s_waitcnt vmcnt(8) lgkmcnt(0)
	s_barrier
; #define PG8_STAGE(bufoff, gbase, voff) do { _Pragma("unroll") for (int _i = 0; _i < 2; ++_i) \
;         __builtin_amdgcn_global_load_lds((const unsigned*)((const char*)(gbase) + (voff)[_i]), (LAS unsigned*)(lds + (bufoff) + ldsw + _i * 8192), 16, 0, 0); } while (0)
; #define PG8_LDA(dst, b, h) do { _Pragma("unroll") for (int m = 0; m < 4; ++m) _Pragma("unroll") for (int k = 0; k < 2; ++k) dst[m][k] = *(const LAS bf16x8*)(lds + PG8_SA(b, h) + aoff + m * 2048 + k * 1024); } while (0)
; #define PG8_LDB(dst, b, h) do { _Pragma("unroll") for (int n = 0; n < 2; ++n) _Pragma("unroll") for (int k = 0; k < 2; ++k) dst[n][k] = *(const LAS bf16x8*)(lds + PG8_SB(b, h) + boff + n * 2048 + k * 1024); } while (0)
; #define PG8_MMA(ai, bj, At, Bt) do { __builtin_amdgcn_s_setprio(1); _Pragma("unroll") for (int m = 0; m < 4; ++m) _Pragma("unroll") for (int n = 0; n < 2; ++n) _Pragma("unroll") for (int k = 0; k < 2; ++k) \
;         acc[ai][bj][m][n] = __builtin_amdgcn_mfma_f32_16x16x32_bf16(Bt[n][k], At[m][k], acc[ai][bj][m][n], 0, 0, 0); __builtin_amdgcn_s_setprio(0); } while (0)
; #define PG8_WAIT_V(n) asm volatile("s_waitcnt vmcnt(" #n ")" ::: "memory")
; #define PG8_WAIT_L(n) asm volatile("s_waitcnt lgkmcnt(" #n ")" ::: "memory")
; #define PG8_BAR __builtin_amdgcn_s_barrier()
; #define PG8_SCHED __builtin_amdgcn_sched_barrier(0)
; template <class Epi, class Sched>
; DI void gemm_phase(LAS unsigned char* lds, const int wv, const int lda, const int ldb, const Sched& S, const Epi& E) {
;     ...
;             PG8_WAIT_V(8); PG8_WAIT_L(0); PG8_BAR; PG8_MMA(0, 0, At, B0); PG8_MMA(0, 1, At, B1); PG8_BAR; PG8_SCHED;
;             PG8_LDA(At, 0, 1); PG8_STAGE(PG8_SB(0, 0), b2, voffB); PG8_STAGE(PG8_SB(0, 1), b2 + hstepB, voffB); PG8_STAGE(PG8_SA(0, 0), a2, voffA);
;             PG8_WAIT_V(8); PG8_WAIT_L(0); PG8_BAR; PG8_MMA(1, 0, At, B0); PG8_MMA(1, 1, At, B1); PG8_BAR; PG8_SCHED;
;             PG8_LDB(B0, 1, 0); PG8_LDB(B1, 1, 1); PG8_SCHED; PG8_LDA(At, 1, 0); PG8_STAGE(PG8_SA(0, 1), a2 + hstepA, voffA);
;             PG8_WAIT_V(8); PG8_WAIT_L(0); PG8_BAR; PG8_MMA(0, 0, At, B0); PG8_MMA(0, 1, At, B1); PG8_BAR; PG8_SCHED;
	v_mfma_f32_16x16x32_bf16 v[60:63], v[138:141], v[176:179], 0
	v_mfma_f32_16x16x32_bf16 v[56:59], v[152:155], v[176:179], 0
	v_mfma_f32_16x16x32_bf16 v[44:47], v[138:141], v[188:191], 0
	v_mfma_f32_16x16x32_bf16 v[40:43], v[152:155], v[188:191], 0
	v_mfma_f32_16x16x32_bf16 v[28:31], v[138:141], v[200:203], 0
	v_mfma_f32_16x16x32_bf16 v[24:27], v[152:155], v[200:203], 0
	v_mfma_f32_16x16x32_bf16 v[12:15], v[138:141], v[208:211], 0
	v_mfma_f32_16x16x32_bf16 v[8:11], v[152:155], v[208:211], 0
	v_mfma_f32_16x16x32_bf16 v[60:63], v[148:151], v[180:183], v[60:63]
	v_mfma_f32_16x16x32_bf16 v[56:59], v[156:159], v[180:183], v[56:59]
	v_mfma_f32_16x16x32_bf16 v[44:47], v[148:151], v[196:199], v[44:47]
	v_mfma_f32_16x16x32_bf16 v[40:43], v[156:159], v[196:199], v[40:43]
	v_mfma_f32_16x16x32_bf16 v[28:31], v[148:151], v[204:207], v[28:31]
	v_mfma_f32_16x16x32_bf16 v[24:27], v[156:159], v[204:207], v[24:27]
	v_mfma_f32_16x16x32_bf16 v[12:15], v[148:151], v[212:215], v[12:15]
	v_mfma_f32_16x16x32_bf16 v[8:11], v[156:159], v[212:215], v[8:11]
	v_mfma_f32_16x16x32_bf16 v[52:55], v[160:163], v[176:179], 0
	v_mfma_f32_16x16x32_bf16 v[48:51], v[168:171], v[176:179], 0
	v_mfma_f32_16x16x32_bf16 v[36:39], v[160:163], v[188:191], 0
	v_mfma_f32_16x16x32_bf16 v[32:35], v[168:171], v[188:191], 0
	v_mfma_f32_16x16x32_bf16 v[20:23], v[160:163], v[200:203], 0
	v_mfma_f32_16x16x32_bf16 v[16:19], v[168:171], v[200:203], 0
	v_mfma_f32_16x16x32_bf16 v[4:7], v[160:163], v[208:211], 0
	v_mfma_f32_16x16x32_bf16 v[0:3], v[168:171], v[208:211], 0
	v_mfma_f32_16x16x32_bf16 v[52:55], v[164:167], v[180:183], v[52:55]
	v_mfma_f32_16x16x32_bf16 v[48:51], v[172:175], v[180:183], v[48:51]
	v_mfma_f32_16x16x32_bf16 v[36:39], v[164:167], v[196:199], v[36:39]
	v_mfma_f32_16x16x32_bf16 v[32:35], v[172:175], v[196:199], v[32:35]
	v_mfma_f32_16x16x32_bf16 v[20:23], v[164:167], v[204:207], v[20:23]
	v_mfma_f32_16x16x32_bf16 v[16:19], v[172:175], v[204:207], v[16:19]
	v_mfma_f32_16x16x32_bf16 v[4:7], v[164:167], v[212:215], v[4:7]
	v_mfma_f32_16x16x32_bf16 v[0:3], v[172:175], v[212:215], v[0:3]
	s_add_i32 s51, 0, 0x18000
	s_add_i32 s52, 0, 0x1c000
	s_barrier
	v_add_u32_e32 v156, s51, v145
	v_add_u32_e32 v172, s52, v145
	ds_read_b128 v[138:141], v156
	ds_read_b128 v[148:151], v156 offset:1024
	ds_read_b128 v[152:155], v156 offset:2048
	ds_read_b128 v[156:159], v156 offset:3072
	ds_read_b128 v[160:163], v172
	ds_read_b128 v[164:167], v172 offset:1024
	ds_read_b128 v[168:171], v172 offset:2048
	ds_read_b128 v[172:175], v172 offset:3072
	s_add_u32 s34, s34, 0x80000
	s_addc_u32 s35, s35, 0
	s_mov_b32 m0, s40
	v_lshl_add_u64 v[222:223], s[34:35], 0, v[128:129]
	ds_read_b128 v[176:179], v147 offset:32768
	ds_read_b128 v[180:183], v147 offset:33792
	ds_read_b128 v[188:191], v147 offset:34816
	ds_read_b128 v[196:199], v147 offset:35840
	ds_read_b128 v[200:203], v147 offset:36864
	ds_read_b128 v[204:207], v147 offset:37888
	ds_read_b128 v[208:211], v147 offset:38912
	ds_read_b128 v[212:215], v147 offset:39936
	global_load_lds_dwordx4 v[222:223], off
	s_mov_b32 m0, s41
	v_lshl_add_u64 v[222:223], s[34:35], 0, v[130:131]
	global_load_lds_dwordx4 v[222:223], off
	s_waitcnt vmcnt(8) lgkmcnt(0)
	s_barrier
	v_mfma_f32_16x16x32_bf16 v[124:127], v[138:141], v[176:179], v[124:127]
	v_mfma_f32_16x16x32_bf16 v[120:123], v[152:155], v[176:179], v[120:123]
	v_mfma_f32_16x16x32_bf16 v[108:111], v[138:141], v[188:191], v[108:111]
	v_mfma_f32_16x16x32_bf16 v[104:107], v[152:155], v[188:191], v[104:107]
	v_mfma_f32_16x16x32_bf16 v[92:95], v[138:141], v[200:203], v[92:95]
	v_mfma_f32_16x16x32_bf16 v[88:91], v[152:155], v[200:203], v[88:91]
	v_mfma_f32_16x16x32_bf16 v[76:79], v[138:141], v[208:211], v[76:79]
	v_mfma_f32_16x16x32_bf16 v[72:75], v[152:155], v[208:211], v[72:75]
	v_mfma_f32_16x16x32_bf16 v[124:127], v[148:151], v[180:183], v[124:127]
	v_mfma_f32_16x16x32_bf16 v[120:123], v[156:159], v[180:183], v[120:123]
	v_mfma_f32_16x16x32_bf16 v[108:111], v[148:151], v[196:199], v[108:111]
	v_mfma_f32_16x16x32_bf16 v[104:107], v[156:159], v[196:199], v[104:107]
	v_mfma_f32_16x16x32_bf16 v[92:95], v[148:151], v[204:207], v[92:95]
	v_mfma_f32_16x16x32_bf16 v[88:91], v[156:159], v[204:207], v[88:91]
	v_mfma_f32_16x16x32_bf16 v[76:79], v[148:151], v[212:215], v[76:79]
	v_mfma_f32_16x16x32_bf16 v[72:75], v[156:159], v[212:215], v[72:75]
	v_mfma_f32_16x16x32_bf16 v[116:119], v[160:163], v[176:179], v[116:119]
	v_mfma_f32_16x16x32_bf16 v[112:115], v[168:171], v[176:179], v[112:115]
	v_mfma_f32_16x16x32_bf16 v[100:103], v[160:163], v[188:191], v[100:103]
	v_mfma_f32_16x16x32_bf16 v[96:99], v[168:171], v[188:191], v[96:99]
	v_mfma_f32_16x16x32_bf16 v[84:87], v[160:163], v[200:203], v[84:87]
	v_mfma_f32_16x16x32_bf16 v[80:83], v[168:171], v[200:203], v[80:83]
	v_mfma_f32_16x16x32_bf16 v[68:71], v[160:163], v[208:211], v[68:71]
	v_mfma_f32_16x16x32_bf16 v[64:67], v[168:171], v[208:211], v[64:67]
	v_mfma_f32_16x16x32_bf16 v[116:119], v[164:167], v[180:183], v[116:119]
	v_mfma_f32_16x16x32_bf16 v[112:115], v[172:175], v[180:183], v[112:115]
	v_mfma_f32_16x16x32_bf16 v[100:103], v[164:167], v[196:199], v[100:103]
	v_mfma_f32_16x16x32_bf16 v[96:99], v[172:175], v[196:199], v[96:99]
	v_mfma_f32_16x16x32_bf16 v[84:87], v[164:167], v[204:207], v[84:87]
	v_mfma_f32_16x16x32_bf16 v[80:83], v[172:175], v[204:207], v[80:83]
	v_mfma_f32_16x16x32_bf16 v[68:71], v[164:167], v[212:215], v[68:71]
	v_mfma_f32_16x16x32_bf16 v[64:67], v[172:175], v[212:215], v[64:67]
	s_add_i32 s34, s51, s38
	v_lshl_add_u64 v[142:143], v[142:143], 0, s[28:29]
	s_mov_b32 m0, s34
	s_barrier
; #define PG8_STAGE(bufoff, gbase, voff) do { _Pragma("unroll") for (int _i = 0; _i < 2; ++_i) \
;         __builtin_amdgcn_global_load_lds((const unsigned*)((const char*)(gbase) + (voff)[_i]), (LAS unsigned*)(lds + (bufoff) + ldsw + _i * 8192), 16, 0, 0); } while (0)
; #define PG8_LDA(dst, b, h) do { _Pragma("unroll") for (int m = 0; m < 4; ++m) _Pragma("unroll") for (int k = 0; k < 2; ++k) dst[m][k] = *(const LAS bf16x8*)(lds + PG8_SA(b, h) + aoff + m * 2048 + k * 1024); } while (0)
; #define PG8_LDB(dst, b, h) do { _Pragma("unroll") for (int n = 0; n < 2; ++n) _Pragma("unroll") for (int k = 0; k < 2; ++k) dst[n][k] = *(const LAS bf16x8*)(lds + PG8_SB(b, h) + boff + n * 2048 + k * 1024); } while (0)
; #define PG8_MMA(ai, bj, At, Bt) do { __builtin_amdgcn_s_setprio(1); _Pragma("unroll") for (int m = 0; m < 4; ++m) _Pragma("unroll") for (int n = 0; n < 2; ++n) _Pragma("unroll") for (int k = 0; k < 2; ++k) \
;         acc[ai][bj][m][n] = __builtin_amdgcn_mfma_f32_16x16x32_bf16(Bt[n][k], At[m][k], acc[ai][bj][m][n], 0, 0, 0); __builtin_amdgcn_s_setprio(0); } while (0)
; #define PG8_WAIT_V(n) asm volatile("s_waitcnt vmcnt(" #n ")" ::: "memory")
; #define PG8_WAIT_L(n) asm volatile("s_waitcnt lgkmcnt(" #n ")" ::: "memory")
; template <class Epi, class Sched>
; DI void gemm_phase(LAS unsigned char* lds, const int wv, const int lda, const int ldb, const Sched& S, const Epi& E) {
;     ...
;         for (int t = 0; t < nt; t += 2) {
;             const bool last = (t == nt - 2);
;             const char* a1 = cA + (size_t)(t + 1) * kstep;
;             const char* a2 = last ? nA : cA + (size_t)(t + 2) * kstep; const char* b2 = last ? nB : cB + (size_t)(t + 2) * kstep;
;             const char* a3 = a2 + kstep; const char* b3 = b2 + kstep;
;             PG8_LDB(B0, 0, 0); PG8_LDB(B1, 0, 1); PG8_SCHED; PG8_LDA(At, 0, 0); PG8_STAGE(PG8_SA(1, 1), a1 + hstepA, voffA);
;             PG8_WAIT_V(8); PG8_WAIT_L(0); PG8_BAR; PG8_MMA(0, 0, At, B0); PG8_MMA(0, 1, At, B1); PG8_BAR; PG8_SCHED;
;     ...
;             PG8_WAIT_V(8); PG8_WAIT_L(0); PG8_BAR; PG8_MMA(0, 0, At, B0); PG8_MMA(0, 1, At, B1); PG8_BAR; PG8_SCHED;
;             PG8_LDA(At, 1, 1); PG8_STAGE(PG8_SB(1, 0), b3, voffB); PG8_STAGE(PG8_SB(1, 1), b3 + hstepB, voffB); PG8_STAGE(PG8_SA(1, 0), a3, voffA);
;             PG8_WAIT_V(8); PG8_WAIT_L(0); PG8_BAR; PG8_MMA(1, 0, At, B0); PG8_MMA(1, 1, At, B1); PG8_BAR; PG8_SCHED;
	ds_read_b128 v[176:179], v147 offset:49152
	ds_read_b128 v[180:183], v147 offset:50176
	ds_read_b128 v[188:191], v147 offset:51200
	ds_read_b128 v[196:199], v147 offset:52224
	ds_read_b128 v[200:203], v147 offset:53248
	ds_read_b128 v[204:207], v147 offset:54272
	ds_read_b128 v[208:211], v147 offset:55296
	ds_read_b128 v[212:215], v147 offset:56320
	global_load_lds_dwordx4 v[142:143], off
	s_add_i32 m0, s34, 0x2000
	s_add_u32 s30, s30, 0x80080
	v_lshl_add_u64 v[142:143], v[216:217], 0, s[28:29]
	s_addc_u32 s31, s31, 0
	s_add_i32 s34, s52, s38
	global_load_lds_dwordx4 v[142:143], off
	s_mov_b32 m0, s34
	v_lshl_add_u64 v[142:143], s[30:31], 0, v[184:185]
	global_load_lds_dwordx4 v[142:143], off
	s_add_i32 m0, s34, 0x2000
	v_lshl_add_u64 v[142:143], s[30:31], 0, v[132:133]
	global_load_lds_dwordx4 v[142:143], off
	s_mov_b32 m0, s43
	v_lshl_add_u64 v[142:143], v[218:219], 0, s[28:29]
	global_load_lds_dwordx4 v[142:143], off
	s_mov_b32 m0, s44
	v_lshl_add_u64 v[142:143], v[220:221], 0, s[28:29]
	global_load_lds_dwordx4 v[142:143], off
	s_waitcnt vmcnt(8) lgkmcnt(0)
	s_barrier
	v_mfma_f32_16x16x32_bf16 v[60:63], v[138:141], v[176:179], v[60:63]
	v_mfma_f32_16x16x32_bf16 v[56:59], v[152:155], v[176:179], v[56:59]
	v_mfma_f32_16x16x32_bf16 v[44:47], v[138:141], v[188:191], v[44:47]
	v_mfma_f32_16x16x32_bf16 v[40:43], v[152:155], v[188:191], v[40:43]
	v_mfma_f32_16x16x32_bf16 v[28:31], v[138:141], v[200:203], v[28:31]
	v_mfma_f32_16x16x32_bf16 v[24:27], v[152:155], v[200:203], v[24:27]
	v_mfma_f32_16x16x32_bf16 v[12:15], v[138:141], v[208:211], v[12:15]
	v_mfma_f32_16x16x32_bf16 v[8:11], v[152:155], v[208:211], v[8:11]
	v_mfma_f32_16x16x32_bf16 v[60:63], v[148:151], v[180:183], v[60:63]
	v_mfma_f32_16x16x32_bf16 v[56:59], v[156:159], v[180:183], v[56:59]
	v_mfma_f32_16x16x32_bf16 v[44:47], v[148:151], v[196:199], v[44:47]
	v_mfma_f32_16x16x32_bf16 v[40:43], v[156:159], v[196:199], v[40:43]
	v_mfma_f32_16x16x32_bf16 v[28:31], v[148:151], v[204:207], v[28:31]
	v_mfma_f32_16x16x32_bf16 v[24:27], v[156:159], v[204:207], v[24:27]
	v_mfma_f32_16x16x32_bf16 v[12:15], v[148:151], v[212:215], v[12:15]
	v_mfma_f32_16x16x32_bf16 v[8:11], v[156:159], v[212:215], v[8:11]
	v_mfma_f32_16x16x32_bf16 v[52:55], v[160:163], v[176:179], v[52:55]
	v_mfma_f32_16x16x32_bf16 v[48:51], v[168:171], v[176:179], v[48:51]
	v_mfma_f32_16x16x32_bf16 v[36:39], v[160:163], v[188:191], v[36:39]
	v_mfma_f32_16x16x32_bf16 v[32:35], v[168:171], v[188:191], v[32:35]
	v_mfma_f32_16x16x32_bf16 v[20:23], v[160:163], v[200:203], v[20:23]
	v_mfma_f32_16x16x32_bf16 v[16:19], v[168:171], v[200:203], v[16:19]
	v_mfma_f32_16x16x32_bf16 v[4:7], v[160:163], v[208:211], v[4:7]
	v_mfma_f32_16x16x32_bf16 v[0:3], v[168:171], v[208:211], v[0:3]
	v_mfma_f32_16x16x32_bf16 v[52:55], v[164:167], v[180:183], v[52:55]
	v_mfma_f32_16x16x32_bf16 v[48:51], v[172:175], v[180:183], v[48:51]
	v_mfma_f32_16x16x32_bf16 v[36:39], v[164:167], v[196:199], v[36:39]
	v_mfma_f32_16x16x32_bf16 v[32:35], v[172:175], v[196:199], v[32:35]
	v_mfma_f32_16x16x32_bf16 v[20:23], v[164:167], v[204:207], v[20:23]
	v_mfma_f32_16x16x32_bf16 v[16:19], v[172:175], v[204:207], v[16:19]
	v_mfma_f32_16x16x32_bf16 v[4:7], v[164:167], v[212:215], v[4:7]
	v_mfma_f32_16x16x32_bf16 v[0:3], v[172:175], v[212:215], v[0:3]
	s_add_i32 s50, s50, 2
	s_add_u32 s26, s26, 0x100
	s_addc_u32 s27, s27, 0
	s_add_u32 s48, s48, 0x100
	s_addc_u32 s49, s49, 0
	s_barrier
.LBB0_1397:
	s_add_u32 s30, s26, 0xfff80080
	s_addc_u32 s31, s27, -1
	s_add_i32 s51, 0, 0x10000
	s_cmp_eq_u32 s50, 28
	s_cselect_b32 s35, s0, s31
	s_cselect_b32 s34, s1, s30
	v_add_u32_e32 v142, s51, v145
	s_cselect_b32 s31, s13, s49
	s_cselect_b32 s30, s15, s48
	s_add_i32 s54, 0, 0x14000
	ds_read_b128 v[138:141], v142
	ds_read_b128 v[148:151], v142 offset:1024
	ds_read_b128 v[152:155], v142 offset:2048
	ds_read_b128 v[156:159], v142 offset:3072
	v_add_u32_e32 v142, s54, v145
	ds_read_b128 v[160:163], v142
	ds_read_b128 v[164:167], v142 offset:1024
	ds_read_b128 v[168:171], v142 offset:2048
	ds_read_b128 v[172:175], v142 offset:3072
	v_lshl_add_u64 v[142:143], s[26:27], 0, v[134:135]
	s_add_i32 m0, s25, 0xc000
	ds_read_b128 v[176:179], v147
	ds_read_b128 v[180:183], v147 offset:1024
	ds_read_b128 v[188:191], v147 offset:2048
	ds_read_b128 v[196:199], v147 offset:3072
	ds_read_b128 v[200:203], v147 offset:4096
	ds_read_b128 v[204:207], v147 offset:5120
	ds_read_b128 v[208:211], v147 offset:6144
	ds_read_b128 v[212:215], v147 offset:7168
	global_load_lds_dwordx4 v[142:143], off
	s_add_i32 m0, s25, 0xe000
	v_lshl_add_u64 v[142:143], s[26:27], 0, v[136:137]
	global_load_lds_dwordx4 v[142:143], off
	s_waitcnt vmcnt(8) lgkmcnt(0)
	s_barrier
; #define PG8_STAGE(bufoff, gbase, voff) do { _Pragma("unroll") for (int _i = 0; _i < 2; ++_i) \
;         __builtin_amdgcn_global_load_lds((const unsigned*)((const char*)(gbase) + (voff)[_i]), (LAS unsigned*)(lds + (bufoff) + ldsw + _i * 8192), 16, 0, 0); } while (0)
; #define PG8_LDA(dst, b, h) do { _Pragma("unroll") for (int m = 0; m < 4; ++m) _Pragma("unroll") for (int k = 0; k < 2; ++k) dst[m][k] = *(const LAS bf16x8*)(lds + PG8_SA(b, h) + aoff + m * 2048 + k * 1024); } while (0)
; #define PG8_LDB(dst, b, h) do { _Pragma("unroll") for (int n = 0; n < 2; ++n) _Pragma("unroll") for (int k = 0; k < 2; ++k) dst[n][k] = *(const LAS bf16x8*)(lds + PG8_SB(b, h) + boff + n * 2048 + k * 1024); } while (0)
; #define PG8_MMA(ai, bj, At, Bt) do { __builtin_amdgcn_s_setprio(1); _Pragma("unroll") for (int m = 0; m < 4; ++m) _Pragma("unroll") for (int n = 0; n < 2; ++n) _Pragma("unroll") for (int k = 0; k < 2; ++k) \
;         acc[ai][bj][m][n] = __builtin_amdgcn_mfma_f32_16x16x32_bf16(Bt[n][k], At[m][k], acc[ai][bj][m][n], 0, 0, 0); __builtin_amdgcn_s_setprio(0); } while (0)
; #define PG8_WAIT_V(n) asm volatile("s_waitcnt vmcnt(" #n ")" ::: "memory")
; #define PG8_WAIT_L(n) asm volatile("s_waitcnt lgkmcnt(" #n ")" ::: "memory")
; #define PG8_BAR __builtin_amdgcn_s_barrier()
; #define PG8_SCHED __builtin_amdgcn_sched_barrier(0)
; template <class Epi, class Sched>
; DI void gemm_phase(LAS unsigned char* lds, const int wv, const int lda, const int ldb, const Sched& S, const Epi& E) {
;     ...
;             PG8_WAIT_V(8); PG8_WAIT_L(0); PG8_BAR; PG8_MMA(0, 0, At, B0); PG8_MMA(0, 1, At, B1); PG8_BAR; PG8_SCHED;
;             PG8_LDA(At, 0, 1); PG8_STAGE(PG8_SB(0, 0), b2, voffB); PG8_STAGE(PG8_SB(0, 1), b2 + hstepB, voffB); PG8_STAGE(PG8_SA(0, 0), a2, voffA);
;             PG8_WAIT_V(8); PG8_WAIT_L(0); PG8_BAR; PG8_MMA(1, 0, At, B0); PG8_MMA(1, 1, At, B1); PG8_BAR; PG8_SCHED;
;             PG8_LDB(B0, 1, 0); PG8_LDB(B1, 1, 1); PG8_SCHED; PG8_LDA(At, 1, 0); PG8_STAGE(PG8_SA(0, 1), a2 + hstepA, voffA);
;             PG8_WAIT_V(8); PG8_WAIT_L(0); PG8_BAR; PG8_MMA(0, 0, At, B0); PG8_MMA(0, 1, At, B1); PG8_BAR; PG8_SCHED;
	v_mfma_f32_16x16x32_bf16 v[124:127], v[138:141], v[176:179], v[124:127]
	v_mfma_f32_16x16x32_bf16 v[120:123], v[152:155], v[176:179], v[120:123]
	v_mfma_f32_16x16x32_bf16 v[108:111], v[138:141], v[188:191], v[108:111]
	v_mfma_f32_16x16x32_bf16 v[104:107], v[152:155], v[188:191], v[104:107]
	v_mfma_f32_16x16x32_bf16 v[92:95], v[138:141], v[200:203], v[92:95]
	v_mfma_f32_16x16x32_bf16 v[88:91], v[152:155], v[200:203], v[88:91]
	v_mfma_f32_16x16x32_bf16 v[76:79], v[138:141], v[208:211], v[76:79]
	v_mfma_f32_16x16x32_bf16 v[72:75], v[152:155], v[208:211], v[72:75]
	v_mfma_f32_16x16x32_bf16 v[124:127], v[148:151], v[180:183], v[124:127]
	v_mfma_f32_16x16x32_bf16 v[120:123], v[156:159], v[180:183], v[120:123]
	v_mfma_f32_16x16x32_bf16 v[108:111], v[148:151], v[196:199], v[108:111]
	v_mfma_f32_16x16x32_bf16 v[104:107], v[156:159], v[196:199], v[104:107]
	v_mfma_f32_16x16x32_bf16 v[92:95], v[148:151], v[204:207], v[92:95]
	v_mfma_f32_16x16x32_bf16 v[88:91], v[156:159], v[204:207], v[88:91]
	v_mfma_f32_16x16x32_bf16 v[76:79], v[148:151], v[212:215], v[76:79]
	v_mfma_f32_16x16x32_bf16 v[72:75], v[156:159], v[212:215], v[72:75]
	v_mfma_f32_16x16x32_bf16 v[116:119], v[160:163], v[176:179], v[116:119]
	v_mfma_f32_16x16x32_bf16 v[112:115], v[168:171], v[176:179], v[112:115]
	v_mfma_f32_16x16x32_bf16 v[100:103], v[160:163], v[188:191], v[100:103]
	v_mfma_f32_16x16x32_bf16 v[96:99], v[168:171], v[188:191], v[96:99]
	v_mfma_f32_16x16x32_bf16 v[84:87], v[160:163], v[200:203], v[84:87]
	v_mfma_f32_16x16x32_bf16 v[80:83], v[168:171], v[200:203], v[80:83]
	v_mfma_f32_16x16x32_bf16 v[68:71], v[160:163], v[208:211], v[68:71]
	v_mfma_f32_16x16x32_bf16 v[64:67], v[168:171], v[208:211], v[64:67]
	v_mfma_f32_16x16x32_bf16 v[116:119], v[164:167], v[180:183], v[116:119]
	v_mfma_f32_16x16x32_bf16 v[112:115], v[172:175], v[180:183], v[112:115]
	v_mfma_f32_16x16x32_bf16 v[100:103], v[164:167], v[196:199], v[100:103]
	v_mfma_f32_16x16x32_bf16 v[96:99], v[172:175], v[196:199], v[96:99]
	v_mfma_f32_16x16x32_bf16 v[84:87], v[164:167], v[204:207], v[84:87]
	v_mfma_f32_16x16x32_bf16 v[80:83], v[172:175], v[204:207], v[80:83]
	v_mfma_f32_16x16x32_bf16 v[68:71], v[164:167], v[212:215], v[68:71]
	v_mfma_f32_16x16x32_bf16 v[64:67], v[172:175], v[212:215], v[64:67]
	s_add_i32 s51, s51, s38
	v_lshl_add_u64 v[142:143], s[30:31], 0, v[184:185]
	s_mov_b32 m0, s51
	s_barrier
	ds_read_b128 v[176:179], v147 offset:16384
	ds_read_b128 v[180:183], v147 offset:17408
	ds_read_b128 v[188:191], v147 offset:18432
	ds_read_b128 v[196:199], v147 offset:19456
	ds_read_b128 v[200:203], v147 offset:20480
	ds_read_b128 v[204:207], v147 offset:21504
	ds_read_b128 v[208:211], v147 offset:22528
	ds_read_b128 v[212:215], v147 offset:23552
	global_load_lds_dwordx4 v[142:143], off
	s_add_i32 m0, s51, 0x2000
	s_add_u32 s52, s30, 0x80000
	v_lshl_add_u64 v[216:217], s[30:31], 0, v[132:133]
	s_addc_u32 s53, s31, 0
	s_add_i32 s51, s54, s38
	global_load_lds_dwordx4 v[216:217], off
	v_lshl_add_u64 v[218:219], s[52:53], 0, v[184:185]
	s_mov_b32 m0, s51
	v_lshl_add_u64 v[220:221], s[34:35], 0, v[130:131]
	global_load_lds_dwordx4 v[218:219], off
	s_add_i32 m0, s51, 0x2000
	v_lshl_add_u64 v[218:219], s[52:53], 0, v[132:133]
	global_load_lds_dwordx4 v[218:219], off
	s_mov_b32 m0, s25
	v_lshl_add_u64 v[218:219], s[34:35], 0, v[128:129]
	global_load_lds_dwordx4 v[218:219], off
	s_mov_b32 m0, s39
	s_nop 0
	global_load_lds_dwordx4 v[220:221], off
	s_waitcnt vmcnt(8) lgkmcnt(0)
	s_barrier
	v_mfma_f32_16x16x32_bf16 v[60:63], v[138:141], v[176:179], v[60:63]
	v_mfma_f32_16x16x32_bf16 v[56:59], v[152:155], v[176:179], v[56:59]
	v_mfma_f32_16x16x32_bf16 v[44:47], v[138:141], v[188:191], v[44:47]
	v_mfma_f32_16x16x32_bf16 v[40:43], v[152:155], v[188:191], v[40:43]
	v_mfma_f32_16x16x32_bf16 v[28:31], v[138:141], v[200:203], v[28:31]
	v_mfma_f32_16x16x32_bf16 v[24:27], v[152:155], v[200:203], v[24:27]
	v_mfma_f32_16x16x32_bf16 v[12:15], v[138:141], v[208:211], v[12:15]
	v_mfma_f32_16x16x32_bf16 v[8:11], v[152:155], v[208:211], v[8:11]
	v_mfma_f32_16x16x32_bf16 v[60:63], v[148:151], v[180:183], v[60:63]
	v_mfma_f32_16x16x32_bf16 v[56:59], v[156:159], v[180:183], v[56:59]
	v_mfma_f32_16x16x32_bf16 v[44:47], v[148:151], v[196:199], v[44:47]
	v_mfma_f32_16x16x32_bf16 v[40:43], v[156:159], v[196:199], v[40:43]
	v_mfma_f32_16x16x32_bf16 v[28:31], v[148:151], v[204:207], v[28:31]
	v_mfma_f32_16x16x32_bf16 v[24:27], v[156:159], v[204:207], v[24:27]
	v_mfma_f32_16x16x32_bf16 v[12:15], v[148:151], v[212:215], v[12:15]
	v_mfma_f32_16x16x32_bf16 v[8:11], v[156:159], v[212:215], v[8:11]
	v_mfma_f32_16x16x32_bf16 v[52:55], v[160:163], v[176:179], v[52:55]
	v_mfma_f32_16x16x32_bf16 v[48:51], v[168:171], v[176:179], v[48:51]
	v_mfma_f32_16x16x32_bf16 v[36:39], v[160:163], v[188:191], v[36:39]
	v_mfma_f32_16x16x32_bf16 v[32:35], v[168:171], v[188:191], v[32:35]
	v_mfma_f32_16x16x32_bf16 v[20:23], v[160:163], v[200:203], v[20:23]
	v_mfma_f32_16x16x32_bf16 v[16:19], v[168:171], v[200:203], v[16:19]
	v_mfma_f32_16x16x32_bf16 v[4:7], v[160:163], v[208:211], v[4:7]
	v_mfma_f32_16x16x32_bf16 v[0:3], v[168:171], v[208:211], v[0:3]
	v_mfma_f32_16x16x32_bf16 v[52:55], v[164:167], v[180:183], v[52:55]
	v_mfma_f32_16x16x32_bf16 v[48:51], v[172:175], v[180:183], v[48:51]
	v_mfma_f32_16x16x32_bf16 v[36:39], v[164:167], v[196:199], v[36:39]
	v_mfma_f32_16x16x32_bf16 v[32:35], v[172:175], v[196:199], v[32:35]
	v_mfma_f32_16x16x32_bf16 v[20:23], v[164:167], v[204:207], v[20:23]
	v_mfma_f32_16x16x32_bf16 v[16:19], v[172:175], v[204:207], v[16:19]
	v_mfma_f32_16x16x32_bf16 v[4:7], v[164:167], v[212:215], v[4:7]
	v_mfma_f32_16x16x32_bf16 v[0:3], v[172:175], v[212:215], v[0:3]
	s_add_i32 s51, 0, 0x18000
	s_add_i32 s52, 0, 0x1c000
	s_barrier
; #define PG8_STAGE(bufoff, gbase, voff) do { _Pragma("unroll") for (int _i = 0; _i < 2; ++_i) \
;         __builtin_amdgcn_global_load_lds((const unsigned*)((const char*)(gbase) + (voff)[_i]), (LAS unsigned*)(lds + (bufoff) + ldsw + _i * 8192), 16, 0, 0); } while (0)
; #define PG8_LDA(dst, b, h) do { _Pragma("unroll") for (int m = 0; m < 4; ++m) _Pragma("unroll") for (int k = 0; k < 2; ++k) dst[m][k] = *(const LAS bf16x8*)(lds + PG8_SA(b, h) + aoff + m * 2048 + k * 1024); } while (0)
; #define PG8_LDB(dst, b, h) do { _Pragma("unroll") for (int n = 0; n < 2; ++n) _Pragma("unroll") for (int k = 0; k < 2; ++k) dst[n][k] = *(const LAS bf16x8*)(lds + PG8_SB(b, h) + boff + n * 2048 + k * 1024); } while (0)
; #define PG8_MMA(ai, bj, At, Bt) do { __builtin_amdgcn_s_setprio(1); _Pragma("unroll") for (int m = 0; m < 4; ++m) _Pragma("unroll") for (int n = 0; n < 2; ++n) _Pragma("unroll") for (int k = 0; k < 2; ++k) \
;         acc[ai][bj][m][n] = __builtin_amdgcn_mfma_f32_16x16x32_bf16(Bt[n][k], At[m][k], acc[ai][bj][m][n], 0, 0, 0); __builtin_amdgcn_s_setprio(0); } while (0)
; #define PG8_WAIT_V(n) asm volatile("s_waitcnt vmcnt(" #n ")" ::: "memory")
; #define PG8_WAIT_L(n) asm volatile("s_waitcnt lgkmcnt(" #n ")" ::: "memory")
; #define PG8_BAR __builtin_amdgcn_s_barrier()
; #define PG8_SCHED __builtin_amdgcn_sched_barrier(0)
; template <class Epi, class Sched>
; DI void gemm_phase(LAS unsigned char* lds, const int wv, const int lda, const int ldb, const Sched& S, const Epi& E) {
;     ...
;             PG8_LDB(B0, 1, 0); PG8_LDB(B1, 1, 1); PG8_SCHED; PG8_LDA(At, 1, 0); PG8_STAGE(PG8_SA(0, 1), a2 + hstepA, voffA);
;             PG8_WAIT_V(8); PG8_WAIT_L(0); PG8_BAR; PG8_MMA(0, 0, At, B0); PG8_MMA(0, 1, At, B1); PG8_BAR; PG8_SCHED;
;             PG8_LDA(At, 1, 1); PG8_STAGE(PG8_SB(1, 0), b3, voffB); PG8_STAGE(PG8_SB(1, 1), b3 + hstepB, voffB); PG8_STAGE(PG8_SA(1, 0), a3, voffA);
;             PG8_WAIT_V(8); PG8_WAIT_L(0); PG8_BAR; PG8_MMA(1, 0, At, B0); PG8_MMA(1, 1, At, B1); PG8_BAR; PG8_SCHED;
;         }
	v_add_u32_e32 v156, s51, v145
	v_add_u32_e32 v172, s52, v145
	ds_read_b128 v[138:141], v156
	ds_read_b128 v[148:151], v156 offset:1024
	ds_read_b128 v[152:155], v156 offset:2048
	ds_read_b128 v[156:159], v156 offset:3072
	ds_read_b128 v[160:163], v172
	ds_read_b128 v[164:167], v172 offset:1024
	ds_read_b128 v[168:171], v172 offset:2048
	ds_read_b128 v[172:175], v172 offset:3072
	s_add_u32 s34, s34, 0x80000
	s_addc_u32 s35, s35, 0
	s_mov_b32 m0, s40
	v_lshl_add_u64 v[222:223], s[34:35], 0, v[128:129]
	ds_read_b128 v[176:179], v147 offset:32768
	ds_read_b128 v[180:183], v147 offset:33792
	ds_read_b128 v[188:191], v147 offset:34816
	ds_read_b128 v[196:199], v147 offset:35840
	ds_read_b128 v[200:203], v147 offset:36864
	ds_read_b128 v[204:207], v147 offset:37888
	ds_read_b128 v[208:211], v147 offset:38912
	ds_read_b128 v[212:215], v147 offset:39936
	global_load_lds_dwordx4 v[222:223], off
	s_mov_b32 m0, s41
	v_lshl_add_u64 v[222:223], s[34:35], 0, v[130:131]
	global_load_lds_dwordx4 v[222:223], off
	s_waitcnt vmcnt(8) lgkmcnt(0)
	s_barrier
	v_mfma_f32_16x16x32_bf16 v[124:127], v[138:141], v[176:179], v[124:127]
	v_mfma_f32_16x16x32_bf16 v[120:123], v[152:155], v[176:179], v[120:123]
	v_mfma_f32_16x16x32_bf16 v[108:111], v[138:141], v[188:191], v[108:111]
	v_mfma_f32_16x16x32_bf16 v[104:107], v[152:155], v[188:191], v[104:107]
	v_mfma_f32_16x16x32_bf16 v[92:95], v[138:141], v[200:203], v[92:95]
	v_mfma_f32_16x16x32_bf16 v[88:91], v[152:155], v[200:203], v[88:91]
	v_mfma_f32_16x16x32_bf16 v[76:79], v[138:141], v[208:211], v[76:79]
	v_mfma_f32_16x16x32_bf16 v[72:75], v[152:155], v[208:211], v[72:75]
	v_mfma_f32_16x16x32_bf16 v[124:127], v[148:151], v[180:183], v[124:127]
	v_mfma_f32_16x16x32_bf16 v[120:123], v[156:159], v[180:183], v[120:123]
	v_mfma_f32_16x16x32_bf16 v[108:111], v[148:151], v[196:199], v[108:111]
	v_mfma_f32_16x16x32_bf16 v[104:107], v[156:159], v[196:199], v[104:107]
	v_mfma_f32_16x16x32_bf16 v[92:95], v[148:151], v[204:207], v[92:95]
	v_mfma_f32_16x16x32_bf16 v[88:91], v[156:159], v[204:207], v[88:91]
	v_mfma_f32_16x16x32_bf16 v[76:79], v[148:151], v[212:215], v[76:79]
	v_mfma_f32_16x16x32_bf16 v[72:75], v[156:159], v[212:215], v[72:75]
	v_mfma_f32_16x16x32_bf16 v[116:119], v[160:163], v[176:179], v[116:119]
	v_mfma_f32_16x16x32_bf16 v[112:115], v[168:171], v[176:179], v[112:115]
	v_mfma_f32_16x16x32_bf16 v[100:103], v[160:163], v[188:191], v[100:103]
	v_mfma_f32_16x16x32_bf16 v[96:99], v[168:171], v[188:191], v[96:99]
	v_mfma_f32_16x16x32_bf16 v[84:87], v[160:163], v[200:203], v[84:87]
	v_mfma_f32_16x16x32_bf16 v[80:83], v[168:171], v[200:203], v[80:83]
	v_mfma_f32_16x16x32_bf16 v[68:71], v[160:163], v[208:211], v[68:71]
	v_mfma_f32_16x16x32_bf16 v[64:67], v[168:171], v[208:211], v[64:67]
	v_mfma_f32_16x16x32_bf16 v[116:119], v[164:167], v[180:183], v[116:119]
	v_mfma_f32_16x16x32_bf16 v[112:115], v[172:175], v[180:183], v[112:115]
	v_mfma_f32_16x16x32_bf16 v[100:103], v[164:167], v[196:199], v[100:103]
	v_mfma_f32_16x16x32_bf16 v[96:99], v[172:175], v[196:199], v[96:99]
	v_mfma_f32_16x16x32_bf16 v[84:87], v[164:167], v[204:207], v[84:87]
	v_mfma_f32_16x16x32_bf16 v[80:83], v[172:175], v[204:207], v[80:83]
	v_mfma_f32_16x16x32_bf16 v[68:71], v[164:167], v[212:215], v[68:71]
	v_mfma_f32_16x16x32_bf16 v[64:67], v[172:175], v[212:215], v[64:67]
	s_add_i32 s34, s51, s38
	v_lshl_add_u64 v[142:143], v[142:143], 0, s[28:29]
	s_mov_b32 m0, s34
	s_barrier
	ds_read_b128 v[176:179], v147 offset:49152
	ds_read_b128 v[180:183], v147 offset:50176
	ds_read_b128 v[188:191], v147 offset:51200
	ds_read_b128 v[196:199], v147 offset:52224
	ds_read_b128 v[200:203], v147 offset:53248
	ds_read_b128 v[204:207], v147 offset:54272
	ds_read_b128 v[208:211], v147 offset:55296
	ds_read_b128 v[212:215], v147 offset:56320
	global_load_lds_dwordx4 v[142:143], off
	s_add_i32 m0, s34, 0x2000
	s_add_u32 s30, s30, 0x80080
	v_lshl_add_u64 v[142:143], v[216:217], 0, s[28:29]
	s_addc_u32 s31, s31, 0
	s_add_i32 s34, s52, s38
	global_load_lds_dwordx4 v[142:143], off
	s_mov_b32 m0, s34
	v_lshl_add_u64 v[142:143], s[30:31], 0, v[184:185]
	global_load_lds_dwordx4 v[142:143], off
	s_add_i32 m0, s34, 0x2000
	v_lshl_add_u64 v[142:143], s[30:31], 0, v[132:133]
	global_load_lds_dwordx4 v[142:143], off
	s_mov_b32 m0, s43
	v_lshl_add_u64 v[142:143], v[218:219], 0, s[28:29]
	global_load_lds_dwordx4 v[142:143], off
	s_mov_b32 m0, s44
	v_lshl_add_u64 v[142:143], v[220:221], 0, s[28:29]
	global_load_lds_dwordx4 v[142:143], off
	s_waitcnt vmcnt(8) lgkmcnt(0)
	s_barrier
	v_mfma_f32_16x16x32_bf16 v[60:63], v[138:141], v[176:179], v[60:63]
	v_mfma_f32_16x16x32_bf16 v[56:59], v[152:155], v[176:179], v[56:59]
	v_mfma_f32_16x16x32_bf16 v[44:47], v[138:141], v[188:191], v[44:47]
	v_mfma_f32_16x16x32_bf16 v[40:43], v[152:155], v[188:191], v[40:43]
	v_mfma_f32_16x16x32_bf16 v[28:31], v[138:141], v[200:203], v[28:31]
	v_mfma_f32_16x16x32_bf16 v[24:27], v[152:155], v[200:203], v[24:27]
	v_mfma_f32_16x16x32_bf16 v[12:15], v[138:141], v[208:211], v[12:15]
	v_mfma_f32_16x16x32_bf16 v[8:11], v[152:155], v[208:211], v[8:11]
	v_mfma_f32_16x16x32_bf16 v[60:63], v[148:151], v[180:183], v[60:63]
	v_mfma_f32_16x16x32_bf16 v[56:59], v[156:159], v[180:183], v[56:59]
	v_mfma_f32_16x16x32_bf16 v[44:47], v[148:151], v[196:199], v[44:47]
	v_mfma_f32_16x16x32_bf16 v[40:43], v[156:159], v[196:199], v[40:43]
	v_mfma_f32_16x16x32_bf16 v[28:31], v[148:151], v[204:207], v[28:31]
	v_mfma_f32_16x16x32_bf16 v[24:27], v[156:159], v[204:207], v[24:27]
	v_mfma_f32_16x16x32_bf16 v[12:15], v[148:151], v[212:215], v[12:15]
	v_mfma_f32_16x16x32_bf16 v[8:11], v[156:159], v[212:215], v[8:11]
	v_mfma_f32_16x16x32_bf16 v[52:55], v[160:163], v[176:179], v[52:55]
	v_mfma_f32_16x16x32_bf16 v[48:51], v[168:171], v[176:179], v[48:51]
	v_mfma_f32_16x16x32_bf16 v[36:39], v[160:163], v[188:191], v[36:39]
	v_mfma_f32_16x16x32_bf16 v[32:35], v[168:171], v[188:191], v[32:35]
	v_mfma_f32_16x16x32_bf16 v[20:23], v[160:163], v[200:203], v[20:23]
	v_mfma_f32_16x16x32_bf16 v[16:19], v[168:171], v[200:203], v[16:19]
	v_mfma_f32_16x16x32_bf16 v[4:7], v[160:163], v[208:211], v[4:7]
	v_mfma_f32_16x16x32_bf16 v[0:3], v[168:171], v[208:211], v[0:3]
	v_mfma_f32_16x16x32_bf16 v[52:55], v[164:167], v[180:183], v[52:55]
	v_mfma_f32_16x16x32_bf16 v[48:51], v[172:175], v[180:183], v[48:51]
	v_mfma_f32_16x16x32_bf16 v[36:39], v[164:167], v[196:199], v[36:39]
	v_mfma_f32_16x16x32_bf16 v[32:35], v[172:175], v[196:199], v[32:35]
	v_mfma_f32_16x16x32_bf16 v[20:23], v[164:167], v[204:207], v[20:23]
	v_mfma_f32_16x16x32_bf16 v[16:19], v[172:175], v[204:207], v[16:19]
	v_mfma_f32_16x16x32_bf16 v[4:7], v[164:167], v[212:215], v[4:7]
	v_mfma_f32_16x16x32_bf16 v[0:3], v[172:175], v[212:215], v[0:3]
	s_add_i32 s50, s50, 2
	s_add_u32 s26, s26, 0x100
	s_addc_u32 s27, s27, 0
	s_add_u32 s48, s48, 0x100
	s_addc_u32 s49, s49, 0
	s_cmp_gt_u32 s50, 29
	s_barrier
	s_cbranch_scc0 .LBB0_1397
	s_and_b64 vcc, exec, s[10:11]
	s_cbranch_vccz .LBB0_1400
	s_barrier

;     DI bool next(int i, Unit& u) const { const long L = (long)i * G + c; if (L >= T.nwg) return false; T.map((int)L, u.pm, u.pn); u.seg = 0; return true; }
;     DI bool next(int i, Unit& u) const { const int ti = i / 3; const long L = (long)ti * G + c; if (L >= T.nwg) return false; T.map((int)L, u.pm, u.pn); u.seg = i - 3 * ti; return true; }
;     DI const char* aptr(const Unit& u) const { return A + (size_t)u.pm * ta + (size_t)kofs(u.seg) * 2; }
;     DI const char* bptr(const Unit& u) const { return B + (size_t)u.pn * tb + (size_t)kofs(u.seg) * 2; }
; #define PG8_WAIT_V(n) asm volatile("s_waitcnt vmcnt(" #n ")" ::: "memory")
; #define PG8_BAR __builtin_amdgcn_s_barrier()
; template <class Epi, class Sched>
; DI void gemm_phase(LAS unsigned char* lds, const int wv, const int lda, const int ldb, const Sched& S, const Epi& E) {
;     ...
;         const bool has_next = S.next(ui + 1, nxt);
;         const char* nA = has_next ? S.aptr(nxt) : cA; const char* nB = has_next ? S.bptr(nxt) : cB;
;         for (int t = 0; t < nt; t += 2) {
;             const bool last = (t == nt - 2);
;             const char* a1 = cA + (size_t)(t + 1) * kstep;
;             const char* a2 = last ? nA : cA + (size_t)(t + 2) * kstep; const char* b2 = last ? nB : cB + (size_t)(t + 2) * kstep;
;             const char* a3 = a2 + kstep; const char* b3 = b2 + kstep;
;             PG8_LDB(B0, 0, 0); PG8_LDB(B1, 0, 1); PG8_SCHED; PG8_LDA(At, 0, 0); PG8_STAGE(PG8_SA(1, 1), a1 + hstepA, voffA);
;             PG8_WAIT_V(8); PG8_WAIT_L(0); PG8_BAR; PG8_MMA(0, 0, At, B0); PG8_MMA(0, 1, At, B1); PG8_BAR; PG8_SCHED;
;             PG8_LDA(At, 0, 1); PG8_STAGE(PG8_SB(0, 0), b2, voffB); PG8_STAGE(PG8_SB(0, 1), b2 + hstepB, voffB); PG8_STAGE(PG8_SA(0, 0), a2, voffA);
;             PG8_WAIT_V(8); PG8_WAIT_L(0); PG8_BAR; PG8_MMA(1, 0, At, B0); PG8_MMA(1, 1, At, B1); PG8_BAR; PG8_SCHED;
;             PG8_LDB(B0, 1, 0); PG8_LDB(B1, 1, 1); PG8_SCHED; PG8_LDA(At, 1, 0); PG8_STAGE(PG8_SA(0, 1), a2 + hstepA, voffA);
;             PG8_WAIT_V(8); PG8_WAIT_L(0); PG8_BAR; PG8_MMA(0, 0, At, B0); PG8_MMA(0, 1, At, B1); PG8_BAR; PG8_SCHED;
;             PG8_LDA(At, 1, 1); PG8_STAGE(PG8_SB(1, 0), b3, voffB); PG8_STAGE(PG8_SB(1, 1), b3 + hstepB, voffB); PG8_STAGE(PG8_SA(1, 0), a3, voffA);
;             PG8_WAIT_V(8); PG8_WAIT_L(0); PG8_BAR; PG8_MMA(1, 0, At, B0); PG8_MMA(1, 1, At, B1); PG8_BAR; PG8_SCHED;
.LBB0_1476:
	s_ashr_i32 s23, s22, 31
	s_lshl_b64 s[0:1], s[22:23], 22
	s_add_u32 s24, s33, s0
	s_addc_u32 s25, s40, s1
	s_and_b64 s[0:1], s[6:7], exec
	s_cselect_b32 s0, s25, s35
	s_cselect_b32 s1, s24, s34
	s_ashr_i32 s11, s10, 31
	s_lshl_b64 s[26:27], s[10:11], 22
	s_add_u32 s26, s41, s26
	s_addc_u32 s27, s42, s27
	s_and_b64 s[38:39], s[6:7], exec
	s_cselect_b32 s11, s27, s37
	s_cselect_b32 s19, s26, s36
	s_add_u32 s34, s34, 0x200080
	s_addc_u32 s35, s35, 0
	s_add_u32 s23, s36, 0x100
	s_addc_u32 s54, s37, 0
	s_mov_b32 s55, -2
	s_waitcnt lgkmcnt(0)
	s_add_u32 s36, s34, 0xffe00080
	s_addc_u32 s37, s35, -1
	s_add_i32 s56, 0, 0x10000
	s_cmpk_eq_i32 s55, 0x7c
	s_cselect_b32 s39, s0, s37
	s_cselect_b32 s38, s1, s36
	s_cselect_b32 s37, s11, s54
	s_cselect_b32 s36, s19, s23
	s_add_i32 s58, 0, 0x14000
	v_add_u32_e32 v150, s56, v155
	v_add_u32_e32 v172, s58, v155
	ds_read_b128 v[128:131], v150
	ds_read_b128 v[142:145], v150 offset:1024
	ds_read_b128 v[146:149], v150 offset:2048
	ds_read_b128 v[150:153], v150 offset:3072
	ds_read_b128 v[160:163], v172
	ds_read_b128 v[164:167], v172 offset:1024
	ds_read_b128 v[168:171], v172 offset:2048
	ds_read_b128 v[172:175], v172 offset:3072
	v_lshl_add_u64 v[216:217], s[34:35], 0, v[138:139]
	s_add_i32 m0, s31, 0xc000
	ds_read_b128 v[176:179], v159
	ds_read_b128 v[180:183], v159 offset:1024
	ds_read_b128 v[188:191], v159 offset:2048
	ds_read_b128 v[196:199], v159 offset:3072
	ds_read_b128 v[200:203], v159 offset:4096
	ds_read_b128 v[204:207], v159 offset:5120
	ds_read_b128 v[208:211], v159 offset:6144
	ds_read_b128 v[212:215], v159 offset:7168
	global_load_lds_dwordx4 v[216:217], off
	s_add_i32 m0, s31, 0xe000
	v_lshl_add_u64 v[216:217], s[34:35], 0, v[140:141]
	global_load_lds_dwordx4 v[216:217], off
	s_waitcnt vmcnt(8) lgkmcnt(0)
	s_barrier
	v_mfma_f32_16x16x32_bf16 v[124:127], v[128:131], v[176:179], 0
	v_mfma_f32_16x16x32_bf16 v[120:123], v[146:149], v[176:179], 0
	v_mfma_f32_16x16x32_bf16 v[108:111], v[128:131], v[188:191], 0
	v_mfma_f32_16x16x32_bf16 v[104:107], v[146:149], v[188:191], 0
	v_mfma_f32_16x16x32_bf16 v[96:99], v[128:131], v[200:203], 0
	v_mfma_f32_16x16x32_bf16 v[88:91], v[146:149], v[200:203], 0
	v_mfma_f32_16x16x32_bf16 v[80:83], v[128:131], v[208:211], 0
	v_mfma_f32_16x16x32_bf16 v[72:75], v[146:149], v[208:211], 0
	v_mfma_f32_16x16x32_bf16 v[124:127], v[142:145], v[180:183], v[124:127]
	v_mfma_f32_16x16x32_bf16 v[120:123], v[150:153], v[180:183], v[120:123]
	v_mfma_f32_16x16x32_bf16 v[108:111], v[142:145], v[196:199], v[108:111]
	v_mfma_f32_16x16x32_bf16 v[104:107], v[150:153], v[196:199], v[104:107]
	v_mfma_f32_16x16x32_bf16 v[96:99], v[142:145], v[204:207], v[96:99]
	v_mfma_f32_16x16x32_bf16 v[88:91], v[150:153], v[204:207], v[88:91]
	v_mfma_f32_16x16x32_bf16 v[80:83], v[142:145], v[212:215], v[80:83]
	v_mfma_f32_16x16x32_bf16 v[72:75], v[150:153], v[212:215], v[72:75]
	v_mfma_f32_16x16x32_bf16 v[116:119], v[160:163], v[176:179], 0
	v_mfma_f32_16x16x32_bf16 v[112:115], v[168:171], v[176:179], 0
	v_mfma_f32_16x16x32_bf16 v[100:103], v[160:163], v[188:191], 0
	v_mfma_f32_16x16x32_bf16 v[92:95], v[168:171], v[188:191], 0
	v_mfma_f32_16x16x32_bf16 v[84:87], v[160:163], v[200:203], 0
	v_mfma_f32_16x16x32_bf16 v[76:79], v[168:171], v[200:203], 0
	v_mfma_f32_16x16x32_bf16 v[68:71], v[160:163], v[208:211], 0
	v_mfma_f32_16x16x32_bf16 v[64:67], v[168:171], v[208:211], 0
	v_mfma_f32_16x16x32_bf16 v[116:119], v[164:167], v[180:183], v[116:119]
	v_mfma_f32_16x16x32_bf16 v[112:115], v[172:175], v[180:183], v[112:115]
	v_mfma_f32_16x16x32_bf16 v[100:103], v[164:167], v[196:199], v[100:103]
	v_mfma_f32_16x16x32_bf16 v[92:95], v[172:175], v[196:199], v[92:95]
	v_mfma_f32_16x16x32_bf16 v[84:87], v[164:167], v[204:207], v[84:87]
	v_mfma_f32_16x16x32_bf16 v[76:79], v[172:175], v[204:207], v[76:79]
	v_mfma_f32_16x16x32_bf16 v[68:71], v[164:167], v[212:215], v[68:71]
	v_mfma_f32_16x16x32_bf16 v[64:67], v[172:175], v[212:215], v[64:67]
	s_add_i32 s56, s56, s43
	v_lshl_add_u64 v[216:217], s[36:37], 0, v[184:185]
	s_mov_b32 m0, s56
	s_barrier
	ds_read_b128 v[176:179], v159 offset:16384
	ds_read_b128 v[180:183], v159 offset:17408
	ds_read_b128 v[188:191], v159 offset:18432
	ds_read_b128 v[196:199], v159 offset:19456
	ds_read_b128 v[200:203], v159 offset:20480
	ds_read_b128 v[204:207], v159 offset:21504
	ds_read_b128 v[208:211], v159 offset:22528
	ds_read_b128 v[212:215], v159 offset:23552
	global_load_lds_dwordx4 v[216:217], off
	s_add_i32 m0, s56, 0x2000
	s_add_u32 s56, s36, 0x200000
	v_lshl_add_u64 v[218:219], s[36:37], 0, v[136:137]
	s_addc_u32 s57, s37, 0
	s_add_i32 s58, s58, s43
	global_load_lds_dwordx4 v[218:219], off
	v_lshl_add_u64 v[220:221], s[56:57], 0, v[184:185]
	s_mov_b32 m0, s58
	v_lshl_add_u64 v[222:223], s[38:39], 0, v[134:135]
	global_load_lds_dwordx4 v[220:221], off
	s_add_i32 m0, s58, 0x2000
	v_lshl_add_u64 v[220:221], s[56:57], 0, v[136:137]
	global_load_lds_dwordx4 v[220:221], off
	s_mov_b32 m0, s31
	v_lshl_add_u64 v[220:221], s[38:39], 0, v[132:133]
	global_load_lds_dwordx4 v[220:221], off
	s_mov_b32 m0, s44
	s_nop 0
	global_load_lds_dwordx4 v[222:223], off
	s_waitcnt vmcnt(8) lgkmcnt(0)
	s_barrier
; #define PG8_STAGE(bufoff, gbase, voff) do { _Pragma("unroll") for (int _i = 0; _i < 2; ++_i) \
;         __builtin_amdgcn_global_load_lds((const unsigned*)((const char*)(gbase) + (voff)[_i]), (LAS unsigned*)(lds + (bufoff) + ldsw + _i * 8192), 16, 0, 0); } while (0)
; #define PG8_LDA(dst, b, h) do { _Pragma("unroll") for (int m = 0; m < 4; ++m) _Pragma("unroll") for (int k = 0; k < 2; ++k) dst[m][k] = *(const LAS bf16x8*)(lds + PG8_SA(b, h) + aoff + m * 2048 + k * 1024); } while (0)
; #define PG8_LDB(dst, b, h) do { _Pragma("unroll") for (int n = 0; n < 2; ++n) _Pragma("unroll") for (int k = 0; k < 2; ++k) dst[n][k] = *(const LAS bf16x8*)(lds + PG8_SB(b, h) + boff + n * 2048 + k * 1024); } while (0)
; #define PG8_MMA(ai, bj, At, Bt) do { __builtin_amdgcn_s_setprio(1); _Pragma("unroll") for (int m = 0; m < 4; ++m) _Pragma("unroll") for (int n = 0; n < 2; ++n) _Pragma("unroll") for (int k = 0; k < 2; ++k) \
;         acc[ai][bj][m][n] = __builtin_amdgcn_mfma_f32_16x16x32_bf16(Bt[n][k], At[m][k], acc[ai][bj][m][n], 0, 0, 0); __builtin_amdgcn_s_setprio(0); } while (0)
; #define PG8_WAIT_V(n) asm volatile("s_waitcnt vmcnt(" #n ")" ::: "memory")
; #define PG8_WAIT_L(n) asm volatile("s_waitcnt lgkmcnt(" #n ")" ::: "memory")
; #define PG8_BAR __builtin_amdgcn_s_barrier()
; #define PG8_SCHED __builtin_amdgcn_sched_barrier(0)
; template <class Epi, class Sched>
; DI void gemm_phase(LAS unsigned char* lds, const int wv, const int lda, const int ldb, const Sched& S, const Epi& E) {
;     ...
;             PG8_WAIT_V(8); PG8_WAIT_L(0); PG8_BAR; PG8_MMA(0, 0, At, B0); PG8_MMA(0, 1, At, B1); PG8_BAR; PG8_SCHED;
;             PG8_LDA(At, 0, 1); PG8_STAGE(PG8_SB(0, 0), b2, voffB); PG8_STAGE(PG8_SB(0, 1), b2 + hstepB, voffB); PG8_STAGE(PG8_SA(0, 0), a2, voffA);
;             PG8_WAIT_V(8); PG8_WAIT_L(0); PG8_BAR; PG8_MMA(1, 0, At, B0); PG8_MMA(1, 1, At, B1); PG8_BAR; PG8_SCHED;
;             PG8_LDB(B0, 1, 0); PG8_LDB(B1, 1, 1); PG8_SCHED; PG8_LDA(At, 1, 0); PG8_STAGE(PG8_SA(0, 1), a2 + hstepA, voffA);
;             PG8_WAIT_V(8); PG8_WAIT_L(0); PG8_BAR; PG8_MMA(0, 0, At, B0); PG8_MMA(0, 1, At, B1); PG8_BAR; PG8_SCHED;
	v_mfma_f32_16x16x32_bf16 v[60:63], v[128:131], v[176:179], 0
	v_mfma_f32_16x16x32_bf16 v[56:59], v[146:149], v[176:179], 0
	v_mfma_f32_16x16x32_bf16 v[48:51], v[128:131], v[188:191], 0
	v_mfma_f32_16x16x32_bf16 v[40:43], v[146:149], v[188:191], 0
	v_mfma_f32_16x16x32_bf16 v[32:35], v[128:131], v[200:203], 0
	v_mfma_f32_16x16x32_bf16 v[24:27], v[146:149], v[200:203], 0
	v_mfma_f32_16x16x32_bf16 v[16:19], v[128:131], v[208:211], 0
	v_mfma_f32_16x16x32_bf16 v[8:11], v[146:149], v[208:211], 0
	v_mfma_f32_16x16x32_bf16 v[60:63], v[142:145], v[180:183], v[60:63]
	v_mfma_f32_16x16x32_bf16 v[56:59], v[150:153], v[180:183], v[56:59]
	v_mfma_f32_16x16x32_bf16 v[48:51], v[142:145], v[196:199], v[48:51]
	v_mfma_f32_16x16x32_bf16 v[40:43], v[150:153], v[196:199], v[40:43]
	v_mfma_f32_16x16x32_bf16 v[32:35], v[142:145], v[204:207], v[32:35]
	v_mfma_f32_16x16x32_bf16 v[24:27], v[150:153], v[204:207], v[24:27]
	v_mfma_f32_16x16x32_bf16 v[16:19], v[142:145], v[212:215], v[16:19]
	v_mfma_f32_16x16x32_bf16 v[8:11], v[150:153], v[212:215], v[8:11]
	v_mfma_f32_16x16x32_bf16 v[52:55], v[160:163], v[176:179], 0
	v_mfma_f32_16x16x32_bf16 v[44:47], v[168:171], v[176:179], 0
	v_mfma_f32_16x16x32_bf16 v[36:39], v[160:163], v[188:191], 0
	v_mfma_f32_16x16x32_bf16 v[28:31], v[168:171], v[188:191], 0
	v_mfma_f32_16x16x32_bf16 v[20:23], v[160:163], v[200:203], 0
	v_mfma_f32_16x16x32_bf16 v[12:15], v[168:171], v[200:203], 0
	v_mfma_f32_16x16x32_bf16 v[4:7], v[160:163], v[208:211], 0
	v_mfma_f32_16x16x32_bf16 v[0:3], v[168:171], v[208:211], 0
	v_mfma_f32_16x16x32_bf16 v[52:55], v[164:167], v[180:183], v[52:55]
	v_mfma_f32_16x16x32_bf16 v[44:47], v[172:175], v[180:183], v[44:47]
	v_mfma_f32_16x16x32_bf16 v[36:39], v[164:167], v[196:199], v[36:39]
	v_mfma_f32_16x16x32_bf16 v[28:31], v[172:175], v[196:199], v[28:31]
	v_mfma_f32_16x16x32_bf16 v[20:23], v[164:167], v[204:207], v[20:23]
	v_mfma_f32_16x16x32_bf16 v[12:15], v[172:175], v[204:207], v[12:15]
	v_mfma_f32_16x16x32_bf16 v[4:7], v[164:167], v[212:215], v[4:7]
	v_mfma_f32_16x16x32_bf16 v[0:3], v[172:175], v[212:215], v[0:3]
	s_add_i32 s56, 0, 0x18000
	s_add_i32 s57, 0, 0x1c000
	s_barrier
	v_add_u32_e32 v150, s56, v155
	v_add_u32_e32 v172, s57, v155
	ds_read_b128 v[128:131], v150
	ds_read_b128 v[142:145], v150 offset:1024
	ds_read_b128 v[146:149], v150 offset:2048
	ds_read_b128 v[150:153], v150 offset:3072
	ds_read_b128 v[160:163], v172
	ds_read_b128 v[164:167], v172 offset:1024
	ds_read_b128 v[168:171], v172 offset:2048
	ds_read_b128 v[172:175], v172 offset:3072
	s_add_u32 s38, s38, 0x200000
	s_addc_u32 s39, s39, 0
	s_mov_b32 m0, s45
	v_lshl_add_u64 v[234:235], s[38:39], 0, v[132:133]
	ds_read_b128 v[176:179], v159 offset:32768
	ds_read_b128 v[180:183], v159 offset:33792
	ds_read_b128 v[188:191], v159 offset:34816
	ds_read_b128 v[196:199], v159 offset:35840
	ds_read_b128 v[200:203], v159 offset:36864
	ds_read_b128 v[204:207], v159 offset:37888
	ds_read_b128 v[208:211], v159 offset:38912
	ds_read_b128 v[212:215], v159 offset:39936
	global_load_lds_dwordx4 v[234:235], off
	s_mov_b32 m0, s46
	v_lshl_add_u64 v[234:235], s[38:39], 0, v[134:135]
	global_load_lds_dwordx4 v[234:235], off
	s_waitcnt vmcnt(8) lgkmcnt(0)
	s_barrier
	v_mfma_f32_16x16x32_bf16 v[124:127], v[128:131], v[176:179], v[124:127]
	v_mfma_f32_16x16x32_bf16 v[120:123], v[146:149], v[176:179], v[120:123]
	v_mfma_f32_16x16x32_bf16 v[108:111], v[128:131], v[188:191], v[108:111]
	v_mfma_f32_16x16x32_bf16 v[104:107], v[146:149], v[188:191], v[104:107]
	v_mfma_f32_16x16x32_bf16 v[96:99], v[128:131], v[200:203], v[96:99]
	v_mfma_f32_16x16x32_bf16 v[88:91], v[146:149], v[200:203], v[88:91]
	v_mfma_f32_16x16x32_bf16 v[80:83], v[128:131], v[208:211], v[80:83]
	v_mfma_f32_16x16x32_bf16 v[72:75], v[146:149], v[208:211], v[72:75]
	v_mfma_f32_16x16x32_bf16 v[124:127], v[142:145], v[180:183], v[124:127]
	v_mfma_f32_16x16x32_bf16 v[120:123], v[150:153], v[180:183], v[120:123]
	v_mfma_f32_16x16x32_bf16 v[108:111], v[142:145], v[196:199], v[108:111]
	v_mfma_f32_16x16x32_bf16 v[104:107], v[150:153], v[196:199], v[104:107]
	v_mfma_f32_16x16x32_bf16 v[96:99], v[142:145], v[204:207], v[96:99]
	v_mfma_f32_16x16x32_bf16 v[88:91], v[150:153], v[204:207], v[88:91]
	v_mfma_f32_16x16x32_bf16 v[80:83], v[142:145], v[212:215], v[80:83]
	v_mfma_f32_16x16x32_bf16 v[72:75], v[150:153], v[212:215], v[72:75]
	v_mfma_f32_16x16x32_bf16 v[116:119], v[160:163], v[176:179], v[116:119]
	v_mfma_f32_16x16x32_bf16 v[112:115], v[168:171], v[176:179], v[112:115]
	v_mfma_f32_16x16x32_bf16 v[100:103], v[160:163], v[188:191], v[100:103]
	v_mfma_f32_16x16x32_bf16 v[92:95], v[168:171], v[188:191], v[92:95]
	v_mfma_f32_16x16x32_bf16 v[84:87], v[160:163], v[200:203], v[84:87]
	v_mfma_f32_16x16x32_bf16 v[76:79], v[168:171], v[200:203], v[76:79]
	v_mfma_f32_16x16x32_bf16 v[68:71], v[160:163], v[208:211], v[68:71]
	v_mfma_f32_16x16x32_bf16 v[64:67], v[168:171], v[208:211], v[64:67]
	v_mfma_f32_16x16x32_bf16 v[116:119], v[164:167], v[180:183], v[116:119]
	v_mfma_f32_16x16x32_bf16 v[112:115], v[172:175], v[180:183], v[112:115]
	v_mfma_f32_16x16x32_bf16 v[100:103], v[164:167], v[196:199], v[100:103]
	v_mfma_f32_16x16x32_bf16 v[92:95], v[172:175], v[196:199], v[92:95]
	v_mfma_f32_16x16x32_bf16 v[84:87], v[164:167], v[204:207], v[84:87]
	v_mfma_f32_16x16x32_bf16 v[76:79], v[172:175], v[204:207], v[76:79]
	v_mfma_f32_16x16x32_bf16 v[68:71], v[164:167], v[212:215], v[68:71]
	v_mfma_f32_16x16x32_bf16 v[64:67], v[172:175], v[212:215], v[64:67]
	s_add_i32 s38, s56, s43
	v_lshl_add_u64 v[216:217], v[216:217], 0, s[28:29]
	s_mov_b32 m0, s38
	s_barrier
; #define PG8_STAGE(bufoff, gbase, voff) do { _Pragma("unroll") for (int _i = 0; _i < 2; ++_i) \
;         __builtin_amdgcn_global_load_lds((const unsigned*)((const char*)(gbase) + (voff)[_i]), (LAS unsigned*)(lds + (bufoff) + ldsw + _i * 8192), 16, 0, 0); } while (0)
; #define PG8_LDA(dst, b, h) do { _Pragma("unroll") for (int m = 0; m < 4; ++m) _Pragma("unroll") for (int k = 0; k < 2; ++k) dst[m][k] = *(const LAS bf16x8*)(lds + PG8_SA(b, h) + aoff + m * 2048 + k * 1024); } while (0)
; #define PG8_LDB(dst, b, h) do { _Pragma("unroll") for (int n = 0; n < 2; ++n) _Pragma("unroll") for (int k = 0; k < 2; ++k) dst[n][k] = *(const LAS bf16x8*)(lds + PG8_SB(b, h) + boff + n * 2048 + k * 1024); } while (0)
; #define PG8_MMA(ai, bj, At, Bt) do { __builtin_amdgcn_s_setprio(1); _Pragma("unroll") for (int m = 0; m < 4; ++m) _Pragma("unroll") for (int n = 0; n < 2; ++n) _Pragma("unroll") for (int k = 0; k < 2; ++k) \
;         acc[ai][bj][m][n] = __builtin_amdgcn_mfma_f32_16x16x32_bf16(Bt[n][k], At[m][k], acc[ai][bj][m][n], 0, 0, 0); __builtin_amdgcn_s_setprio(0); } while (0)
; #define PG8_WAIT_V(n) asm volatile("s_waitcnt vmcnt(" #n ")" ::: "memory")
; #define PG8_WAIT_L(n) asm volatile("s_waitcnt lgkmcnt(" #n ")" ::: "memory")
; template <class Epi, class Sched>
; DI void gemm_phase(LAS unsigned char* lds, const int wv, const int lda, const int ldb, const Sched& S, const Epi& E) {
;     ...
;         for (int t = 0; t < nt; t += 2) {
;             const bool last = (t == nt - 2);
;             const char* a1 = cA + (size_t)(t + 1) * kstep;
;             const char* a2 = last ? nA : cA + (size_t)(t + 2) * kstep; const char* b2 = last ? nB : cB + (size_t)(t + 2) * kstep;
;             const char* a3 = a2 + kstep; const char* b3 = b2 + kstep;
;             PG8_LDB(B0, 0, 0); PG8_LDB(B1, 0, 1); PG8_SCHED; PG8_LDA(At, 0, 0); PG8_STAGE(PG8_SA(1, 1), a1 + hstepA, voffA);
;             PG8_WAIT_V(8); PG8_WAIT_L(0); PG8_BAR; PG8_MMA(0, 0, At, B0); PG8_MMA(0, 1, At, B1); PG8_BAR; PG8_SCHED;
;     ...
;             PG8_WAIT_V(8); PG8_WAIT_L(0); PG8_BAR; PG8_MMA(0, 0, At, B0); PG8_MMA(0, 1, At, B1); PG8_BAR; PG8_SCHED;
;             PG8_LDA(At, 1, 1); PG8_STAGE(PG8_SB(1, 0), b3, voffB); PG8_STAGE(PG8_SB(1, 1), b3 + hstepB, voffB); PG8_STAGE(PG8_SA(1, 0), a3, voffA);
;             PG8_WAIT_V(8); PG8_WAIT_L(0); PG8_BAR; PG8_MMA(1, 0, At, B0); PG8_MMA(1, 1, At, B1); PG8_BAR; PG8_SCHED;
	ds_read_b128 v[176:179], v159 offset:49152
	ds_read_b128 v[180:183], v159 offset:50176
	ds_read_b128 v[188:191], v159 offset:51200
	ds_read_b128 v[196:199], v159 offset:52224
	ds_read_b128 v[200:203], v159 offset:53248
	ds_read_b128 v[204:207], v159 offset:54272
	ds_read_b128 v[208:211], v159 offset:55296
	ds_read_b128 v[212:215], v159 offset:56320
	global_load_lds_dwordx4 v[216:217], off
	s_add_i32 m0, s38, 0x2000
	s_add_u32 s36, s36, 0x200080
	v_lshl_add_u64 v[216:217], v[218:219], 0, s[28:29]
	s_addc_u32 s37, s37, 0
	s_add_i32 s38, s57, s43
	global_load_lds_dwordx4 v[216:217], off
	s_mov_b32 m0, s38
	v_lshl_add_u64 v[216:217], s[36:37], 0, v[184:185]
	global_load_lds_dwordx4 v[216:217], off
	s_add_i32 m0, s38, 0x2000
	v_lshl_add_u64 v[216:217], s[36:37], 0, v[136:137]
	global_load_lds_dwordx4 v[216:217], off
	s_mov_b32 m0, s47
	v_lshl_add_u64 v[216:217], v[220:221], 0, s[28:29]
	global_load_lds_dwordx4 v[216:217], off
	s_mov_b32 m0, s48
	v_lshl_add_u64 v[216:217], v[222:223], 0, s[28:29]
	global_load_lds_dwordx4 v[216:217], off
	s_waitcnt vmcnt(8) lgkmcnt(0)
	s_barrier
	v_mfma_f32_16x16x32_bf16 v[60:63], v[128:131], v[176:179], v[60:63]
	v_mfma_f32_16x16x32_bf16 v[56:59], v[146:149], v[176:179], v[56:59]
	v_mfma_f32_16x16x32_bf16 v[48:51], v[128:131], v[188:191], v[48:51]
	v_mfma_f32_16x16x32_bf16 v[40:43], v[146:149], v[188:191], v[40:43]
	v_mfma_f32_16x16x32_bf16 v[32:35], v[128:131], v[200:203], v[32:35]
	v_mfma_f32_16x16x32_bf16 v[24:27], v[146:149], v[200:203], v[24:27]
	v_mfma_f32_16x16x32_bf16 v[16:19], v[128:131], v[208:211], v[16:19]
	v_mfma_f32_16x16x32_bf16 v[8:11], v[146:149], v[208:211], v[8:11]
	v_mfma_f32_16x16x32_bf16 v[60:63], v[142:145], v[180:183], v[60:63]
	v_mfma_f32_16x16x32_bf16 v[56:59], v[150:153], v[180:183], v[56:59]
	v_mfma_f32_16x16x32_bf16 v[48:51], v[142:145], v[196:199], v[48:51]
	v_mfma_f32_16x16x32_bf16 v[40:43], v[150:153], v[196:199], v[40:43]
	v_mfma_f32_16x16x32_bf16 v[32:35], v[142:145], v[204:207], v[32:35]
	v_mfma_f32_16x16x32_bf16 v[24:27], v[150:153], v[204:207], v[24:27]
	v_mfma_f32_16x16x32_bf16 v[16:19], v[142:145], v[212:215], v[16:19]
	v_mfma_f32_16x16x32_bf16 v[8:11], v[150:153], v[212:215], v[8:11]
	v_mfma_f32_16x16x32_bf16 v[52:55], v[160:163], v[176:179], v[52:55]
	v_mfma_f32_16x16x32_bf16 v[44:47], v[168:171], v[176:179], v[44:47]
	v_mfma_f32_16x16x32_bf16 v[36:39], v[160:163], v[188:191], v[36:39]
	v_mfma_f32_16x16x32_bf16 v[28:31], v[168:171], v[188:191], v[28:31]
	v_mfma_f32_16x16x32_bf16 v[20:23], v[160:163], v[200:203], v[20:23]
	v_mfma_f32_16x16x32_bf16 v[12:15], v[168:171], v[200:203], v[12:15]
	v_mfma_f32_16x16x32_bf16 v[4:7], v[160:163], v[208:211], v[4:7]
	v_mfma_f32_16x16x32_bf16 v[0:3], v[168:171], v[208:211], v[0:3]
	v_mfma_f32_16x16x32_bf16 v[52:55], v[164:167], v[180:183], v[52:55]
	v_mfma_f32_16x16x32_bf16 v[44:47], v[172:175], v[180:183], v[44:47]
	v_mfma_f32_16x16x32_bf16 v[36:39], v[164:167], v[196:199], v[36:39]
	v_mfma_f32_16x16x32_bf16 v[28:31], v[172:175], v[196:199], v[28:31]
	v_mfma_f32_16x16x32_bf16 v[20:23], v[164:167], v[204:207], v[20:23]
	v_mfma_f32_16x16x32_bf16 v[12:15], v[172:175], v[204:207], v[12:15]
	v_mfma_f32_16x16x32_bf16 v[4:7], v[164:167], v[212:215], v[4:7]
	v_mfma_f32_16x16x32_bf16 v[0:3], v[172:175], v[212:215], v[0:3]
	s_add_i32 s55, s55, 2
	s_add_u32 s34, s34, 0x100
	s_addc_u32 s35, s35, 0
	s_add_u32 s23, s23, 0x100
	s_addc_u32 s54, s54, 0
	s_barrier
.LBB0_1477:
	s_add_u32 s36, s34, 0xffe00080
	s_addc_u32 s37, s35, -1
	s_add_i32 s56, 0, 0x10000
	s_cmpk_eq_i32 s55, 0x7c
	s_cselect_b32 s39, s0, s37
	s_cselect_b32 s38, s1, s36
	s_cselect_b32 s37, s11, s54
	s_cselect_b32 s36, s19, s23
	s_add_i32 s58, 0, 0x14000
	v_add_u32_e32 v150, s56, v155
	v_add_u32_e32 v172, s58, v155
	ds_read_b128 v[128:131], v150
	ds_read_b128 v[142:145], v150 offset:1024
	ds_read_b128 v[146:149], v150 offset:2048
	ds_read_b128 v[150:153], v150 offset:3072
	ds_read_b128 v[160:163], v172
	ds_read_b128 v[164:167], v172 offset:1024
	ds_read_b128 v[168:171], v172 offset:2048
	ds_read_b128 v[172:175], v172 offset:3072
	v_lshl_add_u64 v[216:217], s[34:35], 0, v[138:139]
	s_add_i32 m0, s31, 0xc000
	ds_read_b128 v[176:179], v159
	ds_read_b128 v[180:183], v159 offset:1024
	ds_read_b128 v[188:191], v159 offset:2048
	ds_read_b128 v[196:199], v159 offset:3072
	ds_read_b128 v[200:203], v159 offset:4096
	ds_read_b128 v[204:207], v159 offset:5120
	ds_read_b128 v[208:211], v159 offset:6144
	ds_read_b128 v[212:215], v159 offset:7168
	global_load_lds_dwordx4 v[216:217], off
	s_add_i32 m0, s31, 0xe000
	v_lshl_add_u64 v[216:217], s[34:35], 0, v[140:141]
	global_load_lds_dwordx4 v[216:217], off
	s_waitcnt vmcnt(8) lgkmcnt(0)
	s_barrier
; #define PG8_STAGE(bufoff, gbase, voff) do { _Pragma("unroll") for (int _i = 0; _i < 2; ++_i) \
;         __builtin_amdgcn_global_load_lds((const unsigned*)((const char*)(gbase) + (voff)[_i]), (LAS unsigned*)(lds + (bufoff) + ldsw + _i * 8192), 16, 0, 0); } while (0)
; #define PG8_LDA(dst, b, h) do { _Pragma("unroll") for (int m = 0; m < 4; ++m) _Pragma("unroll") for (int k = 0; k < 2; ++k) dst[m][k] = *(const LAS bf16x8*)(lds + PG8_SA(b, h) + aoff + m * 2048 + k * 1024); } while (0)
; #define PG8_LDB(dst, b, h) do { _Pragma("unroll") for (int n = 0; n < 2; ++n) _Pragma("unroll") for (int k = 0; k < 2; ++k) dst[n][k] = *(const LAS bf16x8*)(lds + PG8_SB(b, h) + boff + n * 2048 + k * 1024); } while (0)
; #define PG8_MMA(ai, bj, At, Bt) do { __builtin_amdgcn_s_setprio(1); _Pragma("unroll") for (int m = 0; m < 4; ++m) _Pragma("unroll") for (int n = 0; n < 2; ++n) _Pragma("unroll") for (int k = 0; k < 2; ++k) \
;         acc[ai][bj][m][n] = __builtin_amdgcn_mfma_f32_16x16x32_bf16(Bt[n][k], At[m][k], acc[ai][bj][m][n], 0, 0, 0); __builtin_amdgcn_s_setprio(0); } while (0)
; #define PG8_WAIT_V(n) asm volatile("s_waitcnt vmcnt(" #n ")" ::: "memory")
; #define PG8_WAIT_L(n) asm volatile("s_waitcnt lgkmcnt(" #n ")" ::: "memory")
; #define PG8_BAR __builtin_amdgcn_s_barrier()
; #define PG8_SCHED __builtin_amdgcn_sched_barrier(0)
; template <class Epi, class Sched>
; DI void gemm_phase(LAS unsigned char* lds, const int wv, const int lda, const int ldb, const Sched& S, const Epi& E) {
;     ...
;             PG8_WAIT_V(8); PG8_WAIT_L(0); PG8_BAR; PG8_MMA(0, 0, At, B0); PG8_MMA(0, 1, At, B1); PG8_BAR; PG8_SCHED;
;             PG8_LDA(At, 0, 1); PG8_STAGE(PG8_SB(0, 0), b2, voffB); PG8_STAGE(PG8_SB(0, 1), b2 + hstepB, voffB); PG8_STAGE(PG8_SA(0, 0), a2, voffA);
;             PG8_WAIT_V(8); PG8_WAIT_L(0); PG8_BAR; PG8_MMA(1, 0, At, B0); PG8_MMA(1, 1, At, B1); PG8_BAR; PG8_SCHED;
;             PG8_LDB(B0, 1, 0); PG8_LDB(B1, 1, 1); PG8_SCHED; PG8_LDA(At, 1, 0); PG8_STAGE(PG8_SA(0, 1), a2 + hstepA, voffA);
;             PG8_WAIT_V(8); PG8_WAIT_L(0); PG8_BAR; PG8_MMA(0, 0, At, B0); PG8_MMA(0, 1, At, B1); PG8_BAR; PG8_SCHED;
	v_mfma_f32_16x16x32_bf16 v[124:127], v[128:131], v[176:179], v[124:127]
	v_mfma_f32_16x16x32_bf16 v[120:123], v[146:149], v[176:179], v[120:123]
	v_mfma_f32_16x16x32_bf16 v[108:111], v[128:131], v[188:191], v[108:111]
	v_mfma_f32_16x16x32_bf16 v[104:107], v[146:149], v[188:191], v[104:107]
	v_mfma_f32_16x16x32_bf16 v[96:99], v[128:131], v[200:203], v[96:99]
	v_mfma_f32_16x16x32_bf16 v[88:91], v[146:149], v[200:203], v[88:91]
	v_mfma_f32_16x16x32_bf16 v[80:83], v[128:131], v[208:211], v[80:83]
	v_mfma_f32_16x16x32_bf16 v[72:75], v[146:149], v[208:211], v[72:75]
	v_mfma_f32_16x16x32_bf16 v[124:127], v[142:145], v[180:183], v[124:127]
	v_mfma_f32_16x16x32_bf16 v[120:123], v[150:153], v[180:183], v[120:123]
	v_mfma_f32_16x16x32_bf16 v[108:111], v[142:145], v[196:199], v[108:111]
	v_mfma_f32_16x16x32_bf16 v[104:107], v[150:153], v[196:199], v[104:107]
	v_mfma_f32_16x16x32_bf16 v[96:99], v[142:145], v[204:207], v[96:99]
	v_mfma_f32_16x16x32_bf16 v[88:91], v[150:153], v[204:207], v[88:91]
	v_mfma_f32_16x16x32_bf16 v[80:83], v[142:145], v[212:215], v[80:83]
	v_mfma_f32_16x16x32_bf16 v[72:75], v[150:153], v[212:215], v[72:75]
	v_mfma_f32_16x16x32_bf16 v[116:119], v[160:163], v[176:179], v[116:119]
	v_mfma_f32_16x16x32_bf16 v[112:115], v[168:171], v[176:179], v[112:115]
	v_mfma_f32_16x16x32_bf16 v[100:103], v[160:163], v[188:191], v[100:103]
	v_mfma_f32_16x16x32_bf16 v[92:95], v[168:171], v[188:191], v[92:95]
	v_mfma_f32_16x16x32_bf16 v[84:87], v[160:163], v[200:203], v[84:87]
	v_mfma_f32_16x16x32_bf16 v[76:79], v[168:171], v[200:203], v[76:79]
	v_mfma_f32_16x16x32_bf16 v[68:71], v[160:163], v[208:211], v[68:71]
	v_mfma_f32_16x16x32_bf16 v[64:67], v[168:171], v[208:211], v[64:67]
	v_mfma_f32_16x16x32_bf16 v[116:119], v[164:167], v[180:183], v[116:119]
	v_mfma_f32_16x16x32_bf16 v[112:115], v[172:175], v[180:183], v[112:115]
	v_mfma_f32_16x16x32_bf16 v[100:103], v[164:167], v[196:199], v[100:103]
	v_mfma_f32_16x16x32_bf16 v[92:95], v[172:175], v[196:199], v[92:95]
	v_mfma_f32_16x16x32_bf16 v[84:87], v[164:167], v[204:207], v[84:87]
	v_mfma_f32_16x16x32_bf16 v[76:79], v[172:175], v[204:207], v[76:79]
	v_mfma_f32_16x16x32_bf16 v[68:71], v[164:167], v[212:215], v[68:71]
	v_mfma_f32_16x16x32_bf16 v[64:67], v[172:175], v[212:215], v[64:67]
	s_add_i32 s56, s56, s43
	v_lshl_add_u64 v[216:217], s[36:37], 0, v[184:185]
	s_mov_b32 m0, s56
	s_barrier
	ds_read_b128 v[176:179], v159 offset:16384
	ds_read_b128 v[180:183], v159 offset:17408
	ds_read_b128 v[188:191], v159 offset:18432
	ds_read_b128 v[196:199], v159 offset:19456
	ds_read_b128 v[200:203], v159 offset:20480
	ds_read_b128 v[204:207], v159 offset:21504
	ds_read_b128 v[208:211], v159 offset:22528
	ds_read_b128 v[212:215], v159 offset:23552
	global_load_lds_dwordx4 v[216:217], off
	s_add_i32 m0, s56, 0x2000
	s_add_u32 s56, s36, 0x200000
	v_lshl_add_u64 v[218:219], s[36:37], 0, v[136:137]
	s_addc_u32 s57, s37, 0
	s_add_i32 s58, s58, s43
	global_load_lds_dwordx4 v[218:219], off
	v_lshl_add_u64 v[220:221], s[56:57], 0, v[184:185]
	s_mov_b32 m0, s58
	v_lshl_add_u64 v[222:223], s[38:39], 0, v[134:135]
	global_load_lds_dwordx4 v[220:221], off
	s_add_i32 m0, s58, 0x2000
	v_lshl_add_u64 v[220:221], s[56:57], 0, v[136:137]
	global_load_lds_dwordx4 v[220:221], off
	s_mov_b32 m0, s31
	v_lshl_add_u64 v[220:221], s[38:39], 0, v[132:133]
	global_load_lds_dwordx4 v[220:221], off
	s_mov_b32 m0, s44
	s_nop 0
	global_load_lds_dwordx4 v[222:223], off
	s_waitcnt vmcnt(8) lgkmcnt(0)
	s_barrier
	v_mfma_f32_16x16x32_bf16 v[60:63], v[128:131], v[176:179], v[60:63]
	v_mfma_f32_16x16x32_bf16 v[56:59], v[146:149], v[176:179], v[56:59]
	v_mfma_f32_16x16x32_bf16 v[48:51], v[128:131], v[188:191], v[48:51]
	v_mfma_f32_16x16x32_bf16 v[40:43], v[146:149], v[188:191], v[40:43]
	v_mfma_f32_16x16x32_bf16 v[32:35], v[128:131], v[200:203], v[32:35]
	v_mfma_f32_16x16x32_bf16 v[24:27], v[146:149], v[200:203], v[24:27]
	v_mfma_f32_16x16x32_bf16 v[16:19], v[128:131], v[208:211], v[16:19]
	v_mfma_f32_16x16x32_bf16 v[8:11], v[146:149], v[208:211], v[8:11]
	v_mfma_f32_16x16x32_bf16 v[60:63], v[142:145], v[180:183], v[60:63]
	v_mfma_f32_16x16x32_bf16 v[56:59], v[150:153], v[180:183], v[56:59]
	v_mfma_f32_16x16x32_bf16 v[48:51], v[142:145], v[196:199], v[48:51]
	v_mfma_f32_16x16x32_bf16 v[40:43], v[150:153], v[196:199], v[40:43]
	v_mfma_f32_16x16x32_bf16 v[32:35], v[142:145], v[204:207], v[32:35]
	v_mfma_f32_16x16x32_bf16 v[24:27], v[150:153], v[204:207], v[24:27]
	v_mfma_f32_16x16x32_bf16 v[16:19], v[142:145], v[212:215], v[16:19]
	v_mfma_f32_16x16x32_bf16 v[8:11], v[150:153], v[212:215], v[8:11]
	v_mfma_f32_16x16x32_bf16 v[52:55], v[160:163], v[176:179], v[52:55]
	v_mfma_f32_16x16x32_bf16 v[44:47], v[168:171], v[176:179], v[44:47]
	v_mfma_f32_16x16x32_bf16 v[36:39], v[160:163], v[188:191], v[36:39]
	v_mfma_f32_16x16x32_bf16 v[28:31], v[168:171], v[188:191], v[28:31]
	v_mfma_f32_16x16x32_bf16 v[20:23], v[160:163], v[200:203], v[20:23]
	v_mfma_f32_16x16x32_bf16 v[12:15], v[168:171], v[200:203], v[12:15]
	v_mfma_f32_16x16x32_bf16 v[4:7], v[160:163], v[208:211], v[4:7]
	v_mfma_f32_16x16x32_bf16 v[0:3], v[168:171], v[208:211], v[0:3]
	v_mfma_f32_16x16x32_bf16 v[52:55], v[164:167], v[180:183], v[52:55]
	v_mfma_f32_16x16x32_bf16 v[44:47], v[172:175], v[180:183], v[44:47]
	v_mfma_f32_16x16x32_bf16 v[36:39], v[164:167], v[196:199], v[36:39]
	v_mfma_f32_16x16x32_bf16 v[28:31], v[172:175], v[196:199], v[28:31]
	v_mfma_f32_16x16x32_bf16 v[20:23], v[164:167], v[204:207], v[20:23]
	v_mfma_f32_16x16x32_bf16 v[12:15], v[172:175], v[204:207], v[12:15]
	v_mfma_f32_16x16x32_bf16 v[4:7], v[164:167], v[212:215], v[4:7]
	v_mfma_f32_16x16x32_bf16 v[0:3], v[172:175], v[212:215], v[0:3]
	s_add_i32 s56, 0, 0x18000
	s_add_i32 s57, 0, 0x1c000
	s_barrier
; #define PG8_STAGE(bufoff, gbase, voff) do { _Pragma("unroll") for (int _i = 0; _i < 2; ++_i) \
;         __builtin_amdgcn_global_load_lds((const unsigned*)((const char*)(gbase) + (voff)[_i]), (LAS unsigned*)(lds + (bufoff) + ldsw + _i * 8192), 16, 0, 0); } while (0)
; #define PG8_LDA(dst, b, h) do { _Pragma("unroll") for (int m = 0; m < 4; ++m) _Pragma("unroll") for (int k = 0; k < 2; ++k) dst[m][k] = *(const LAS bf16x8*)(lds + PG8_SA(b, h) + aoff + m * 2048 + k * 1024); } while (0)
; #define PG8_LDB(dst, b, h) do { _Pragma("unroll") for (int n = 0; n < 2; ++n) _Pragma("unroll") for (int k = 0; k < 2; ++k) dst[n][k] = *(const LAS bf16x8*)(lds + PG8_SB(b, h) + boff + n * 2048 + k * 1024); } while (0)
; #define PG8_MMA(ai, bj, At, Bt) do { __builtin_amdgcn_s_setprio(1); _Pragma("unroll") for (int m = 0; m < 4; ++m) _Pragma("unroll") for (int n = 0; n < 2; ++n) _Pragma("unroll") for (int k = 0; k < 2; ++k) \
;         acc[ai][bj][m][n] = __builtin_amdgcn_mfma_f32_16x16x32_bf16(Bt[n][k], At[m][k], acc[ai][bj][m][n], 0, 0, 0); __builtin_amdgcn_s_setprio(0); } while (0)
; #define PG8_WAIT_V(n) asm volatile("s_waitcnt vmcnt(" #n ")" ::: "memory")
; #define PG8_WAIT_L(n) asm volatile("s_waitcnt lgkmcnt(" #n ")" ::: "memory")
; #define PG8_BAR __builtin_amdgcn_s_barrier()
; #define PG8_SCHED __builtin_amdgcn_sched_barrier(0)
; template <class Epi, class Sched>
; DI void gemm_phase(LAS unsigned char* lds, const int wv, const int lda, const int ldb, const Sched& S, const Epi& E) {
;     ...
;             PG8_LDB(B0, 1, 0); PG8_LDB(B1, 1, 1); PG8_SCHED; PG8_LDA(At, 1, 0); PG8_STAGE(PG8_SA(0, 1), a2 + hstepA, voffA);
;             PG8_WAIT_V(8); PG8_WAIT_L(0); PG8_BAR; PG8_MMA(0, 0, At, B0); PG8_MMA(0, 1, At, B1); PG8_BAR; PG8_SCHED;
;             PG8_LDA(At, 1, 1); PG8_STAGE(PG8_SB(1, 0), b3, voffB); PG8_STAGE(PG8_SB(1, 1), b3 + hstepB, voffB); PG8_STAGE(PG8_SA(1, 0), a3, voffA);
;             PG8_WAIT_V(8); PG8_WAIT_L(0); PG8_BAR; PG8_MMA(1, 0, At, B0); PG8_MMA(1, 1, At, B1); PG8_BAR; PG8_SCHED;
;         }
	v_add_u32_e32 v150, s56, v155
	v_add_u32_e32 v172, s57, v155
	ds_read_b128 v[128:131], v150
	ds_read_b128 v[142:145], v150 offset:1024
	ds_read_b128 v[146:149], v150 offset:2048
	ds_read_b128 v[150:153], v150 offset:3072
	ds_read_b128 v[160:163], v172
	ds_read_b128 v[164:167], v172 offset:1024
	ds_read_b128 v[168:171], v172 offset:2048
	ds_read_b128 v[172:175], v172 offset:3072
	s_add_u32 s38, s38, 0x200000
	s_addc_u32 s39, s39, 0
	s_mov_b32 m0, s45
	v_lshl_add_u64 v[234:235], s[38:39], 0, v[132:133]
	ds_read_b128 v[176:179], v159 offset:32768
	ds_read_b128 v[180:183], v159 offset:33792
	ds_read_b128 v[188:191], v159 offset:34816
	ds_read_b128 v[196:199], v159 offset:35840
	ds_read_b128 v[200:203], v159 offset:36864
	ds_read_b128 v[204:207], v159 offset:37888
	ds_read_b128 v[208:211], v159 offset:38912
	ds_read_b128 v[212:215], v159 offset:39936
	global_load_lds_dwordx4 v[234:235], off
	s_mov_b32 m0, s46
	v_lshl_add_u64 v[234:235], s[38:39], 0, v[134:135]
	global_load_lds_dwordx4 v[234:235], off
	s_waitcnt vmcnt(8) lgkmcnt(0)
	s_barrier
	v_mfma_f32_16x16x32_bf16 v[124:127], v[128:131], v[176:179], v[124:127]
	v_mfma_f32_16x16x32_bf16 v[120:123], v[146:149], v[176:179], v[120:123]
	v_mfma_f32_16x16x32_bf16 v[108:111], v[128:131], v[188:191], v[108:111]
	v_mfma_f32_16x16x32_bf16 v[104:107], v[146:149], v[188:191], v[104:107]
	v_mfma_f32_16x16x32_bf16 v[96:99], v[128:131], v[200:203], v[96:99]
	v_mfma_f32_16x16x32_bf16 v[88:91], v[146:149], v[200:203], v[88:91]
	v_mfma_f32_16x16x32_bf16 v[80:83], v[128:131], v[208:211], v[80:83]
	v_mfma_f32_16x16x32_bf16 v[72:75], v[146:149], v[208:211], v[72:75]
	v_mfma_f32_16x16x32_bf16 v[124:127], v[142:145], v[180:183], v[124:127]
	v_mfma_f32_16x16x32_bf16 v[120:123], v[150:153], v[180:183], v[120:123]
	v_mfma_f32_16x16x32_bf16 v[108:111], v[142:145], v[196:199], v[108:111]
	v_mfma_f32_16x16x32_bf16 v[104:107], v[150:153], v[196:199], v[104:107]
	v_mfma_f32_16x16x32_bf16 v[96:99], v[142:145], v[204:207], v[96:99]
	v_mfma_f32_16x16x32_bf16 v[88:91], v[150:153], v[204:207], v[88:91]
	v_mfma_f32_16x16x32_bf16 v[80:83], v[142:145], v[212:215], v[80:83]
	v_mfma_f32_16x16x32_bf16 v[72:75], v[150:153], v[212:215], v[72:75]
	v_mfma_f32_16x16x32_bf16 v[116:119], v[160:163], v[176:179], v[116:119]
	v_mfma_f32_16x16x32_bf16 v[112:115], v[168:171], v[176:179], v[112:115]
	v_mfma_f32_16x16x32_bf16 v[100:103], v[160:163], v[188:191], v[100:103]
	v_mfma_f32_16x16x32_bf16 v[92:95], v[168:171], v[188:191], v[92:95]
	v_mfma_f32_16x16x32_bf16 v[84:87], v[160:163], v[200:203], v[84:87]
	v_mfma_f32_16x16x32_bf16 v[76:79], v[168:171], v[200:203], v[76:79]
	v_mfma_f32_16x16x32_bf16 v[68:71], v[160:163], v[208:211], v[68:71]
	v_mfma_f32_16x16x32_bf16 v[64:67], v[168:171], v[208:211], v[64:67]
	v_mfma_f32_16x16x32_bf16 v[116:119], v[164:167], v[180:183], v[116:119]
	v_mfma_f32_16x16x32_bf16 v[112:115], v[172:175], v[180:183], v[112:115]
	v_mfma_f32_16x16x32_bf16 v[100:103], v[164:167], v[196:199], v[100:103]
	v_mfma_f32_16x16x32_bf16 v[92:95], v[172:175], v[196:199], v[92:95]
	v_mfma_f32_16x16x32_bf16 v[84:87], v[164:167], v[204:207], v[84:87]
	v_mfma_f32_16x16x32_bf16 v[76:79], v[172:175], v[204:207], v[76:79]
	v_mfma_f32_16x16x32_bf16 v[68:71], v[164:167], v[212:215], v[68:71]
	v_mfma_f32_16x16x32_bf16 v[64:67], v[172:175], v[212:215], v[64:67]
	s_add_i32 s38, s56, s43
	v_lshl_add_u64 v[216:217], v[216:217], 0, s[28:29]
	s_mov_b32 m0, s38
	s_barrier
	ds_read_b128 v[176:179], v159 offset:49152
	ds_read_b128 v[180:183], v159 offset:50176
	ds_read_b128 v[188:191], v159 offset:51200
	ds_read_b128 v[196:199], v159 offset:52224
	ds_read_b128 v[200:203], v159 offset:53248
	ds_read_b128 v[204:207], v159 offset:54272
	ds_read_b128 v[208:211], v159 offset:55296
	ds_read_b128 v[212:215], v159 offset:56320
	global_load_lds_dwordx4 v[216:217], off
	s_add_i32 m0, s38, 0x2000
	s_add_u32 s36, s36, 0x200080
	v_lshl_add_u64 v[216:217], v[218:219], 0, s[28:29]
	s_addc_u32 s37, s37, 0
	s_add_i32 s38, s57, s43
	global_load_lds_dwordx4 v[216:217], off
	s_mov_b32 m0, s38
	v_lshl_add_u64 v[216:217], s[36:37], 0, v[184:185]
	global_load_lds_dwordx4 v[216:217], off
	s_add_i32 m0, s38, 0x2000
	v_lshl_add_u64 v[216:217], s[36:37], 0, v[136:137]
	global_load_lds_dwordx4 v[216:217], off
	s_mov_b32 m0, s47
	v_lshl_add_u64 v[216:217], v[220:221], 0, s[28:29]
	global_load_lds_dwordx4 v[216:217], off
	s_mov_b32 m0, s48
	v_lshl_add_u64 v[216:217], v[222:223], 0, s[28:29]
	global_load_lds_dwordx4 v[216:217], off
	s_waitcnt vmcnt(8) lgkmcnt(0)
	s_barrier
	v_mfma_f32_16x16x32_bf16 v[60:63], v[128:131], v[176:179], v[60:63]
	v_mfma_f32_16x16x32_bf16 v[56:59], v[146:149], v[176:179], v[56:59]
	v_mfma_f32_16x16x32_bf16 v[48:51], v[128:131], v[188:191], v[48:51]
	v_mfma_f32_16x16x32_bf16 v[40:43], v[146:149], v[188:191], v[40:43]
	v_mfma_f32_16x16x32_bf16 v[32:35], v[128:131], v[200:203], v[32:35]
	v_mfma_f32_16x16x32_bf16 v[24:27], v[146:149], v[200:203], v[24:27]
	v_mfma_f32_16x16x32_bf16 v[16:19], v[128:131], v[208:211], v[16:19]
	v_mfma_f32_16x16x32_bf16 v[8:11], v[146:149], v[208:211], v[8:11]
	v_mfma_f32_16x16x32_bf16 v[60:63], v[142:145], v[180:183], v[60:63]
	v_mfma_f32_16x16x32_bf16 v[56:59], v[150:153], v[180:183], v[56:59]
	v_mfma_f32_16x16x32_bf16 v[48:51], v[142:145], v[196:199], v[48:51]
	v_mfma_f32_16x16x32_bf16 v[40:43], v[150:153], v[196:199], v[40:43]
	v_mfma_f32_16x16x32_bf16 v[32:35], v[142:145], v[204:207], v[32:35]
	v_mfma_f32_16x16x32_bf16 v[24:27], v[150:153], v[204:207], v[24:27]
	v_mfma_f32_16x16x32_bf16 v[16:19], v[142:145], v[212:215], v[16:19]
	v_mfma_f32_16x16x32_bf16 v[8:11], v[150:153], v[212:215], v[8:11]
	v_mfma_f32_16x16x32_bf16 v[52:55], v[160:163], v[176:179], v[52:55]
	v_mfma_f32_16x16x32_bf16 v[44:47], v[168:171], v[176:179], v[44:47]
	v_mfma_f32_16x16x32_bf16 v[36:39], v[160:163], v[188:191], v[36:39]
	v_mfma_f32_16x16x32_bf16 v[28:31], v[168:171], v[188:191], v[28:31]
	v_mfma_f32_16x16x32_bf16 v[20:23], v[160:163], v[200:203], v[20:23]
	v_mfma_f32_16x16x32_bf16 v[12:15], v[168:171], v[200:203], v[12:15]
	v_mfma_f32_16x16x32_bf16 v[4:7], v[160:163], v[208:211], v[4:7]
	v_mfma_f32_16x16x32_bf16 v[0:3], v[168:171], v[208:211], v[0:3]
	v_mfma_f32_16x16x32_bf16 v[52:55], v[164:167], v[180:183], v[52:55]
	v_mfma_f32_16x16x32_bf16 v[44:47], v[172:175], v[180:183], v[44:47]
	v_mfma_f32_16x16x32_bf16 v[36:39], v[164:167], v[196:199], v[36:39]
	v_mfma_f32_16x16x32_bf16 v[28:31], v[172:175], v[196:199], v[28:31]
	v_mfma_f32_16x16x32_bf16 v[20:23], v[164:167], v[204:207], v[20:23]
	v_mfma_f32_16x16x32_bf16 v[12:15], v[172:175], v[204:207], v[12:15]
	v_mfma_f32_16x16x32_bf16 v[4:7], v[164:167], v[212:215], v[4:7]
	v_mfma_f32_16x16x32_bf16 v[0:3], v[172:175], v[212:215], v[0:3]
	s_add_i32 s55, s55, 2
	s_add_u32 s34, s34, 0x100
	s_addc_u32 s35, s35, 0
	s_add_u32 s23, s23, 0x100
	s_addc_u32 s54, s54, 0
	s_cmpk_gt_u32 s55, 0x7d
	s_barrier
	s_cbranch_scc0 .LBB0_1477
	s_and_b64 vcc, exec, s[14:15]
	s_cbranch_vccz .LBB0_1480
	s_barrier
